# grid barrier trimmed to one returning atomic + one poll stage (per-XCD words, sites 2-12) and write-through sc1 on the wide dwordx4 stores of GEMM epilogues, ffn_act and final norm, on top of the row-
# speedup vs baseline: 1.0745x; 1.0231x over previous
.LBB0_2:
	s_or_b64 exec, exec, s[2:3]
	s_waitcnt lgkmcnt(0)
	s_barrier
	s_add_u32 s6, s76, 0xf980000
	s_getreg_b32 s2, hwreg(HW_REG_XCC_ID, 0, 4)
	s_addc_u32 s7, s77, 0
	s_and_b32 s33, s2, 15
	s_add_u32 s100, s76, 0xf980000
	s_addc_u32 s101, s77, 0
	s_mov_b32 s98, 0
	s_lshl_b32 s99, s33, 8
	s_add_u32 s99, s99, 0x1480
	s_and_saveexec_b64 s[2:3], s[34:35]
	s_cbranch_execz .LBB0_5
	s_mov_b64 s[4:5], exec
	v_mbcnt_lo_u32_b32 v1, s4, 0
	v_mbcnt_hi_u32_b32 v1, s5, v1
	v_cmp_eq_u32_e32 vcc, 0, v1
	s_and_b64 s[8:9], exec, vcc
	s_mov_b64 exec, s[8:9]
	s_cbranch_execz .LBB0_5
	s_lshl_b32 s8, s33, 8
	s_bcnt1_i32_b64 s4, s[4:5]
	v_mov_b32_e32 v1, s8
	v_mov_b32_e32 v2, s4
	global_atomic_add v1, v2, s[6:7] offset:1024

.LBB0_99:
	s_or_b64 exec, exec, s[2:3]
	s_waitcnt vmcnt(0)
	s_barrier
	s_and_saveexec_b64 s[0:1], s[34:35]
	s_cbranch_execz .LBB0_151
	s_add_u32 s98, s98, 1
	v_mov_b32_e32 v7, 0x26c00
	ds_read2_b32 v[8:9], v7 offset1:1
	v_mov_b32_e32 v2, s99
	v_mov_b32_e32 v3, 1
	global_atomic_add v4, v2, v3, s[100:101] sc0
	v_add_u32_e32 v2, 0x1000, v2
	v_mov_b32_e32 v10, 0x2480
	s_waitcnt vmcnt(0) lgkmcnt(0)
	v_add_u32_e32 v4, 1, v4
	v_mul_lo_u32 v5, v8, s98
	v_mul_lo_u32 v9, v9, s98
	v_cmp_eq_u32_e32 vcc, v4, v5
	s_and_saveexec_b64 s[4:5], vcc
	s_cbranch_execz .Lh2_skip_0
	buffer_wbl2 sc1
	s_waitcnt vmcnt(0)
	global_atomic_add v10, v3, s[100:101]
	global_atomic_add v10, v3, s[100:101] offset:256
	global_atomic_add v10, v3, s[100:101] offset:512
	global_atomic_add v10, v3, s[100:101] offset:768
	global_atomic_add v10, v3, s[100:101] offset:1024
	global_atomic_add v10, v3, s[100:101] offset:1280
	global_atomic_add v10, v3, s[100:101] offset:1536
	global_atomic_add v10, v3, s[100:101] offset:1792
	global_atomic_add v10, v3, s[100:101] offset:2048
	global_atomic_add v10, v3, s[100:101] offset:2304
	global_atomic_add v10, v3, s[100:101] offset:2560
	global_atomic_add v10, v3, s[100:101] offset:2816
	global_atomic_add v10, v3, s[100:101] offset:3072
	global_atomic_add v10, v3, s[100:101] offset:3328
	global_atomic_add v10, v3, s[100:101] offset:3584
	global_atomic_add v10, v3, s[100:101] offset:3840

.Lh2_spin_0:
	s_sleep 1
	global_load_dword v4, v2, s[100:101] sc1
	s_waitcnt vmcnt(0)
	v_cmp_lt_u32_e32 vcc, v4, v9
	s_cbranch_vccnz .Lh2_spin_0
	buffer_inv sc1
	s_waitcnt vmcnt(0)

.LBB0_162:
	ds_read_b128 v[144:147], v152
	ds_read_b128 v[156:159], v152 offset:1024
	ds_read_b128 v[160:163], v152 offset:2048
	ds_read_b128 v[164:167], v152 offset:3072
	s_add_u32 s44, s42, 0xfffc0080
	s_addc_u32 s45, s43, -1
	s_cmp_eq_u32 s67, 12
	s_cselect_b32 s47, s1, s45
	s_cselect_b32 s46, s31, s44
	s_cselect_b32 s45, s25, s65
	s_cselect_b32 s44, s41, s64
	v_lshl_add_u64 v[202:203], s[42:43], 0, v[136:137]
	s_add_i32 m0, s50, 0xc000
	ds_read_b128 v[168:171], v153
	ds_read_b128 v[172:175], v153 offset:1024
	ds_read_b128 v[178:181], v153 offset:2048
	ds_read_b128 v[182:185], v153 offset:3072
	ds_read_b128 v[186:189], v153 offset:4096
	ds_read_b128 v[190:193], v153 offset:5120
	ds_read_b128 v[194:197], v153 offset:6144
	ds_read_b128 v[198:201], v153 offset:7168
	global_load_lds_dwordx4 v[202:203], off
	v_lshl_add_u64 v[202:203], s[42:43], 0, v[138:139]
	s_add_i32 m0, s50, 0xe000
	s_nop 0
	global_load_lds_dwordx4 v[202:203], off
	s_waitcnt lgkmcnt(8)
	s_barrier
	s_waitcnt lgkmcnt(0)
	s_setprio 1
	s_waitcnt lgkmcnt(0)
	v_mfma_f32_16x16x32_bf16 v[124:127], v[144:147], v[168:171], v[124:127]
	v_mfma_f32_16x16x32_bf16 v[120:123], v[160:163], v[168:171], v[120:123]
	v_mfma_f32_16x16x32_bf16 v[112:115], v[144:147], v[178:181], v[112:115]
	v_mfma_f32_16x16x32_bf16 v[104:107], v[160:163], v[178:181], v[104:107]
	v_mfma_f32_16x16x32_bf16 v[96:99], v[144:147], v[186:189], v[96:99]
	v_mfma_f32_16x16x32_bf16 v[88:91], v[160:163], v[186:189], v[88:91]
	v_mfma_f32_16x16x32_bf16 v[80:83], v[144:147], v[194:197], v[80:83]
	v_mfma_f32_16x16x32_bf16 v[72:75], v[160:163], v[194:197], v[72:75]
	v_mfma_f32_16x16x32_bf16 v[124:127], v[156:159], v[172:175], v[124:127]
	v_mfma_f32_16x16x32_bf16 v[120:123], v[164:167], v[172:175], v[120:123]
	v_mfma_f32_16x16x32_bf16 v[112:115], v[156:159], v[182:185], v[112:115]
	v_mfma_f32_16x16x32_bf16 v[104:107], v[164:167], v[182:185], v[104:107]
	v_mfma_f32_16x16x32_bf16 v[96:99], v[156:159], v[190:193], v[96:99]
	v_mfma_f32_16x16x32_bf16 v[88:91], v[164:167], v[190:193], v[88:91]
	v_mfma_f32_16x16x32_bf16 v[80:83], v[156:159], v[198:201], v[80:83]
	v_mfma_f32_16x16x32_bf16 v[72:75], v[164:167], v[198:201], v[72:75]
	s_setprio 0
	s_barrier
	s_add_i32 s68, s60, s49
	v_lshl_add_u64 v[218:219], s[44:45], 0, v[130:131]
	s_mov_b32 m0, s68
	ds_read_b128 v[202:205], v154
	ds_read_b128 v[206:209], v154 offset:1024
	ds_read_b128 v[210:213], v154 offset:2048
	ds_read_b128 v[214:217], v154 offset:3072
	global_load_lds_dwordx4 v[218:219], off
	v_lshl_add_u64 v[220:221], s[44:45], 0, v[134:135]
	s_add_i32 m0, s68, 0x2000
	s_nop 0
	global_load_lds_dwordx4 v[220:221], off
	s_barrier
	s_waitcnt lgkmcnt(0)
	s_setprio 1
	s_waitcnt lgkmcnt(0)
	v_mfma_f32_16x16x32_bf16 v[116:119], v[202:205], v[168:171], v[116:119]
	v_mfma_f32_16x16x32_bf16 v[108:111], v[210:213], v[168:171], v[108:111]
	v_mfma_f32_16x16x32_bf16 v[100:103], v[202:205], v[178:181], v[100:103]
	v_mfma_f32_16x16x32_bf16 v[92:95], v[210:213], v[178:181], v[92:95]
	v_mfma_f32_16x16x32_bf16 v[84:87], v[202:205], v[186:189], v[84:87]
	v_mfma_f32_16x16x32_bf16 v[76:79], v[210:213], v[186:189], v[76:79]
	v_mfma_f32_16x16x32_bf16 v[68:71], v[202:205], v[194:197], v[68:71]
	v_mfma_f32_16x16x32_bf16 v[64:67], v[210:213], v[194:197], v[64:67]
	v_mfma_f32_16x16x32_bf16 v[116:119], v[206:209], v[172:175], v[116:119]
	v_mfma_f32_16x16x32_bf16 v[108:111], v[214:217], v[172:175], v[108:111]
	v_mfma_f32_16x16x32_bf16 v[100:103], v[206:209], v[182:185], v[100:103]
	v_mfma_f32_16x16x32_bf16 v[92:95], v[214:217], v[182:185], v[92:95]
	v_mfma_f32_16x16x32_bf16 v[84:87], v[206:209], v[190:193], v[84:87]
	v_mfma_f32_16x16x32_bf16 v[76:79], v[214:217], v[190:193], v[76:79]
	v_mfma_f32_16x16x32_bf16 v[68:71], v[206:209], v[198:201], v[68:71]
	v_mfma_f32_16x16x32_bf16 v[64:67], v[214:217], v[198:201], v[64:67]
	s_setprio 0
	s_mov_b32 m0, s50
	v_lshl_add_u64 v[222:223], s[46:47], 0, v[128:129]
	s_barrier
	ds_read_b128 v[168:171], v153 offset:16384
	ds_read_b128 v[172:175], v153 offset:17408
	ds_read_b128 v[178:181], v153 offset:18432
	ds_read_b128 v[182:185], v153 offset:19456
	ds_read_b128 v[186:189], v153 offset:20480
	ds_read_b128 v[190:193], v153 offset:21504
	ds_read_b128 v[194:197], v153 offset:22528
	ds_read_b128 v[198:201], v153 offset:23552
	global_load_lds_dwordx4 v[222:223], off
	v_lshl_add_u64 v[224:225], s[46:47], 0, v[132:133]
	s_mov_b32 m0, s51
	s_nop 0
	global_load_lds_dwordx4 v[224:225], off
	s_barrier
	s_waitcnt lgkmcnt(0)
	s_setprio 1
	s_waitcnt lgkmcnt(0)
	v_mfma_f32_16x16x32_bf16 v[60:63], v[144:147], v[168:171], v[60:63]
	v_mfma_f32_16x16x32_bf16 v[56:59], v[160:163], v[168:171], v[56:59]
	v_mfma_f32_16x16x32_bf16 v[48:51], v[144:147], v[178:181], v[48:51]
	v_mfma_f32_16x16x32_bf16 v[40:43], v[160:163], v[178:181], v[40:43]
	v_mfma_f32_16x16x32_bf16 v[32:35], v[144:147], v[186:189], v[32:35]
	v_mfma_f32_16x16x32_bf16 v[24:27], v[160:163], v[186:189], v[24:27]
	v_mfma_f32_16x16x32_bf16 v[16:19], v[144:147], v[194:197], v[16:19]
	v_mfma_f32_16x16x32_bf16 v[8:11], v[160:163], v[194:197], v[8:11]
	v_mfma_f32_16x16x32_bf16 v[60:63], v[156:159], v[172:175], v[60:63]
	v_mfma_f32_16x16x32_bf16 v[56:59], v[164:167], v[172:175], v[56:59]
	v_mfma_f32_16x16x32_bf16 v[48:51], v[156:159], v[182:185], v[48:51]
	v_mfma_f32_16x16x32_bf16 v[40:43], v[164:167], v[182:185], v[40:43]
	v_mfma_f32_16x16x32_bf16 v[32:35], v[156:159], v[190:193], v[32:35]
	v_mfma_f32_16x16x32_bf16 v[24:27], v[164:167], v[190:193], v[24:27]
	v_mfma_f32_16x16x32_bf16 v[16:19], v[156:159], v[198:201], v[16:19]
	v_mfma_f32_16x16x32_bf16 v[8:11], v[164:167], v[198:201], v[8:11]
	s_setprio 0
	s_barrier
	s_add_u32 s68, s44, 0x40000
	s_addc_u32 s69, s45, 0
	s_add_i32 s70, s61, s49
	v_lshl_add_u64 v[144:145], s[68:69], 0, v[130:131]
	s_mov_b32 m0, s70
	s_nop 0
	global_load_lds_dwordx4 v[144:145], off
	v_lshl_add_u64 v[144:145], s[68:69], 0, v[134:135]
	s_add_i32 m0, s70, 0x2000
	s_nop 0
	global_load_lds_dwordx4 v[144:145], off
	s_waitcnt vmcnt(6)
	s_barrier
	s_setprio 1
	v_mfma_f32_16x16x32_bf16 v[52:55], v[202:205], v[168:171], v[52:55]
	v_mfma_f32_16x16x32_bf16 v[44:47], v[210:213], v[168:171], v[44:47]
	v_mfma_f32_16x16x32_bf16 v[36:39], v[202:205], v[178:181], v[36:39]
	v_mfma_f32_16x16x32_bf16 v[28:31], v[210:213], v[178:181], v[28:31]
	v_mfma_f32_16x16x32_bf16 v[20:23], v[202:205], v[186:189], v[20:23]
	v_mfma_f32_16x16x32_bf16 v[12:15], v[210:213], v[186:189], v[12:15]
	v_mfma_f32_16x16x32_bf16 v[4:7], v[202:205], v[194:197], v[4:7]
	v_mfma_f32_16x16x32_bf16 v[0:3], v[210:213], v[194:197], v[0:3]
	v_mfma_f32_16x16x32_bf16 v[52:55], v[206:209], v[172:175], v[52:55]
	v_mfma_f32_16x16x32_bf16 v[44:47], v[214:217], v[172:175], v[44:47]
	v_mfma_f32_16x16x32_bf16 v[36:39], v[206:209], v[182:185], v[36:39]
	v_mfma_f32_16x16x32_bf16 v[28:31], v[214:217], v[182:185], v[28:31]
	v_mfma_f32_16x16x32_bf16 v[20:23], v[206:209], v[190:193], v[20:23]
	v_mfma_f32_16x16x32_bf16 v[12:15], v[214:217], v[190:193], v[12:15]
	v_mfma_f32_16x16x32_bf16 v[4:7], v[206:209], v[198:201], v[4:7]
	v_mfma_f32_16x16x32_bf16 v[0:3], v[214:217], v[198:201], v[0:3]
	s_setprio 0
	s_add_i32 s68, 0, 0x18000
	v_add_u32_e32 v155, s68, v150
	s_barrier
	ds_read_b128 v[144:147], v155
	ds_read_b128 v[156:159], v155 offset:1024
	ds_read_b128 v[160:163], v155 offset:2048
	ds_read_b128 v[164:167], v155 offset:3072
	s_add_u32 s46, s46, 0x40000
	s_addc_u32 s47, s47, 0
	s_mov_b32 m0, s52
	v_lshl_add_u64 v[202:203], s[46:47], 0, v[128:129]
	ds_read_b128 v[168:171], v153 offset:32768
	ds_read_b128 v[172:175], v153 offset:33792
	ds_read_b128 v[178:181], v153 offset:34816
	ds_read_b128 v[182:185], v153 offset:35840
	ds_read_b128 v[186:189], v153 offset:36864
	ds_read_b128 v[190:193], v153 offset:37888
	ds_read_b128 v[194:197], v153 offset:38912
	ds_read_b128 v[198:201], v153 offset:39936
	global_load_lds_dwordx4 v[202:203], off
	v_lshl_add_u64 v[202:203], s[46:47], 0, v[132:133]
	s_mov_b32 m0, s53
	s_nop 0
	global_load_lds_dwordx4 v[202:203], off
	s_waitcnt lgkmcnt(8)
	s_barrier
	s_waitcnt lgkmcnt(0)
	s_setprio 1
	s_waitcnt lgkmcnt(0)
	v_mfma_f32_16x16x32_bf16 v[124:127], v[144:147], v[168:171], v[124:127]
	v_mfma_f32_16x16x32_bf16 v[120:123], v[160:163], v[168:171], v[120:123]
	v_mfma_f32_16x16x32_bf16 v[112:115], v[144:147], v[178:181], v[112:115]
	v_mfma_f32_16x16x32_bf16 v[104:107], v[160:163], v[178:181], v[104:107]
	v_mfma_f32_16x16x32_bf16 v[96:99], v[144:147], v[186:189], v[96:99]
	v_mfma_f32_16x16x32_bf16 v[88:91], v[160:163], v[186:189], v[88:91]
	v_mfma_f32_16x16x32_bf16 v[80:83], v[144:147], v[194:197], v[80:83]
	v_mfma_f32_16x16x32_bf16 v[72:75], v[160:163], v[194:197], v[72:75]
	v_mfma_f32_16x16x32_bf16 v[124:127], v[156:159], v[172:175], v[124:127]
	v_mfma_f32_16x16x32_bf16 v[120:123], v[164:167], v[172:175], v[120:123]
	v_mfma_f32_16x16x32_bf16 v[112:115], v[156:159], v[182:185], v[112:115]
	v_mfma_f32_16x16x32_bf16 v[104:107], v[164:167], v[182:185], v[104:107]
	v_mfma_f32_16x16x32_bf16 v[96:99], v[156:159], v[190:193], v[96:99]
	v_mfma_f32_16x16x32_bf16 v[88:91], v[164:167], v[190:193], v[88:91]
	v_mfma_f32_16x16x32_bf16 v[80:83], v[156:159], v[198:201], v[80:83]
	v_mfma_f32_16x16x32_bf16 v[72:75], v[164:167], v[198:201], v[72:75]
	s_setprio 0
	s_barrier
	s_add_i32 s46, 0, 0x1c000
	s_add_i32 s47, s68, s49
	v_add_u32_e32 v155, s46, v150
	v_lshl_add_u64 v[218:219], v[218:219], 0, s[2:3]
	s_mov_b32 m0, s47
	ds_read_b128 v[202:205], v155
	ds_read_b128 v[206:209], v155 offset:1024
	ds_read_b128 v[210:213], v155 offset:2048
	ds_read_b128 v[214:217], v155 offset:3072
	global_load_lds_dwordx4 v[218:219], off
	v_lshl_add_u64 v[218:219], v[220:221], 0, s[2:3]
	s_add_i32 m0, s47, 0x2000
	s_nop 0
	global_load_lds_dwordx4 v[218:219], off
	s_barrier
	s_waitcnt lgkmcnt(0)
	s_setprio 1
	s_waitcnt lgkmcnt(0)
	v_mfma_f32_16x16x32_bf16 v[116:119], v[202:205], v[168:171], v[116:119]
	v_mfma_f32_16x16x32_bf16 v[108:111], v[210:213], v[168:171], v[108:111]
	v_mfma_f32_16x16x32_bf16 v[100:103], v[202:205], v[178:181], v[100:103]
	v_mfma_f32_16x16x32_bf16 v[92:95], v[210:213], v[178:181], v[92:95]
	v_mfma_f32_16x16x32_bf16 v[84:87], v[202:205], v[186:189], v[84:87]
	v_mfma_f32_16x16x32_bf16 v[76:79], v[210:213], v[186:189], v[76:79]
	v_mfma_f32_16x16x32_bf16 v[68:71], v[202:205], v[194:197], v[68:71]
	v_mfma_f32_16x16x32_bf16 v[64:67], v[210:213], v[194:197], v[64:67]
	v_mfma_f32_16x16x32_bf16 v[116:119], v[206:209], v[172:175], v[116:119]
	v_mfma_f32_16x16x32_bf16 v[108:111], v[214:217], v[172:175], v[108:111]
	v_mfma_f32_16x16x32_bf16 v[100:103], v[206:209], v[182:185], v[100:103]
	v_mfma_f32_16x16x32_bf16 v[92:95], v[214:217], v[182:185], v[92:95]
	v_mfma_f32_16x16x32_bf16 v[84:87], v[206:209], v[190:193], v[84:87]
	v_mfma_f32_16x16x32_bf16 v[76:79], v[214:217], v[190:193], v[76:79]
	v_mfma_f32_16x16x32_bf16 v[68:71], v[206:209], v[198:201], v[68:71]
	v_mfma_f32_16x16x32_bf16 v[64:67], v[214:217], v[198:201], v[64:67]
	s_setprio 0
	s_mov_b32 m0, s55
	v_lshl_add_u64 v[218:219], v[222:223], 0, s[2:3]
	s_barrier
	ds_read_b128 v[168:171], v153 offset:49152
	ds_read_b128 v[172:175], v153 offset:50176
	ds_read_b128 v[178:181], v153 offset:51200
	ds_read_b128 v[182:185], v153 offset:52224
	ds_read_b128 v[186:189], v153 offset:53248
	ds_read_b128 v[190:193], v153 offset:54272
	ds_read_b128 v[194:197], v153 offset:55296
	ds_read_b128 v[198:201], v153 offset:56320
	global_load_lds_dwordx4 v[218:219], off
	v_lshl_add_u64 v[218:219], v[224:225], 0, s[2:3]
	s_mov_b32 m0, s56
	s_nop 0
	global_load_lds_dwordx4 v[218:219], off
	s_barrier
	s_waitcnt lgkmcnt(0)
	s_setprio 1
	s_waitcnt lgkmcnt(0)
	v_mfma_f32_16x16x32_bf16 v[60:63], v[144:147], v[168:171], v[60:63]
	v_mfma_f32_16x16x32_bf16 v[56:59], v[160:163], v[168:171], v[56:59]
	v_mfma_f32_16x16x32_bf16 v[48:51], v[144:147], v[178:181], v[48:51]
	v_mfma_f32_16x16x32_bf16 v[40:43], v[160:163], v[178:181], v[40:43]
	v_mfma_f32_16x16x32_bf16 v[32:35], v[144:147], v[186:189], v[32:35]
	v_mfma_f32_16x16x32_bf16 v[24:27], v[160:163], v[186:189], v[24:27]
	v_mfma_f32_16x16x32_bf16 v[16:19], v[144:147], v[194:197], v[16:19]
	v_mfma_f32_16x16x32_bf16 v[8:11], v[160:163], v[194:197], v[8:11]
	v_mfma_f32_16x16x32_bf16 v[60:63], v[156:159], v[172:175], v[60:63]
	v_mfma_f32_16x16x32_bf16 v[56:59], v[164:167], v[172:175], v[56:59]
	v_mfma_f32_16x16x32_bf16 v[48:51], v[156:159], v[182:185], v[48:51]
	v_mfma_f32_16x16x32_bf16 v[40:43], v[164:167], v[182:185], v[40:43]
	v_mfma_f32_16x16x32_bf16 v[32:35], v[156:159], v[190:193], v[32:35]
	v_mfma_f32_16x16x32_bf16 v[24:27], v[164:167], v[190:193], v[24:27]
	v_mfma_f32_16x16x32_bf16 v[16:19], v[156:159], v[198:201], v[16:19]
	v_mfma_f32_16x16x32_bf16 v[8:11], v[164:167], v[198:201], v[8:11]
	s_setprio 0
	s_barrier
	s_add_u32 s44, s44, 0x40080
	s_addc_u32 s45, s45, 0
	s_add_i32 s46, s46, s49
	v_lshl_add_u64 v[144:145], s[44:45], 0, v[130:131]
	s_mov_b32 m0, s46
	s_nop 0
	global_load_lds_dwordx4 v[144:145], off
	v_lshl_add_u64 v[144:145], s[44:45], 0, v[134:135]
	s_add_i32 m0, s46, 0x2000
	s_nop 0
	global_load_lds_dwordx4 v[144:145], off
	s_waitcnt vmcnt(6)
	s_barrier
	s_setprio 1
	v_mfma_f32_16x16x32_bf16 v[52:55], v[202:205], v[168:171], v[52:55]
	v_mfma_f32_16x16x32_bf16 v[44:47], v[210:213], v[168:171], v[44:47]
	v_mfma_f32_16x16x32_bf16 v[36:39], v[202:205], v[178:181], v[36:39]
	v_mfma_f32_16x16x32_bf16 v[28:31], v[210:213], v[178:181], v[28:31]
	v_mfma_f32_16x16x32_bf16 v[20:23], v[202:205], v[186:189], v[20:23]
	v_mfma_f32_16x16x32_bf16 v[12:15], v[210:213], v[186:189], v[12:15]
	v_mfma_f32_16x16x32_bf16 v[4:7], v[202:205], v[194:197], v[4:7]
	v_mfma_f32_16x16x32_bf16 v[0:3], v[210:213], v[194:197], v[0:3]
	v_mfma_f32_16x16x32_bf16 v[52:55], v[206:209], v[172:175], v[52:55]
	v_mfma_f32_16x16x32_bf16 v[44:47], v[214:217], v[172:175], v[44:47]
	v_mfma_f32_16x16x32_bf16 v[36:39], v[206:209], v[182:185], v[36:39]
	v_mfma_f32_16x16x32_bf16 v[28:31], v[214:217], v[182:185], v[28:31]
	v_mfma_f32_16x16x32_bf16 v[20:23], v[206:209], v[190:193], v[20:23]
	v_mfma_f32_16x16x32_bf16 v[12:15], v[214:217], v[190:193], v[12:15]
	v_mfma_f32_16x16x32_bf16 v[4:7], v[206:209], v[198:201], v[4:7]
	v_mfma_f32_16x16x32_bf16 v[0:3], v[214:217], v[198:201], v[0:3]
	s_setprio 0
	s_add_i32 s67, s67, 2
	s_add_u32 s42, s42, 0x100
	s_addc_u32 s43, s43, 0
	s_add_u32 s64, s64, 0x100
	s_addc_u32 s65, s65, 0
	s_cmp_gt_u32 s67, 13
	s_barrier
	s_cbranch_scc0 .LBB0_162
	v_lshl_add_u32 v155, s40, 8, v149
	v_lshl_or_b32 v144, s0, 8, v151
	v_mov_b64_e32 v[146:147], s[16:17]
	v_ashrrev_i32_e32 v145, 31, v144
	v_mad_i64_i32 v[146:147], s[0:1], v155, s62, v[146:147]
	v_lshl_add_u64 v[146:147], v[144:145], 1, v[146:147]
	v_cmp_gt_i32_e32 vcc, s63, v144
	v_cvt_pk_bf16_f32 v124, v124, v125
	v_cvt_pk_bf16_f32 v125, v126, v127
	v_cvt_pk_bf16_f32 v126, v120, v121
	v_cvt_pk_bf16_f32 v127, v122, v123
	s_and_saveexec_b64 s[0:1], vcc
	s_cbranch_execz .LBB0_165
	global_store_dwordx4 v[146:147], v[124:127], off sc1
.LBB0_165:
	s_or_b64 exec, exec, s[0:1]
	v_cvt_pk_bf16_f32 v116, v116, v117
	v_cvt_pk_bf16_f32 v117, v118, v119
	v_cvt_pk_bf16_f32 v118, v108, v109
	v_or_b32_e32 v108, 0x80, v144
	v_cmp_gt_i32_e64 s[0:1], s63, v108
	v_cvt_pk_bf16_f32 v119, v110, v111
	s_and_saveexec_b64 s[40:41], s[0:1]
	s_cbranch_execz .LBB0_167
	global_store_dwordx4 v[146:147], v[116:119], off offset:256 sc1
.LBB0_167:
	s_or_b64 exec, exec, s[40:41]
	v_or_b32_e32 v110, 16, v155
	v_mov_b64_e32 v[108:109], s[16:17]
	v_mad_i64_i32 v[108:109], s[40:41], v110, s62, v[108:109]
	v_lshl_add_u64 v[116:117], v[144:145], 1, v[108:109]
	v_cvt_pk_bf16_f32 v108, v112, v113
	v_cvt_pk_bf16_f32 v109, v114, v115
	v_cvt_pk_bf16_f32 v110, v104, v105
	v_cvt_pk_bf16_f32 v111, v106, v107
	s_and_saveexec_b64 s[40:41], vcc
	s_cbranch_execz .LBB0_169
	global_store_dwordx4 v[116:117], v[108:111], off sc1
.LBB0_169:
	s_or_b64 exec, exec, s[40:41]
	v_cvt_pk_bf16_f32 v100, v100, v101
	v_cvt_pk_bf16_f32 v101, v102, v103
	v_cvt_pk_bf16_f32 v102, v92, v93
	v_cvt_pk_bf16_f32 v103, v94, v95
	s_and_saveexec_b64 s[40:41], s[0:1]
	s_cbranch_execz .LBB0_171
	global_store_dwordx4 v[116:117], v[100:103], off offset:256 sc1
.LBB0_171:
	s_or_b64 exec, exec, s[40:41]
	v_or_b32_e32 v94, 32, v155
	v_mov_b64_e32 v[92:93], s[16:17]
	v_mad_i64_i32 v[92:93], s[40:41], v94, s62, v[92:93]
	v_lshl_add_u64 v[100:101], v[144:145], 1, v[92:93]
	v_cvt_pk_bf16_f32 v92, v96, v97
	v_cvt_pk_bf16_f32 v93, v98, v99
	v_cvt_pk_bf16_f32 v94, v88, v89
	v_cvt_pk_bf16_f32 v95, v90, v91
	s_and_saveexec_b64 s[40:41], vcc
	s_cbranch_execz .LBB0_173
	global_store_dwordx4 v[100:101], v[92:95], off sc1
.LBB0_173:
	s_or_b64 exec, exec, s[40:41]
	v_cvt_pk_bf16_f32 v84, v84, v85
	v_cvt_pk_bf16_f32 v85, v86, v87
	v_cvt_pk_bf16_f32 v86, v76, v77
	v_cvt_pk_bf16_f32 v87, v78, v79
	s_and_saveexec_b64 s[40:41], s[0:1]
	s_cbranch_execz .LBB0_175
	global_store_dwordx4 v[100:101], v[84:87], off offset:256 sc1
.LBB0_175:
	s_or_b64 exec, exec, s[40:41]
	v_or_b32_e32 v78, 48, v155
	v_mov_b64_e32 v[76:77], s[16:17]
	v_mad_i64_i32 v[76:77], s[40:41], v78, s62, v[76:77]
	v_lshl_add_u64 v[84:85], v[144:145], 1, v[76:77]
	v_cvt_pk_bf16_f32 v76, v80, v81
	v_cvt_pk_bf16_f32 v77, v82, v83
	v_cvt_pk_bf16_f32 v78, v72, v73
	v_cvt_pk_bf16_f32 v79, v74, v75
	s_and_saveexec_b64 s[40:41], vcc
	s_cbranch_execz .LBB0_177
	global_store_dwordx4 v[84:85], v[76:79], off sc1
.LBB0_177:
	s_or_b64 exec, exec, s[40:41]
	v_cvt_pk_bf16_f32 v68, v68, v69
	v_cvt_pk_bf16_f32 v69, v70, v71
	v_cvt_pk_bf16_f32 v70, v64, v65
	v_cvt_pk_bf16_f32 v71, v66, v67
	s_and_saveexec_b64 s[40:41], s[0:1]
	s_cbranch_execz .LBB0_179
	global_store_dwordx4 v[84:85], v[68:71], off offset:256 sc1
.LBB0_179:
	s_or_b64 exec, exec, s[40:41]
	v_add_u32_e32 v66, 0x80, v155
	v_mov_b64_e32 v[64:65], s[16:17]
	v_mad_i64_i32 v[64:65], s[40:41], v66, s62, v[64:65]
	v_lshl_add_u64 v[64:65], v[144:145], 1, v[64:65]
	v_cvt_pk_bf16_f32 v60, v60, v61
	v_cvt_pk_bf16_f32 v61, v62, v63
	v_cvt_pk_bf16_f32 v62, v56, v57
	v_cvt_pk_bf16_f32 v63, v58, v59
	s_and_saveexec_b64 s[40:41], vcc
	s_cbranch_execz .LBB0_181
	global_store_dwordx4 v[64:65], v[60:63], off sc1
.LBB0_181:
	s_or_b64 exec, exec, s[40:41]
	v_cvt_pk_bf16_f32 v52, v52, v53
	v_cvt_pk_bf16_f32 v53, v54, v55
	v_cvt_pk_bf16_f32 v54, v44, v45
	v_cvt_pk_bf16_f32 v55, v46, v47
	s_and_saveexec_b64 s[40:41], s[0:1]
	s_cbranch_execz .LBB0_183
	global_store_dwordx4 v[64:65], v[52:55], off offset:256 sc1
.LBB0_183:
	s_or_b64 exec, exec, s[40:41]
	v_add_u32_e32 v46, 0x90, v155
	v_mov_b64_e32 v[44:45], s[16:17]
	v_mad_i64_i32 v[44:45], s[40:41], v46, s62, v[44:45]
	v_lshl_add_u64 v[52:53], v[144:145], 1, v[44:45]
	v_cvt_pk_bf16_f32 v44, v48, v49
	v_cvt_pk_bf16_f32 v45, v50, v51
	v_cvt_pk_bf16_f32 v46, v40, v41
	v_cvt_pk_bf16_f32 v47, v42, v43
	s_and_saveexec_b64 s[40:41], vcc
	s_cbranch_execz .LBB0_185
	global_store_dwordx4 v[52:53], v[44:47], off sc1
.LBB0_185:
	s_or_b64 exec, exec, s[40:41]
	v_cvt_pk_bf16_f32 v36, v36, v37
	v_cvt_pk_bf16_f32 v37, v38, v39
	v_cvt_pk_bf16_f32 v38, v28, v29
	v_cvt_pk_bf16_f32 v39, v30, v31
	s_and_saveexec_b64 s[40:41], s[0:1]
	s_cbranch_execz .LBB0_187
	global_store_dwordx4 v[52:53], v[36:39], off offset:256 sc1
.LBB0_187:
	s_or_b64 exec, exec, s[40:41]
	v_add_u32_e32 v30, 0xa0, v155
	v_mov_b64_e32 v[28:29], s[16:17]
	v_mad_i64_i32 v[28:29], s[40:41], v30, s62, v[28:29]
	v_lshl_add_u64 v[36:37], v[144:145], 1, v[28:29]
	v_cvt_pk_bf16_f32 v28, v32, v33
	v_cvt_pk_bf16_f32 v29, v34, v35
	v_cvt_pk_bf16_f32 v30, v24, v25
	v_cvt_pk_bf16_f32 v31, v26, v27
	s_and_saveexec_b64 s[40:41], vcc
	s_cbranch_execz .LBB0_189
	global_store_dwordx4 v[36:37], v[28:31], off sc1
.LBB0_189:
	s_or_b64 exec, exec, s[40:41]
	v_cvt_pk_bf16_f32 v20, v20, v21
	v_cvt_pk_bf16_f32 v21, v22, v23
	v_cvt_pk_bf16_f32 v22, v12, v13
	v_cvt_pk_bf16_f32 v23, v14, v15
	s_and_saveexec_b64 s[40:41], s[0:1]
	s_cbranch_execz .LBB0_191
	global_store_dwordx4 v[36:37], v[20:23], off offset:256 sc1
.LBB0_191:
	s_or_b64 exec, exec, s[40:41]
	v_add_u32_e32 v14, 0xb0, v155
	v_mov_b64_e32 v[12:13], s[16:17]
	v_mad_i64_i32 v[12:13], s[40:41], v14, s62, v[12:13]
	v_lshl_add_u64 v[20:21], v[144:145], 1, v[12:13]
	v_cvt_pk_bf16_f32 v12, v16, v17
	v_cvt_pk_bf16_f32 v13, v18, v19
	v_cvt_pk_bf16_f32 v14, v8, v9
	v_cvt_pk_bf16_f32 v15, v10, v11
	s_and_saveexec_b64 s[40:41], vcc
	s_cbranch_execz .LBB0_193
	global_store_dwordx4 v[20:21], v[12:15], off sc1
.LBB0_193:
	s_or_b64 exec, exec, s[40:41]
	v_cvt_pk_bf16_f32 v4, v4, v5
	v_cvt_pk_bf16_f32 v5, v6, v7
	v_cvt_pk_bf16_f32 v6, v0, v1
	v_cvt_pk_bf16_f32 v7, v2, v3
	s_and_saveexec_b64 s[40:41], s[0:1]
	s_cbranch_execz .LBB0_158
	global_store_dwordx4 v[20:21], v[4:7], off offset:256 sc1
	s_branch .LBB0_158

.LBB0_201:
	s_cmpk_gt_i32 s36, 0xff
	s_mov_b64 s[30:31], -1
	s_cbranch_scc0 .LBB0_211
	s_cmpk_gt_u32 s36, 0x3bf
	s_cbranch_scc0 .LBB0_208
	s_cmpk_gt_u32 s36, 0x67f
	s_cbranch_scc0 .LBB0_205
	v_mov_b32_e32 v20, v177
	s_and_b32 s24, s40, 0x3ffc0
	s_and_b32 s45, s38, 0x3c0
	v_readlane_b32 s48, v252, 51
	v_ashrrev_i32_e32 v21, 6, v20
	s_lshl_b32 s30, s45, 2
	v_readlane_b32 s58, v252, 61
	v_add_u32_e32 v4, s24, v21
	v_readlane_b32 s59, v252, 62
	s_add_u32 s30, s58, s30
	v_lshlrev_b32_e32 v0, 2, v20
	v_ashrrev_i32_e32 v5, 31, v4
	v_add_u32_e32 v8, 8, v4
	v_add_u32_e32 v10, 16, v4
	s_addc_u32 s31, s59, 0
	v_and_b32_e32 v0, 0xfc, v0
	v_lshlrev_b64 v[6:7], 12, v[4:5]
	v_ashrrev_i32_e32 v9, 31, v8
	v_ashrrev_i32_e32 v11, 31, v10
	v_add_u32_e32 v12, 24, v4
	v_add_u32_e32 v14, 32, v4
	v_add_u32_e32 v16, 40, v4
	v_add_u32_e32 v18, 48, v4
	v_add_u32_e32 v4, 56, v4
	v_lshl_add_u64 v[2:3], s[30:31], 0, v[0:1]
	v_lshlrev_b64 v[8:9], 12, v[8:9]
	v_lshlrev_b64 v[10:11], 12, v[10:11]
	v_ashrrev_i32_e32 v13, 31, v12
	v_ashrrev_i32_e32 v15, 31, v14
	v_ashrrev_i32_e32 v17, 31, v16
	v_ashrrev_i32_e32 v19, 31, v18
	v_ashrrev_i32_e32 v5, 31, v4
	v_lshl_add_u64 v[6:7], v[2:3], 0, v[6:7]
	v_lshl_add_u64 v[8:9], v[2:3], 0, v[8:9]
	v_lshl_add_u64 v[10:11], v[2:3], 0, v[10:11]
	v_lshlrev_b64 v[12:13], 12, v[12:13]
	v_lshlrev_b64 v[14:15], 12, v[14:15]
	v_lshlrev_b64 v[16:17], 12, v[16:17]
	v_lshlrev_b64 v[18:19], 12, v[18:19]
	v_lshlrev_b64 v[4:5], 12, v[4:5]
	v_lshl_add_u64 v[12:13], v[2:3], 0, v[12:13]
	v_lshl_add_u64 v[14:15], v[2:3], 0, v[14:15]
	v_lshl_add_u64 v[16:17], v[2:3], 0, v[16:17]
	v_lshl_add_u64 v[18:19], v[2:3], 0, v[18:19]
	v_lshl_add_u64 v[2:3], v[2:3], 0, v[4:5]
	global_load_dword v4, v[6:7], off
	global_load_dword v5, v[8:9], off
	s_nop 0
	global_load_dword v6, v[10:11], off
	global_load_dword v7, v[12:13], off
	global_load_dword v8, v[14:15], off
	global_load_dword v9, v[16:17], off
	s_nop 0
	global_load_dword v10, v[18:19], off
	global_load_dword v11, v[2:3], off
	v_lshlrev_b32_e32 v13, 3, v20
	v_ashrrev_i32_e32 v12, 3, v20
	v_and_b32_e32 v13, 56, v13
	v_mov_b64_e32 v[2:3], s[4:5]
	v_mul_lo_u32 v14, v21, s42
	v_lshlrev_b32_e32 v15, 2, v12
	v_add_u32_e32 v12, s45, v12
	v_mul_u32_u24_e32 v16, 0x104, v13
	v_add3_u32 v14, 0, v0, v14
	v_mad_i64_i32 v[2:3], s[30:31], v12, s43, v[2:3]
	v_add3_u32 v12, 0, v16, v15
	v_lshlrev_b32_e32 v0, 1, v13
	v_add_u32_e32 v13, 0x400, v12
	s_lshl_b32 s24, s24, 1
	v_lshl_add_u64 v[2:3], v[2:3], 0, s[24:25]
	v_readlane_b32 s49, v252, 52
	v_readlane_b32 s50, v252, 53
	v_readlane_b32 s51, v252, 54
	v_readlane_b32 s52, v252, 55
	v_readlane_b32 s53, v252, 56
	v_readlane_b32 s54, v252, 57
	v_readlane_b32 s55, v252, 58
	v_readlane_b32 s56, v252, 59
	v_readlane_b32 s57, v252, 60
	v_readlane_b32 s60, v252, 63
	v_readlane_b32 s61, v253, 0
	v_readlane_b32 s62, v253, 1
	v_readlane_b32 s63, v253, 2
	s_mov_b64 s[30:31], 0
	s_waitcnt vmcnt(0)
	ds_write_b32 v14, v4
	ds_write_b32 v14, v5 offset:2080
	ds_write_b32 v14, v6 offset:4160
	ds_write_b32 v14, v7 offset:6240
	ds_write_b32 v14, v8 offset:8320
	ds_write_b32 v14, v9 offset:10400
	ds_write_b32 v14, v10 offset:12480
	ds_write_b32 v14, v11 offset:14560
	s_waitcnt lgkmcnt(0)
	s_barrier
	ds_read2_b32 v[4:5], v12 offset1:65
	ds_read2_b32 v[6:7], v12 offset0:130 offset1:195
	ds_read2_b32 v[8:9], v13 offset0:4 offset1:69
	ds_read2_b32 v[10:11], v13 offset0:134 offset1:199
	v_lshl_add_u64 v[12:13], v[2:3], 0, v[0:1]
	s_waitcnt lgkmcnt(3)
	v_cvt_pk_bf16_f32 v2, v4, v5
	s_waitcnt lgkmcnt(2)
	v_cvt_pk_bf16_f32 v3, v6, v7
	s_waitcnt lgkmcnt(1)
	v_cvt_pk_bf16_f32 v4, v8, v9
	s_waitcnt lgkmcnt(0)
	v_cvt_pk_bf16_f32 v5, v10, v11
	global_store_dwordx4 v[12:13], v[2:5], off sc1
	s_barrier
.LBB0_205:
	s_andn2_b64 vcc, exec, s[30:31]
	s_cbranch_vccnz .LBB0_207
	s_add_i32 s24, s36, 0xfc40
	s_and_b32 s30, s24, 0xffff
	s_mul_i32 s30, s30, 0xba2f
	s_lshr_b32 s45, s30, 21
	s_mul_i32 s30, s45, 44
	s_sub_i32 s24, s24, s30
	s_lshl_b32 s46, s24, 6
	s_lshl_b32 s24, s24, 8
	v_readlane_b32 s48, v252, 51
	v_mov_b32_e32 v18, v177
	s_and_b32 s24, s24, 0x3ff00
	v_readlane_b32 s52, v252, 55
	v_readlane_b32 s53, v252, 56
	v_ashrrev_i32_e32 v19, 6, v18
	s_add_u32 s30, s52, s24
	v_lshlrev_b32_e32 v0, 2, v18
	s_addc_u32 s31, s53, 0
	v_and_b32_e32 v0, 0xfc, v0
	v_lshl_add_u32 v20, s45, 6, v19
	v_lshl_add_u64 v[2:3], s[30:31], 0, v[0:1]
	v_add_u32_e32 v6, 8, v20
	v_add_u32_e32 v8, 16, v20
	v_add_u32_e32 v10, 24, v20
	v_mad_i64_i32 v[4:5], s[30:31], v20, s44, v[2:3]
	v_mad_i64_i32 v[6:7], s[30:31], v6, s44, v[2:3]
	v_mad_i64_i32 v[8:9], s[30:31], v8, s44, v[2:3]
	v_mad_i64_i32 v[10:11], s[30:31], v10, s44, v[2:3]
	v_add_u32_e32 v12, 32, v20
	v_add_u32_e32 v14, 40, v20
	v_add_u32_e32 v16, 48, v20
	v_add_u32_e32 v20, 56, v20
	v_mad_i64_i32 v[12:13], s[30:31], v12, s44, v[2:3]
	v_mad_i64_i32 v[14:15], s[30:31], v14, s44, v[2:3]
	v_mad_i64_i32 v[16:17], s[30:31], v16, s44, v[2:3]
	v_mad_i64_i32 v[2:3], s[30:31], v20, s44, v[2:3]
	global_load_dword v4, v[4:5], off
	s_nop 0
	global_load_dword v5, v[6:7], off
	s_nop 0
	global_load_dword v6, v[8:9], off
	global_load_dword v7, v[10:11], off
	s_nop 0
	global_load_dword v8, v[12:13], off
	global_load_dword v9, v[14:15], off
	global_load_dword v10, v[16:17], off
	global_load_dword v11, v[2:3], off
	v_lshlrev_b32_e32 v3, 3, v18
	v_ashrrev_i32_e32 v2, 3, v18
	v_mul_lo_u32 v12, v19, s42
	v_and_b32_e32 v3, 56, v3
	s_addk_i32 s46, 0xb00
	v_lshlrev_b32_e32 v13, 2, v2
	v_add3_u32 v12, 0, v0, v12
	v_mul_u32_u24_e32 v0, 0x104, v3
	s_and_b32 s30, s46, 0xffc0
	v_add3_u32 v13, 0, v0, v13
	v_add_u32_e32 v2, s30, v2
	v_add_u32_e32 v14, 0x400, v13
	v_lshlrev_b32_e32 v0, 1, v3
	v_ashrrev_i32_e32 v3, 31, v2
	v_lshlrev_b64 v[2:3], 11, v[2:3]
	s_lshl_b32 s24, s45, 7
	v_lshl_add_u64 v[2:3], s[2:3], 0, v[2:3]
	v_lshl_add_u64 v[2:3], v[2:3], 0, s[24:25]
	v_readlane_b32 s49, v252, 52
	v_readlane_b32 s50, v252, 53
	v_readlane_b32 s51, v252, 54
	v_readlane_b32 s54, v252, 57
	v_readlane_b32 s55, v252, 58
	v_readlane_b32 s56, v252, 59
	v_readlane_b32 s57, v252, 60
	v_readlane_b32 s58, v252, 61
	v_readlane_b32 s59, v252, 62
	v_readlane_b32 s60, v252, 63
	v_readlane_b32 s61, v253, 0
	v_readlane_b32 s62, v253, 1
	v_readlane_b32 s63, v253, 2
	s_waitcnt vmcnt(0)
	ds_write_b32 v12, v4
	ds_write_b32 v12, v5 offset:2080
	ds_write_b32 v12, v6 offset:4160
	ds_write_b32 v12, v7 offset:6240
	ds_write_b32 v12, v8 offset:8320
	ds_write_b32 v12, v9 offset:10400
	ds_write_b32 v12, v10 offset:12480
	ds_write_b32 v12, v11 offset:14560
	s_waitcnt lgkmcnt(0)
	s_barrier
	ds_read2_b32 v[4:5], v13 offset1:65
	ds_read2_b32 v[6:7], v13 offset0:130 offset1:195
	ds_read2_b32 v[8:9], v14 offset0:4 offset1:69
	ds_read2_b32 v[10:11], v14 offset0:134 offset1:199
	v_lshl_add_u64 v[12:13], v[2:3], 0, v[0:1]
	s_waitcnt lgkmcnt(3)
	v_cvt_pk_bf16_f32 v2, v4, v5
	s_waitcnt lgkmcnt(2)
	v_cvt_pk_bf16_f32 v3, v6, v7
	s_waitcnt lgkmcnt(1)
	v_cvt_pk_bf16_f32 v4, v8, v9
	s_waitcnt lgkmcnt(0)
	v_cvt_pk_bf16_f32 v5, v10, v11
	global_store_dwordx4 v[12:13], v[2:5], off sc1
	s_barrier

.LBB0_208:
	s_andn2_b64 vcc, exec, s[30:31]
	s_cbranch_vccnz .LBB0_210
	s_add_i32 s24, s36, 0xff00
	s_and_b32 s30, s24, 0xffff
	s_mul_i32 s30, s30, 0xba2f
	s_lshr_b32 s45, s30, 21
	s_mul_i32 s30, s45, 44
	s_sub_i32 s24, s24, s30
	s_lshl_b32 s24, s24, 6
	s_and_b32 s24, s24, 0xffc0
	v_readlane_b32 s48, v252, 51
	v_mov_b32_e32 v18, v177
	s_lshl_b32 s30, s24, 2
	v_readlane_b32 s50, v252, 53
	v_readlane_b32 s51, v252, 54
	v_ashrrev_i32_e32 v19, 6, v18
	s_add_u32 s30, s50, s30
	v_lshlrev_b32_e32 v0, 2, v18
	s_addc_u32 s31, s51, 0
	v_and_b32_e32 v0, 0xfc, v0
	v_lshl_add_u32 v20, s45, 6, v19
	v_lshl_add_u64 v[2:3], s[30:31], 0, v[0:1]
	v_add_u32_e32 v6, 8, v20
	v_add_u32_e32 v8, 16, v20
	v_add_u32_e32 v10, 24, v20
	v_mad_i64_i32 v[4:5], s[30:31], v20, s44, v[2:3]
	v_mad_i64_i32 v[6:7], s[30:31], v6, s44, v[2:3]
	v_mad_i64_i32 v[8:9], s[30:31], v8, s44, v[2:3]
	v_mad_i64_i32 v[10:11], s[30:31], v10, s44, v[2:3]
	v_add_u32_e32 v12, 32, v20
	v_add_u32_e32 v14, 40, v20
	v_add_u32_e32 v16, 48, v20
	v_add_u32_e32 v20, 56, v20
	v_mad_i64_i32 v[12:13], s[30:31], v12, s44, v[2:3]
	v_mad_i64_i32 v[14:15], s[30:31], v14, s44, v[2:3]
	v_mad_i64_i32 v[16:17], s[30:31], v16, s44, v[2:3]
	v_mad_i64_i32 v[2:3], s[30:31], v20, s44, v[2:3]
	global_load_dword v4, v[4:5], off
	s_nop 0
	global_load_dword v5, v[6:7], off
	s_nop 0
	global_load_dword v6, v[8:9], off
	global_load_dword v7, v[10:11], off
	s_nop 0
	global_load_dword v8, v[12:13], off
	global_load_dword v9, v[14:15], off
	global_load_dword v10, v[16:17], off
	global_load_dword v11, v[2:3], off
	v_lshlrev_b32_e32 v3, 3, v18
	v_ashrrev_i32_e32 v2, 3, v18
	v_mul_lo_u32 v12, v19, s42
	v_and_b32_e32 v13, 56, v3
	v_lshlrev_b32_e32 v3, 2, v2
	v_add3_u32 v12, 0, v0, v12
	v_mul_u32_u24_e32 v0, 0x104, v13
	v_add3_u32 v14, 0, v0, v3
	v_add_u32_e32 v2, s24, v2
	v_add_u32_e32 v15, 0x400, v14
	v_ashrrev_i32_e32 v3, 31, v2
	v_lshlrev_b64 v[2:3], 11, v[2:3]
	s_lshl_b32 s24, s45, 7
	v_lshl_add_u64 v[2:3], s[2:3], 0, v[2:3]
	v_lshlrev_b32_e32 v0, 1, v13
	v_lshl_add_u64 v[2:3], v[2:3], 0, s[24:25]
	v_readlane_b32 s49, v252, 52
	v_readlane_b32 s52, v252, 55
	v_readlane_b32 s53, v252, 56
	v_readlane_b32 s54, v252, 57
	v_readlane_b32 s55, v252, 58
	v_readlane_b32 s56, v252, 59
	v_readlane_b32 s57, v252, 60
	v_readlane_b32 s58, v252, 61
	v_readlane_b32 s59, v252, 62
	v_readlane_b32 s60, v252, 63
	v_readlane_b32 s61, v253, 0
	v_readlane_b32 s62, v253, 1
	v_readlane_b32 s63, v253, 2
	s_waitcnt vmcnt(0)
	ds_write_b32 v12, v4
	ds_write_b32 v12, v5 offset:2080
	ds_write_b32 v12, v6 offset:4160
	ds_write_b32 v12, v7 offset:6240
	ds_write_b32 v12, v8 offset:8320
	ds_write_b32 v12, v9 offset:10400
	ds_write_b32 v12, v10 offset:12480
	ds_write_b32 v12, v11 offset:14560
	s_waitcnt lgkmcnt(0)
	s_barrier
	ds_read2_b32 v[4:5], v14 offset1:65
	ds_read2_b32 v[6:7], v14 offset0:130 offset1:195
	ds_read2_b32 v[8:9], v15 offset0:4 offset1:69
	ds_read2_b32 v[10:11], v15 offset0:134 offset1:199
	v_lshl_add_u64 v[12:13], v[2:3], 0, v[0:1]
	s_waitcnt lgkmcnt(3)
	v_cvt_pk_bf16_f32 v2, v4, v5
	s_waitcnt lgkmcnt(2)
	v_cvt_pk_bf16_f32 v3, v6, v7
	s_waitcnt lgkmcnt(1)
	v_cvt_pk_bf16_f32 v4, v8, v9
	s_waitcnt lgkmcnt(0)
	v_cvt_pk_bf16_f32 v5, v10, v11
	global_store_dwordx4 v[12:13], v[2:5], off sc1
	s_barrier

.LBB0_211:
	s_andn2_b64 vcc, exec, s[30:31]
	s_cbranch_vccnz .LBB0_200
	s_ashr_i32 s24, s36, 31
	s_lshr_b32 s24, s24, 28
	s_add_i32 s24, s36, s24
	s_ashr_i32 s24, s24, 4
	s_lshl_b32 s30, s24, 6
	s_lshl_b32 s24, s24, 10
	v_readlane_b32 s48, v252, 35
	s_sub_i32 s46, s38, s24
	v_mov_b32_e32 v20, v177
	v_readlane_b32 s49, v252, 36
	v_readlane_b32 s50, v252, 37
	v_readlane_b32 s51, v252, 38
	v_readlane_b32 s52, v252, 39
	v_readlane_b32 s53, v252, 40
	v_readlane_b32 s54, v252, 41
	v_readlane_b32 s55, v252, 42
	v_readlane_b32 s56, v252, 43
	v_readlane_b32 s57, v252, 44
	v_readlane_b32 s58, v252, 45
	v_readlane_b32 s59, v252, 46
	s_ashr_i32 s47, s46, 31
	v_ashrrev_i32_e32 v21, 6, v20
	v_readlane_b32 s60, v252, 47
	v_readlane_b32 s61, v252, 48
	v_readlane_b32 s62, v252, 49
	v_readlane_b32 s63, v252, 50
	s_mov_b64 s[48:49], s[52:53]
	s_lshl_b64 s[46:47], s[46:47], 2
	s_mov_b64 s[50:51], s[54:55]
	s_mov_b64 s[52:53], s[56:57]
	s_mov_b64 s[54:55], s[58:59]
	s_mov_b64 s[56:57], s[60:61]
	s_mov_b64 s[58:59], s[62:63]
	v_add_u32_e32 v4, s30, v21
	s_add_u32 s46, s58, s46
	v_lshlrev_b32_e32 v0, 2, v20
	v_ashrrev_i32_e32 v5, 31, v4
	v_add_u32_e32 v8, 8, v4
	v_add_u32_e32 v10, 16, v4
	s_addc_u32 s47, s59, s47
	v_and_b32_e32 v0, 0xfc, v0
	v_lshlrev_b64 v[6:7], 12, v[4:5]
	v_ashrrev_i32_e32 v9, 31, v8
	v_ashrrev_i32_e32 v11, 31, v10
	v_add_u32_e32 v12, 24, v4
	v_add_u32_e32 v14, 32, v4
	v_add_u32_e32 v16, 40, v4
	v_add_u32_e32 v18, 48, v4
	v_add_u32_e32 v4, 56, v4
	v_lshl_add_u64 v[2:3], s[46:47], 0, v[0:1]
	v_lshlrev_b64 v[8:9], 12, v[8:9]
	v_lshlrev_b64 v[10:11], 12, v[10:11]
	v_ashrrev_i32_e32 v13, 31, v12
	v_ashrrev_i32_e32 v15, 31, v14
	v_ashrrev_i32_e32 v17, 31, v16
	v_ashrrev_i32_e32 v19, 31, v18
	v_ashrrev_i32_e32 v5, 31, v4
	v_lshl_add_u64 v[6:7], v[2:3], 0, v[6:7]
	v_lshl_add_u64 v[8:9], v[2:3], 0, v[8:9]
	v_lshl_add_u64 v[10:11], v[2:3], 0, v[10:11]
	v_lshlrev_b64 v[12:13], 12, v[12:13]
	v_lshlrev_b64 v[14:15], 12, v[14:15]
	v_lshlrev_b64 v[16:17], 12, v[16:17]
	v_lshlrev_b64 v[18:19], 12, v[18:19]
	v_lshlrev_b64 v[4:5], 12, v[4:5]
	v_lshl_add_u64 v[12:13], v[2:3], 0, v[12:13]
	v_lshl_add_u64 v[14:15], v[2:3], 0, v[14:15]
	v_lshl_add_u64 v[16:17], v[2:3], 0, v[16:17]
	v_lshl_add_u64 v[18:19], v[2:3], 0, v[18:19]
	v_lshl_add_u64 v[2:3], v[2:3], 0, v[4:5]
	global_load_dword v4, v[6:7], off
	global_load_dword v5, v[8:9], off
	s_nop 0
	global_load_dword v6, v[10:11], off
	global_load_dword v7, v[12:13], off
	global_load_dword v8, v[14:15], off
	global_load_dword v9, v[16:17], off
	s_nop 0
	global_load_dword v10, v[18:19], off
	global_load_dword v11, v[2:3], off
	v_lshlrev_b32_e32 v3, 3, v20
	v_ashrrev_i32_e32 v2, 3, v20
	v_mul_lo_u32 v12, v21, s42
	v_and_b32_e32 v13, 56, v3
	v_lshlrev_b32_e32 v3, 2, v2
	v_add3_u32 v12, 0, v0, v12
	v_mul_u32_u24_e32 v0, 0x104, v13
	v_add3_u32 v14, 0, v0, v3
	v_subrev_u32_e32 v0, s24, v2
	v_add_u32_e32 v2, s38, v0
	v_add_u32_e32 v15, 0x400, v14
	v_ashrrev_i32_e32 v3, 31, v2
	v_lshlrev_b64 v[2:3], 11, v[2:3]
	v_lshl_add_u64 v[2:3], s[0:1], 0, v[2:3]
	s_ashr_i32 s31, s30, 31
	v_lshl_add_u64 v[2:3], s[30:31], 1, v[2:3]
	v_lshlrev_b32_e32 v0, 1, v13
	s_waitcnt vmcnt(0)
	ds_write_b32 v12, v4
	ds_write_b32 v12, v5 offset:2080
	ds_write_b32 v12, v6 offset:4160
	ds_write_b32 v12, v7 offset:6240
	ds_write_b32 v12, v8 offset:8320
	ds_write_b32 v12, v9 offset:10400
	ds_write_b32 v12, v10 offset:12480
	ds_write_b32 v12, v11 offset:14560
	s_waitcnt lgkmcnt(0)
	s_barrier
	ds_read2_b32 v[4:5], v14 offset1:65
	ds_read2_b32 v[6:7], v14 offset0:130 offset1:195
	ds_read2_b32 v[8:9], v15 offset0:4 offset1:69
	ds_read2_b32 v[10:11], v15 offset0:134 offset1:199
	v_lshl_add_u64 v[12:13], v[2:3], 0, v[0:1]
	s_waitcnt lgkmcnt(3)
	v_cvt_pk_bf16_f32 v2, v4, v5
	s_waitcnt lgkmcnt(2)
	v_cvt_pk_bf16_f32 v3, v6, v7
	s_waitcnt lgkmcnt(1)
	v_cvt_pk_bf16_f32 v4, v8, v9
	s_waitcnt lgkmcnt(0)
	v_cvt_pk_bf16_f32 v5, v10, v11
	global_store_dwordx4 v[12:13], v[2:5], off sc1
	s_barrier
	s_branch .LBB0_200
.LBB0_213:
	s_waitcnt vmcnt(0)
	s_waitcnt vmcnt(0) lgkmcnt(0)
	s_barrier
	s_and_saveexec_b64 s[0:1], s[34:35]
	s_cbranch_execz .LBB0_265
	s_add_u32 s98, s98, 1
	v_mov_b32_e32 v7, 0x26c00
	ds_read2_b32 v[8:9], v7 offset1:1
	v_mov_b32_e32 v2, s99
	v_mov_b32_e32 v3, 1
	global_atomic_add v4, v2, v3, s[100:101] sc0
	v_add_u32_e32 v2, 0x1000, v2
	v_mov_b32_e32 v10, 0x2480
	s_waitcnt vmcnt(0) lgkmcnt(0)
	v_add_u32_e32 v4, 1, v4
	v_mul_lo_u32 v5, v8, s98
	v_mul_lo_u32 v9, v9, s98
	v_cmp_eq_u32_e32 vcc, v4, v5
	s_and_saveexec_b64 s[4:5], vcc
	s_cbranch_execz .Lh2_skip_1
	buffer_wbl2 sc1
	s_waitcnt vmcnt(0)
	global_atomic_add v10, v3, s[100:101]
	global_atomic_add v10, v3, s[100:101] offset:256
	global_atomic_add v10, v3, s[100:101] offset:512
	global_atomic_add v10, v3, s[100:101] offset:768
	global_atomic_add v10, v3, s[100:101] offset:1024
	global_atomic_add v10, v3, s[100:101] offset:1280
	global_atomic_add v10, v3, s[100:101] offset:1536
	global_atomic_add v10, v3, s[100:101] offset:1792
	global_atomic_add v10, v3, s[100:101] offset:2048
	global_atomic_add v10, v3, s[100:101] offset:2304
	global_atomic_add v10, v3, s[100:101] offset:2560
	global_atomic_add v10, v3, s[100:101] offset:2816
	global_atomic_add v10, v3, s[100:101] offset:3072
	global_atomic_add v10, v3, s[100:101] offset:3328
	global_atomic_add v10, v3, s[100:101] offset:3584
	global_atomic_add v10, v3, s[100:101] offset:3840

.LBB0_323:
	s_waitcnt vmcnt(0)
	s_barrier
	s_and_saveexec_b64 s[0:1], s[28:29]
	s_xor_b64 s[0:1], exec, s[0:1]
	s_lshl_b32 s2, s33, 6
	s_mov_b32 s3, 0
	s_or_saveexec_b64 s[0:1], s[0:1]
	v_mov_b64_e32 v[0:1], s[2:3]
	s_xor_b64 exec, exec, s[0:1]
	s_cbranch_execz .LBB0_378
	s_add_u32 s98, s98, 1
	v_mov_b32_e32 v7, 0x26c00
	ds_read2_b32 v[8:9], v7 offset1:1
	v_mov_b32_e32 v2, s99
	v_mov_b32_e32 v3, 1
	global_atomic_add v4, v2, v3, s[100:101] sc0
	v_add_u32_e32 v2, 0x1000, v2
	v_mov_b32_e32 v10, 0x2480
	s_waitcnt vmcnt(0) lgkmcnt(0)
	v_add_u32_e32 v4, 1, v4
	v_mul_lo_u32 v5, v8, s98
	v_mul_lo_u32 v9, v9, s98
	v_cmp_eq_u32_e32 vcc, v4, v5
	s_and_saveexec_b64 s[4:5], vcc
	s_cbranch_execz .Lh2_skip_2
	buffer_wbl2 sc1
	s_waitcnt vmcnt(0)
	global_atomic_add v10, v3, s[100:101]
	global_atomic_add v10, v3, s[100:101] offset:256
	global_atomic_add v10, v3, s[100:101] offset:512
	global_atomic_add v10, v3, s[100:101] offset:768
	global_atomic_add v10, v3, s[100:101] offset:1024
	global_atomic_add v10, v3, s[100:101] offset:1280
	global_atomic_add v10, v3, s[100:101] offset:1536
	global_atomic_add v10, v3, s[100:101] offset:1792
	global_atomic_add v10, v3, s[100:101] offset:2048
	global_atomic_add v10, v3, s[100:101] offset:2304
	global_atomic_add v10, v3, s[100:101] offset:2560
	global_atomic_add v10, v3, s[100:101] offset:2816
	global_atomic_add v10, v3, s[100:101] offset:3072
	global_atomic_add v10, v3, s[100:101] offset:3328
	global_atomic_add v10, v3, s[100:101] offset:3584
	global_atomic_add v10, v3, s[100:101] offset:3840

.LBB0_378:
	v_writelane_b32 v253, s80, 7
	s_nop 1
	v_writelane_b32 v253, s81, 8
	v_writelane_b32 v253, s16, 9
	s_nop 1
	v_writelane_b32 v253, s17, 10
	v_writelane_b32 v253, s14, 11
	s_nop 1
	v_writelane_b32 v253, s15, 12
	v_writelane_b32 v253, s8, 13
	s_nop 1
	v_writelane_b32 v253, s9, 14
	s_or_b64 exec, exec, s[0:1]
	s_add_u32 s21, s76, 0xf984000
	s_addc_u32 s22, s77, 0
	s_add_u32 s24, s76, 0x13000
	s_addc_u32 s25, s77, 0
	s_add_u32 s28, s76, 0x23000
	s_addc_u32 s29, s77, 0
	s_cmpk_lt_i32 s72, 0x400
	s_cselect_b64 s[10:11], -1, 0
	s_ashr_i32 s1, s72, 3
	v_writelane_b32 v253, s1, 15
	s_lshl_b32 s1, s1, 6
	v_writelane_b32 v253, s1, 16
	s_add_i32 s1, s1, -1
	v_writelane_b32 v253, s1, 17
	s_lshl_b32 s1, s72, 6
	s_and_b32 s2, s1, 0x1c0
	v_writelane_b32 v253, s2, 18
	s_add_u32 s2, s76, 0x1b000
	s_addc_u32 s3, s77, 0
	v_writelane_b32 v253, s2, 19
	s_mul_i32 s0, s79, s78
	s_mul_i32 s0, s0, s71
	v_writelane_b32 v253, s3, 20
	s_add_u32 s2, s76, 0x12000
	s_addc_u32 s3, s77, 0
	v_writelane_b32 v253, s2, 21
	v_lshl_add_u64 v[0:1], v[0:1], 2, s[6:7]
	v_mov_b32_e32 v183, 1
	v_writelane_b32 v253, s3, 22
	s_add_u32 s2, s76, 0x43000
	s_addc_u32 s3, s77, 0
	v_writelane_b32 v253, s9, 23
	s_and_b32 s4, s9, 0xffffffc0
	s_and_b32 s1, s1, 0x180
	v_writelane_b32 v253, s4, 24
	s_add_i32 s4, s1, 0xffffff00
	v_writelane_b32 v253, s4, 25
	v_readlane_b32 s4, v252, 34
	s_and_b32 s4, s4, 0x200
	s_or_b32 s4, s4, s1
	v_writelane_b32 v253, s4, 26
	s_addk_i32 s4, 0x380
	s_bitset1_b32 s1, 9
	v_writelane_b32 v253, s4, 27
	s_add_u32 s26, s76, 0xf980200
	v_writelane_b32 v253, s1, 28
	s_addc_u32 s27, s77, 0
	v_writelane_b32 v253, s0, 29
	s_add_u32 s0, s76, 0xf980400
	s_addc_u32 s1, s77, 0
	v_writelane_b32 v253, s0, 30
	v_mov_b32_e32 v184, 0x358637bd
	v_mbcnt_hi_u32_b32 v179, -1, v148
	v_writelane_b32 v253, s1, 31
	s_add_u32 s0, s76, 0xf980500
	s_addc_u32 s1, s77, 0
	v_writelane_b32 v253, s0, 32
	v_mov_b32_e32 v185, 2
	v_mov_b32_e32 v186, 0x2000
	v_writelane_b32 v253, s1, 33
	s_add_u32 s0, s76, 0xf980600
	s_addc_u32 s1, s77, 0
	v_writelane_b32 v253, s0, 34
	v_mov_b32_e32 v187, 0x41b17218
	v_mov_b64_e32 v[124:125], 0xb988000
	v_writelane_b32 v253, s1, 35
	s_add_u32 s0, s76, 0xf980700
	s_addc_u32 s1, s77, 0
	v_writelane_b32 v253, s0, 36
	s_mov_b32 s31, 0x3f317217
	s_mov_b32 s96, 0x7f800000
	v_writelane_b32 v253, s1, 37
	s_add_u32 s0, s76, 0xf980800
	s_addc_u32 s1, s77, 0
	v_writelane_b32 v253, s0, 38
	s_movk_i32 s23, 0xffd0
	s_mov_b32 s68, 0
	v_writelane_b32 v253, s1, 39
	s_add_u32 s0, s76, 0xf980900
	s_addc_u32 s1, s77, 0
	v_writelane_b32 v253, s0, 40
	s_mov_b64 s[66:67], -1
	s_nop 0
	v_writelane_b32 v253, s1, 41
	s_add_u32 s0, s76, 0xf980a00
	s_addc_u32 s1, s77, 0
	v_writelane_b32 v253, s0, 42
	s_barrier
	s_nop 0
	v_writelane_b32 v253, s1, 43
	s_add_u32 s0, s76, 0xf980b00
	s_addc_u32 s1, s77, 0
	v_writelane_b32 v253, s0, 44
	s_nop 1
	v_writelane_b32 v253, s1, 45
	s_add_u32 s0, s76, 0xf980c00
	s_addc_u32 s1, s77, 0
	v_writelane_b32 v253, s0, 46
	s_nop 1
	v_writelane_b32 v253, s1, 47
	s_add_u32 s0, s76, 0xf980d00
	s_addc_u32 s1, s77, 0
	v_writelane_b32 v253, s0, 48
	s_nop 1
	v_writelane_b32 v253, s1, 49
	s_add_u32 s0, s76, 0xf980e00
	s_addc_u32 s1, s77, 0
	v_writelane_b32 v253, s0, 50
	s_nop 1
	v_writelane_b32 v253, s1, 51
	s_add_u32 s0, s76, 0xf980f00
	s_addc_u32 s1, s77, 0
	v_writelane_b32 v253, s0, 52
	s_nop 1
	v_writelane_b32 v253, s1, 53
	s_add_u32 s0, s76, 0xf981000
	s_addc_u32 s1, s77, 0
	v_writelane_b32 v253, s0, 54
	s_nop 1
	v_writelane_b32 v253, s1, 55
	s_add_u32 s0, s76, 0xf981100
	s_addc_u32 s1, s77, 0
	v_writelane_b32 v253, s0, 56
	s_nop 1
	v_writelane_b32 v253, s1, 57
	s_add_u32 s0, s76, 0xf981200
	s_addc_u32 s1, s77, 0
	v_writelane_b32 v253, s0, 58
	s_nop 1
	v_writelane_b32 v253, s1, 59
	s_add_u32 s0, s76, 0xf981300
	s_addc_u32 s1, s77, 0
	v_writelane_b32 v253, s0, 60
	s_cmp_eq_u32 s33, 15
	s_nop 0
	v_writelane_b32 v253, s1, 61
	s_cselect_b64 s[0:1], -1, 0
	v_writelane_b32 v253, s0, 62
	s_cmp_eq_u32 s33, 14
	s_nop 0
	v_writelane_b32 v253, s1, 63
	s_cselect_b64 s[0:1], -1, 0
	v_writelane_b32 v254, s0, 0
	s_cmp_eq_u32 s33, 13
	s_nop 0
	v_writelane_b32 v254, s1, 1
	s_cselect_b64 s[0:1], -1, 0
	v_writelane_b32 v254, s0, 2
	s_cmp_eq_u32 s33, 12
	s_nop 0
	v_writelane_b32 v254, s1, 3
	s_cselect_b64 s[0:1], -1, 0
	v_writelane_b32 v254, s0, 4
	s_cmp_eq_u32 s33, 11
	s_nop 0
	v_writelane_b32 v254, s1, 5
	s_cselect_b64 s[0:1], -1, 0
	v_writelane_b32 v254, s0, 6
	s_cmp_eq_u32 s33, 10
	s_nop 0
	v_writelane_b32 v254, s1, 7
	s_mov_b64 s[0:1], 0x1400
	v_lshl_add_u64 v[162:163], v[0:1], 0, s[0:1]
	s_mov_b64 s[0:1], 0x2400
	v_lshl_add_u64 v[160:161], v[0:1], 0, s[0:1]
	s_cselect_b64 s[0:1], -1, 0
	v_writelane_b32 v254, s0, 8
	s_cmp_eq_u32 s33, 9
	v_cvt_f32_u32_e32 v0, s78
	v_writelane_b32 v254, s1, 9
	v_writelane_b32 v254, s10, 10
	s_cselect_b64 s[0:1], -1, 0
	s_cmp_eq_u32 s33, 8
	v_writelane_b32 v254, s11, 11
	v_writelane_b32 v254, s0, 12
	v_cndmask_b32_e64 v182, 0, 1, s[10:11]
	v_readlane_b32 s4, v252, 51
	v_writelane_b32 v254, s1, 13
	s_cselect_b64 s[0:1], -1, 0
	v_writelane_b32 v254, s0, 14
	s_cmp_eq_u32 s33, 7
	v_rcp_iflag_f32_e32 v0, v0
	v_writelane_b32 v254, s1, 15
	s_cselect_b64 s[0:1], -1, 0
	v_writelane_b32 v254, s0, 16
	s_cmp_eq_u32 s33, 6
	v_readlane_b32 s18, v253, 1
	v_writelane_b32 v254, s1, 17
	s_cselect_b64 s[0:1], -1, 0
	v_writelane_b32 v254, s0, 18
	s_cmp_eq_u32 s33, 5
	v_readlane_b32 s5, v252, 52
	v_writelane_b32 v254, s1, 19
	s_cselect_b64 s[0:1], -1, 0
	v_writelane_b32 v254, s0, 20
	s_cmp_eq_u32 s33, 4
	v_readlane_b32 s19, v253, 2
	v_writelane_b32 v254, s1, 21
	s_cselect_b64 s[0:1], -1, 0
	v_writelane_b32 v254, s0, 22
	s_cmp_eq_u32 s33, 3
	v_mul_f32_e32 v0, 0x4f7ffffe, v0
	v_writelane_b32 v254, s1, 23
	s_cselect_b64 s[0:1], -1, 0
	v_writelane_b32 v254, s0, 24
	s_cmp_eq_u32 s33, 2
	v_cvt_u32_f32_e32 v0, v0
	v_writelane_b32 v254, s1, 25
	s_cselect_b64 s[0:1], -1, 0
	v_writelane_b32 v254, s0, 26
	s_cmp_eq_u32 s33, 1
	v_readlane_b32 s8, v252, 55
	v_writelane_b32 v254, s1, 27
	s_cselect_b64 s[0:1], -1, 0
	v_writelane_b32 v254, s0, 28
	s_cmp_eq_u32 s33, 0
	s_mov_b32 s8, s21
	v_writelane_b32 v254, s1, 29
	s_cselect_b64 s[0:1], -1, 0
	v_writelane_b32 v254, s0, 30
	s_movk_i32 s21, 0x1000
	v_readlane_b32 s9, v252, 56
	v_writelane_b32 v254, s1, 31
	s_add_u32 s0, s76, 0xf983400
	s_addc_u32 s1, s77, 0
	v_writelane_b32 v254, s0, 32
	v_readlane_b32 s14, v252, 61
	v_readlane_b32 s15, v252, 62
	v_writelane_b32 v254, s1, 33
	s_add_u32 s0, s76, 0xf983500
	s_addc_u32 s1, s77, 0
	v_writelane_b32 v254, s0, 34
	s_mov_b32 s9, s22
	s_mov_b64 s[14:15], s[24:25]
	v_writelane_b32 v254, s1, 35
	s_lshr_b32 s0, s78, 31
	s_add_i32 s0, s78, s0
	s_ashr_i32 s0, s0, 1
	s_add_i32 s0, s0, s72
	s_add_u32 s4, s18, 0x4000000
	s_addc_u32 s5, s19, 0
	v_writelane_b32 v254, s4, 36
	v_readlane_b32 s16, v252, 63
	v_readlane_b32 s17, v253, 0
	v_writelane_b32 v254, s5, 37
	s_add_u32 s4, s76, 0x1380400
	s_addc_u32 s5, s77, 0
	v_writelane_b32 v254, s4, 38
	s_cmpk_lt_i32 s72, 0x200
	s_mov_b64 s[18:19], s[28:29]
	v_writelane_b32 v254, s5, 39
	s_cselect_b64 s[4:5], -1, 0
	v_writelane_b32 v254, s4, 40
	s_sub_i32 s1, 0, s78
	v_readlane_b32 s11, v252, 58
	v_writelane_b32 v254, s5, 41
	v_readfirstlane_b32 s4, v0
	s_mul_i32 s1, s1, s4
	s_mul_hi_u32 s1, s4, s1
	s_add_i32 s4, s4, s1
	s_mul_hi_u32 s1, s0, s4
	s_mul_i32 s1, s1, s78
	s_sub_i32 s0, s0, s1
	s_lshl_b32 s1, s72, 4
	s_andn2_b32 s1, s1, 63
	v_writelane_b32 v254, s1, 42
	s_lshl_b32 s1, s72, 7
	s_and_b32 s1, s1, 0x180
	s_add_i32 s4, s1, 0xffffff00
	v_writelane_b32 v254, s4, 43
	s_add_i32 s4, s1, 0x380
	v_writelane_b32 v254, s4, 44
	v_writelane_b32 v254, s1, 45
	s_bitset1_b32 s1, 9
	v_writelane_b32 v254, s1, 46
	s_sub_i32 s1, s0, s78
	s_cmp_ge_u32 s0, s78
	s_cselect_b32 s0, s1, s0
	s_sub_i32 s1, s0, s78
	s_cmp_ge_u32 s0, s78
	s_cselect_b32 s0, s1, s0
	s_lshl_b32 s0, s0, 9
	v_writelane_b32 v254, s0, 47
	s_add_i32 s0, s72, s78
	s_lshl_b32 s1, s0, 3
	v_writelane_b32 v254, s1, 48
	s_lshl_b32 s1, s0, 6
	v_writelane_b32 v254, s1, 49
	s_lshl_b32 s0, s0, 9
	v_writelane_b32 v254, s0, 50
	s_lshl_b32 s0, s78, 6
	v_writelane_b32 v254, s0, 51
	s_add_i32 s0, 0, 0x13000
	v_writelane_b32 v254, s0, 52
	s_add_i32 s0, 0, 0x26300
	v_writelane_b32 v254, s0, 53
	s_add_i32 s0, 0, 0x26000
	v_writelane_b32 v254, s0, 54
	s_add_i32 s0, 0, 0x1d000
	v_writelane_b32 v254, s0, 55
	s_add_i32 s0, 0, 0x2000
	v_writelane_b32 v254, s0, 56
	s_add_i32 s0, 0, 0x26c00
	v_writelane_b32 v254, s0, 57
	s_add_i32 s0, 0, 0x26c04
	v_writelane_b32 v254, s0, 58
	s_add_i32 s0, 0, 0x26200
	v_writelane_b32 v254, s0, 59
	s_add_i32 s0, 0, 0x25800
	v_writelane_b32 v254, s0, 60
	s_add_i32 s0, 0, 0x22000
	v_writelane_b32 v254, s0, 61
	s_add_i32 s0, 0, 0x11400
	v_writelane_b32 v254, s0, 62
	v_writelane_b32 v254, s34, 63
	s_mov_b32 s0, s74
	v_readlane_b32 s12, v252, 59
	v_writelane_b32 v255, s35, 0
	v_writelane_b32 v255, s72, 1
	v_writelane_b32 v255, s0, 2
	v_readlane_b32 s13, v252, 60
	v_readlane_b32 s16, v253, 9
	v_writelane_b32 v255, s1, 3
	v_writelane_b32 v255, s76, 4
	v_mov_b32_e32 v1, 0
	s_mov_b32 s22, 0x2aaaaaab
	v_writelane_b32 v255, s77, 5
	v_writelane_b32 v255, s78, 6
	v_writelane_b32 v255, s79, 7
	v_writelane_b32 v255, s20, 8
	s_movk_i32 s12, 0x2180
	s_movk_i32 s13, 0x300
	v_writelane_b32 v255, s21, 9
	v_writelane_b32 v255, s26, 10
	s_mov_b32 s29, 0x800000
	s_add_i32 s30, 0, 0x1f000
	v_writelane_b32 v255, s27, 11
	v_writelane_b32 v255, s8, 12
	v_writelane_b32 v255, s9, 13
	v_writelane_b32 v255, s14, 14
	s_add_i32 s97, 0, 0x19800
	s_mov_b32 s11, 0
	v_writelane_b32 v255, s15, 15
	v_writelane_b32 v255, s18, 16
	v_readlane_b32 s17, v253, 10
	v_readlane_b32 s6, v252, 53
	v_writelane_b32 v255, s19, 17
	v_readlane_b32 s7, v252, 54
	v_readlane_b32 s10, v252, 57
	s_branch .LBB0_381
.LBB0_380:
	s_or_b64 exec, exec, s[0:1]
	v_readlane_b32 s0, v255, 18
	v_readlane_b32 s1, v255, 19
	s_mov_b32 s68, 1
	s_mov_b64 s[66:67], 0
	s_and_b64 vcc, exec, s[0:1]
	s_waitcnt lgkmcnt(0)
	s_barrier
	s_cbranch_vccnz .LBB0_1238

.LBB0_662:
	s_waitcnt vmcnt(0)
	s_barrier
	s_and_saveexec_b64 s[0:1], s[34:35]
	s_cbranch_execz .LBB0_710
	s_add_u32 s98, s98, 1
	v_mov_b32_e32 v7, 0x26c00
	ds_read2_b32 v[8:9], v7 offset1:1
	v_mov_b32_e32 v2, s99
	v_mov_b32_e32 v3, 1
	global_atomic_add v4, v2, v3, s[100:101] sc0
	v_add_u32_e32 v2, 0x1000, v2
	v_mov_b32_e32 v10, 0x2480
	s_waitcnt vmcnt(0) lgkmcnt(0)
	v_add_u32_e32 v4, 1, v4
	v_mul_lo_u32 v5, v8, s98
	v_mul_lo_u32 v9, v9, s98
	v_cmp_eq_u32_e32 vcc, v4, v5
	s_and_saveexec_b64 s[4:5], vcc
	s_cbranch_execz .Lh2_skip_3
	buffer_wbl2 sc1
	s_waitcnt vmcnt(0)
	global_atomic_add v10, v3, s[100:101]
	global_atomic_add v10, v3, s[100:101] offset:256
	global_atomic_add v10, v3, s[100:101] offset:512
	global_atomic_add v10, v3, s[100:101] offset:768
	global_atomic_add v10, v3, s[100:101] offset:1024
	global_atomic_add v10, v3, s[100:101] offset:1280
	global_atomic_add v10, v3, s[100:101] offset:1536
	global_atomic_add v10, v3, s[100:101] offset:1792
	global_atomic_add v10, v3, s[100:101] offset:2048
	global_atomic_add v10, v3, s[100:101] offset:2304
	global_atomic_add v10, v3, s[100:101] offset:2560
	global_atomic_add v10, v3, s[100:101] offset:2816
	global_atomic_add v10, v3, s[100:101] offset:3072
	global_atomic_add v10, v3, s[100:101] offset:3328
	global_atomic_add v10, v3, s[100:101] offset:3584
	global_atomic_add v10, v3, s[100:101] offset:3840

.LBB0_755:
	s_or_b64 exec, exec, s[40:41]
	s_waitcnt vmcnt(0)
	s_barrier
	s_and_saveexec_b64 s[0:1], s[34:35]
	s_cbranch_execz .LBB0_803
	s_add_u32 s98, s98, 1
	v_mov_b32_e32 v7, 0x26c00
	ds_read2_b32 v[8:9], v7 offset1:1
	v_mov_b32_e32 v2, s99
	v_mov_b32_e32 v3, 1
	global_atomic_add v4, v2, v3, s[100:101] sc0
	v_add_u32_e32 v2, 0x1000, v2
	v_mov_b32_e32 v10, 0x2480
	s_waitcnt vmcnt(0) lgkmcnt(0)
	v_add_u32_e32 v4, 1, v4
	v_mul_lo_u32 v5, v8, s98
	v_mul_lo_u32 v9, v9, s98
	v_cmp_eq_u32_e32 vcc, v4, v5
	s_and_saveexec_b64 s[4:5], vcc
	s_cbranch_execz .Lh2_skip_4
	buffer_wbl2 sc1
	s_waitcnt vmcnt(0)
	global_atomic_add v10, v3, s[100:101]
	global_atomic_add v10, v3, s[100:101] offset:256
	global_atomic_add v10, v3, s[100:101] offset:512
	global_atomic_add v10, v3, s[100:101] offset:768
	global_atomic_add v10, v3, s[100:101] offset:1024
	global_atomic_add v10, v3, s[100:101] offset:1280
	global_atomic_add v10, v3, s[100:101] offset:1536
	global_atomic_add v10, v3, s[100:101] offset:1792
	global_atomic_add v10, v3, s[100:101] offset:2048
	global_atomic_add v10, v3, s[100:101] offset:2304
	global_atomic_add v10, v3, s[100:101] offset:2560
	global_atomic_add v10, v3, s[100:101] offset:2816
	global_atomic_add v10, v3, s[100:101] offset:3072
	global_atomic_add v10, v3, s[100:101] offset:3328
	global_atomic_add v10, v3, s[100:101] offset:3584
	global_atomic_add v10, v3, s[100:101] offset:3840

.LBB0_1191:
	s_waitcnt vmcnt(0)
	s_waitcnt lgkmcnt(0)
	s_barrier
	s_and_saveexec_b64 s[0:1], s[34:35]
	s_cbranch_execz .LBB0_380
	s_add_u32 s98, s98, 1
	v_mov_b32_e32 v7, 0x26c00
	ds_read2_b32 v[8:9], v7 offset1:1
	v_mov_b32_e32 v2, s99
	v_mov_b32_e32 v3, 1
	global_atomic_add v4, v2, v3, s[100:101] sc0
	v_add_u32_e32 v2, 0x1000, v2
	v_mov_b32_e32 v10, 0x2480
	s_waitcnt vmcnt(0) lgkmcnt(0)
	v_add_u32_e32 v4, 1, v4
	v_mul_lo_u32 v5, v8, s98
	v_mul_lo_u32 v9, v9, s98
	v_cmp_eq_u32_e32 vcc, v4, v5
	s_and_saveexec_b64 s[4:5], vcc
	s_cbranch_execz .Lh2_skip_5
	buffer_wbl2 sc1
	s_waitcnt vmcnt(0)
	global_atomic_add v10, v3, s[100:101]
	global_atomic_add v10, v3, s[100:101] offset:256
	global_atomic_add v10, v3, s[100:101] offset:512
	global_atomic_add v10, v3, s[100:101] offset:768
	global_atomic_add v10, v3, s[100:101] offset:1024
	global_atomic_add v10, v3, s[100:101] offset:1280
	global_atomic_add v10, v3, s[100:101] offset:1536
	global_atomic_add v10, v3, s[100:101] offset:1792
	global_atomic_add v10, v3, s[100:101] offset:2048
	global_atomic_add v10, v3, s[100:101] offset:2304
	global_atomic_add v10, v3, s[100:101] offset:2560
	global_atomic_add v10, v3, s[100:101] offset:2816
	global_atomic_add v10, v3, s[100:101] offset:3072
	global_atomic_add v10, v3, s[100:101] offset:3328
	global_atomic_add v10, v3, s[100:101] offset:3584
	global_atomic_add v10, v3, s[100:101] offset:3840

.Lh2_spin_5:
	s_sleep 1
	global_load_dword v4, v2, s[100:101] sc1
	s_waitcnt vmcnt(0)
	v_cmp_lt_u32_e32 vcc, v4, v9
	s_cbranch_vccnz .Lh2_spin_5
	buffer_inv sc1
	s_waitcnt vmcnt(0)
	s_branch .LBB0_380

.LBB0_1253:
	ds_read_b128 v[80:83], v171
	ds_read_b128 v[84:87], v171 offset:1024
	ds_read_b128 v[88:91], v171 offset:2048
	ds_read_b128 v[92:95], v171 offset:3072
	s_add_u32 s24, s18, 0xfffc0080
	s_addc_u32 s25, s19, -1
	s_cmp_eq_u32 s57, 12
	s_cselect_b32 s29, s5, s25
	s_cselect_b32 s28, s53, s24
	s_cselect_b32 s25, s3, s56
	s_cselect_b32 s24, s54, s55
	v_lshl_add_u64 v[158:159], s[18:19], 0, v[150:151]
	s_add_i32 m0, s13, 0xc000
	ds_read_b128 v[164:167], v172
	ds_read_b128 v[180:183], v172 offset:1024
	ds_read_b128 v[184:187], v172 offset:2048
	ds_read_b128 v[188:191], v172 offset:3072
	ds_read_b128 v[192:195], v172 offset:4096
	ds_read_b128 v[196:199], v172 offset:5120
	ds_read_b128 v[200:203], v172 offset:6144
	ds_read_b128 v[204:207], v172 offset:7168
	global_load_lds_dwordx4 v[158:159], off
	v_lshl_add_u64 v[158:159], s[18:19], 0, v[152:153]
	s_add_i32 m0, s13, 0xe000
	s_nop 0
	global_load_lds_dwordx4 v[158:159], off
	s_waitcnt lgkmcnt(8)
	s_barrier
	s_waitcnt lgkmcnt(0)
	s_setprio 1
	s_waitcnt lgkmcnt(0)
	v_mfma_f32_16x16x32_bf16 v[140:143], v[80:83], v[164:167], v[140:143]
	v_mfma_f32_16x16x32_bf16 v[136:139], v[88:91], v[164:167], v[136:139]
	v_mfma_f32_16x16x32_bf16 v[124:127], v[80:83], v[184:187], v[124:127]
	v_mfma_f32_16x16x32_bf16 v[120:123], v[88:91], v[184:187], v[120:123]
	v_mfma_f32_16x16x32_bf16 v[108:111], v[80:83], v[192:195], v[108:111]
	v_mfma_f32_16x16x32_bf16 v[104:107], v[88:91], v[192:195], v[104:107]
	v_mfma_f32_16x16x32_bf16 v[76:79], v[80:83], v[200:203], v[76:79]
	v_mfma_f32_16x16x32_bf16 v[72:75], v[88:91], v[200:203], v[72:75]
	v_mfma_f32_16x16x32_bf16 v[140:143], v[84:87], v[180:183], v[140:143]
	v_mfma_f32_16x16x32_bf16 v[136:139], v[92:95], v[180:183], v[136:139]
	v_mfma_f32_16x16x32_bf16 v[124:127], v[84:87], v[188:191], v[124:127]
	v_mfma_f32_16x16x32_bf16 v[120:123], v[92:95], v[188:191], v[120:123]
	v_mfma_f32_16x16x32_bf16 v[108:111], v[84:87], v[196:199], v[108:111]
	v_mfma_f32_16x16x32_bf16 v[104:107], v[92:95], v[196:199], v[104:107]
	v_mfma_f32_16x16x32_bf16 v[76:79], v[84:87], v[204:207], v[76:79]
	v_mfma_f32_16x16x32_bf16 v[72:75], v[92:95], v[204:207], v[72:75]
	s_setprio 0
	s_barrier
	s_add_i32 s58, s49, s35
	v_lshl_add_u64 v[158:159], s[24:25], 0, v[144:145]
	s_mov_b32 m0, s58
	ds_read_b128 v[208:211], v173
	ds_read_b128 v[212:215], v173 offset:1024
	ds_read_b128 v[216:219], v173 offset:2048
	ds_read_b128 v[220:223], v173 offset:3072
	global_load_lds_dwordx4 v[158:159], off
	v_lshl_add_u64 v[174:175], s[24:25], 0, v[146:147]
	s_add_i32 m0, s58, 0x2000
	s_nop 0
	global_load_lds_dwordx4 v[174:175], off
	s_barrier
	s_waitcnt lgkmcnt(0)
	s_setprio 1
	s_waitcnt lgkmcnt(0)
	v_mfma_f32_16x16x32_bf16 v[132:135], v[208:211], v[164:167], v[132:135]
	v_mfma_f32_16x16x32_bf16 v[128:131], v[216:219], v[164:167], v[128:131]
	v_mfma_f32_16x16x32_bf16 v[116:119], v[208:211], v[184:187], v[116:119]
	v_mfma_f32_16x16x32_bf16 v[112:115], v[216:219], v[184:187], v[112:115]
	v_mfma_f32_16x16x32_bf16 v[100:103], v[208:211], v[192:195], v[100:103]
	v_mfma_f32_16x16x32_bf16 v[96:99], v[216:219], v[192:195], v[96:99]
	v_mfma_f32_16x16x32_bf16 v[68:71], v[208:211], v[200:203], v[68:71]
	v_mfma_f32_16x16x32_bf16 v[64:67], v[216:219], v[200:203], v[64:67]
	v_mfma_f32_16x16x32_bf16 v[132:135], v[212:215], v[180:183], v[132:135]
	v_mfma_f32_16x16x32_bf16 v[128:131], v[220:223], v[180:183], v[128:131]
	v_mfma_f32_16x16x32_bf16 v[116:119], v[212:215], v[188:191], v[116:119]
	v_mfma_f32_16x16x32_bf16 v[112:115], v[220:223], v[188:191], v[112:115]
	v_mfma_f32_16x16x32_bf16 v[100:103], v[212:215], v[196:199], v[100:103]
	v_mfma_f32_16x16x32_bf16 v[96:99], v[220:223], v[196:199], v[96:99]
	v_mfma_f32_16x16x32_bf16 v[68:71], v[212:215], v[204:207], v[68:71]
	v_mfma_f32_16x16x32_bf16 v[64:67], v[220:223], v[204:207], v[64:67]
	s_setprio 0
	s_mov_b32 m0, s13
	v_lshl_add_u64 v[224:225], s[28:29], 0, v[144:145]
	s_barrier
	ds_read_b128 v[164:167], v172 offset:16384
	ds_read_b128 v[180:183], v172 offset:17408
	ds_read_b128 v[184:187], v172 offset:18432
	ds_read_b128 v[188:191], v172 offset:19456
	ds_read_b128 v[192:195], v172 offset:20480
	ds_read_b128 v[196:199], v172 offset:21504
	ds_read_b128 v[200:203], v172 offset:22528
	ds_read_b128 v[204:207], v172 offset:23552
	global_load_lds_dwordx4 v[224:225], off
	v_lshl_add_u64 v[226:227], s[28:29], 0, v[146:147]
	s_mov_b32 m0, s40
	s_nop 0
	global_load_lds_dwordx4 v[226:227], off
	s_barrier
	s_waitcnt lgkmcnt(0)
	s_setprio 1
	s_waitcnt lgkmcnt(0)
	v_mfma_f32_16x16x32_bf16 v[60:63], v[80:83], v[164:167], v[60:63]
	v_mfma_f32_16x16x32_bf16 v[56:59], v[88:91], v[164:167], v[56:59]
	v_mfma_f32_16x16x32_bf16 v[44:47], v[80:83], v[184:187], v[44:47]
	v_mfma_f32_16x16x32_bf16 v[40:43], v[88:91], v[184:187], v[40:43]
	v_mfma_f32_16x16x32_bf16 v[28:31], v[80:83], v[192:195], v[28:31]
	v_mfma_f32_16x16x32_bf16 v[24:27], v[88:91], v[192:195], v[24:27]
	v_mfma_f32_16x16x32_bf16 v[20:23], v[80:83], v[200:203], v[20:23]
	v_mfma_f32_16x16x32_bf16 v[16:19], v[88:91], v[200:203], v[16:19]
	v_mfma_f32_16x16x32_bf16 v[60:63], v[84:87], v[180:183], v[60:63]
	v_mfma_f32_16x16x32_bf16 v[56:59], v[92:95], v[180:183], v[56:59]
	v_mfma_f32_16x16x32_bf16 v[44:47], v[84:87], v[188:191], v[44:47]
	v_mfma_f32_16x16x32_bf16 v[40:43], v[92:95], v[188:191], v[40:43]
	v_mfma_f32_16x16x32_bf16 v[28:31], v[84:87], v[196:199], v[28:31]
	v_mfma_f32_16x16x32_bf16 v[24:27], v[92:95], v[196:199], v[24:27]
	v_mfma_f32_16x16x32_bf16 v[20:23], v[84:87], v[204:207], v[20:23]
	v_mfma_f32_16x16x32_bf16 v[16:19], v[92:95], v[204:207], v[16:19]
	s_setprio 0
	s_barrier
	s_add_u32 s58, s24, 0x40000
	s_addc_u32 s59, s25, 0
	s_add_i32 s60, s50, s35
	v_lshl_add_u64 v[80:81], s[58:59], 0, v[144:145]
	s_mov_b32 m0, s60
	s_nop 0
	global_load_lds_dwordx4 v[80:81], off
	v_lshl_add_u64 v[80:81], s[58:59], 0, v[146:147]
	s_add_i32 m0, s60, 0x2000
	s_nop 0
	global_load_lds_dwordx4 v[80:81], off
	s_waitcnt vmcnt(6)
	s_barrier
	s_setprio 1
	v_mfma_f32_16x16x32_bf16 v[52:55], v[208:211], v[164:167], v[52:55]
	v_mfma_f32_16x16x32_bf16 v[48:51], v[216:219], v[164:167], v[48:51]
	v_mfma_f32_16x16x32_bf16 v[36:39], v[208:211], v[184:187], v[36:39]
	v_mfma_f32_16x16x32_bf16 v[32:35], v[216:219], v[184:187], v[32:35]
	v_mfma_f32_16x16x32_bf16 v[12:15], v[208:211], v[192:195], v[12:15]
	v_mfma_f32_16x16x32_bf16 v[8:11], v[216:219], v[192:195], v[8:11]
	v_mfma_f32_16x16x32_bf16 v[4:7], v[208:211], v[200:203], v[4:7]
	v_mfma_f32_16x16x32_bf16 v[0:3], v[216:219], v[200:203], v[0:3]
	v_mfma_f32_16x16x32_bf16 v[52:55], v[212:215], v[180:183], v[52:55]
	v_mfma_f32_16x16x32_bf16 v[48:51], v[220:223], v[180:183], v[48:51]
	v_mfma_f32_16x16x32_bf16 v[36:39], v[212:215], v[188:191], v[36:39]
	v_mfma_f32_16x16x32_bf16 v[32:35], v[220:223], v[188:191], v[32:35]
	v_mfma_f32_16x16x32_bf16 v[12:15], v[212:215], v[196:199], v[12:15]
	v_mfma_f32_16x16x32_bf16 v[8:11], v[220:223], v[196:199], v[8:11]
	v_mfma_f32_16x16x32_bf16 v[4:7], v[212:215], v[204:207], v[4:7]
	v_mfma_f32_16x16x32_bf16 v[0:3], v[220:223], v[204:207], v[0:3]
	s_setprio 0
	s_add_i32 s58, 0, 0x18000
	v_add_u32_e32 v92, s58, v169
	s_barrier
	ds_read_b128 v[80:83], v92
	ds_read_b128 v[84:87], v92 offset:1024
	ds_read_b128 v[88:91], v92 offset:2048
	ds_read_b128 v[92:95], v92 offset:3072
	s_add_u32 s28, s28, 0x40000
	s_addc_u32 s29, s29, 0
	s_mov_b32 m0, s41
	v_lshl_add_u64 v[208:209], s[28:29], 0, v[144:145]
	ds_read_b128 v[164:167], v172 offset:32768
	ds_read_b128 v[180:183], v172 offset:33792
	ds_read_b128 v[184:187], v172 offset:34816
	ds_read_b128 v[188:191], v172 offset:35840
	ds_read_b128 v[192:195], v172 offset:36864
	ds_read_b128 v[196:199], v172 offset:37888
	ds_read_b128 v[200:203], v172 offset:38912
	ds_read_b128 v[204:207], v172 offset:39936
	global_load_lds_dwordx4 v[208:209], off
	v_lshl_add_u64 v[208:209], s[28:29], 0, v[146:147]
	s_mov_b32 m0, s42
	s_nop 0
	global_load_lds_dwordx4 v[208:209], off
	s_waitcnt lgkmcnt(8)
	s_barrier
	s_waitcnt lgkmcnt(0)
	s_setprio 1
	s_waitcnt lgkmcnt(0)
	v_mfma_f32_16x16x32_bf16 v[140:143], v[80:83], v[164:167], v[140:143]
	v_mfma_f32_16x16x32_bf16 v[136:139], v[88:91], v[164:167], v[136:139]
	v_mfma_f32_16x16x32_bf16 v[124:127], v[80:83], v[184:187], v[124:127]
	v_mfma_f32_16x16x32_bf16 v[120:123], v[88:91], v[184:187], v[120:123]
	v_mfma_f32_16x16x32_bf16 v[108:111], v[80:83], v[192:195], v[108:111]
	v_mfma_f32_16x16x32_bf16 v[104:107], v[88:91], v[192:195], v[104:107]
	v_mfma_f32_16x16x32_bf16 v[76:79], v[80:83], v[200:203], v[76:79]
	v_mfma_f32_16x16x32_bf16 v[72:75], v[88:91], v[200:203], v[72:75]
	v_mfma_f32_16x16x32_bf16 v[140:143], v[84:87], v[180:183], v[140:143]
	v_mfma_f32_16x16x32_bf16 v[136:139], v[92:95], v[180:183], v[136:139]
	v_mfma_f32_16x16x32_bf16 v[124:127], v[84:87], v[188:191], v[124:127]
	v_mfma_f32_16x16x32_bf16 v[120:123], v[92:95], v[188:191], v[120:123]
	v_mfma_f32_16x16x32_bf16 v[108:111], v[84:87], v[196:199], v[108:111]
	v_mfma_f32_16x16x32_bf16 v[104:107], v[92:95], v[196:199], v[104:107]
	v_mfma_f32_16x16x32_bf16 v[76:79], v[84:87], v[204:207], v[76:79]
	v_mfma_f32_16x16x32_bf16 v[72:75], v[92:95], v[204:207], v[72:75]
	s_setprio 0
	s_barrier
	s_add_i32 s28, 0, 0x1c000
	s_add_i32 s29, s58, s35
	v_add_u32_e32 v148, s28, v169
	v_lshl_add_u64 v[158:159], v[158:159], 0, s[0:1]
	s_mov_b32 m0, s29
	ds_read_b128 v[208:211], v148
	ds_read_b128 v[212:215], v148 offset:1024
	ds_read_b128 v[216:219], v148 offset:2048
	ds_read_b128 v[220:223], v148 offset:3072
	global_load_lds_dwordx4 v[158:159], off
	v_lshl_add_u64 v[158:159], v[174:175], 0, s[0:1]
	s_add_i32 m0, s29, 0x2000
	s_nop 0
	global_load_lds_dwordx4 v[158:159], off
	s_barrier
	s_waitcnt lgkmcnt(0)
	s_setprio 1
	s_waitcnt lgkmcnt(0)
	v_mfma_f32_16x16x32_bf16 v[132:135], v[208:211], v[164:167], v[132:135]
	v_mfma_f32_16x16x32_bf16 v[128:131], v[216:219], v[164:167], v[128:131]
	v_mfma_f32_16x16x32_bf16 v[116:119], v[208:211], v[184:187], v[116:119]
	v_mfma_f32_16x16x32_bf16 v[112:115], v[216:219], v[184:187], v[112:115]
	v_mfma_f32_16x16x32_bf16 v[100:103], v[208:211], v[192:195], v[100:103]
	v_mfma_f32_16x16x32_bf16 v[96:99], v[216:219], v[192:195], v[96:99]
	v_mfma_f32_16x16x32_bf16 v[68:71], v[208:211], v[200:203], v[68:71]
	v_mfma_f32_16x16x32_bf16 v[64:67], v[216:219], v[200:203], v[64:67]
	v_mfma_f32_16x16x32_bf16 v[132:135], v[212:215], v[180:183], v[132:135]
	v_mfma_f32_16x16x32_bf16 v[128:131], v[220:223], v[180:183], v[128:131]
	v_mfma_f32_16x16x32_bf16 v[116:119], v[212:215], v[188:191], v[116:119]
	v_mfma_f32_16x16x32_bf16 v[112:115], v[220:223], v[188:191], v[112:115]
	v_mfma_f32_16x16x32_bf16 v[100:103], v[212:215], v[196:199], v[100:103]
	v_mfma_f32_16x16x32_bf16 v[96:99], v[220:223], v[196:199], v[96:99]
	v_mfma_f32_16x16x32_bf16 v[68:71], v[212:215], v[204:207], v[68:71]
	v_mfma_f32_16x16x32_bf16 v[64:67], v[220:223], v[204:207], v[64:67]
	s_setprio 0
	s_mov_b32 m0, s46
	v_lshl_add_u64 v[158:159], v[224:225], 0, s[0:1]
	s_barrier
	ds_read_b128 v[164:167], v172 offset:49152
	ds_read_b128 v[180:183], v172 offset:50176
	ds_read_b128 v[184:187], v172 offset:51200
	ds_read_b128 v[188:191], v172 offset:52224
	ds_read_b128 v[192:195], v172 offset:53248
	ds_read_b128 v[196:199], v172 offset:54272
	ds_read_b128 v[200:203], v172 offset:55296
	ds_read_b128 v[204:207], v172 offset:56320
	global_load_lds_dwordx4 v[158:159], off
	v_lshl_add_u64 v[158:159], v[226:227], 0, s[0:1]
	s_mov_b32 m0, s47
	s_nop 0
	global_load_lds_dwordx4 v[158:159], off
	s_barrier
	s_waitcnt lgkmcnt(0)
	s_setprio 1
	s_waitcnt lgkmcnt(0)
	v_mfma_f32_16x16x32_bf16 v[60:63], v[80:83], v[164:167], v[60:63]
	v_mfma_f32_16x16x32_bf16 v[56:59], v[88:91], v[164:167], v[56:59]
	v_mfma_f32_16x16x32_bf16 v[44:47], v[80:83], v[184:187], v[44:47]
	v_mfma_f32_16x16x32_bf16 v[40:43], v[88:91], v[184:187], v[40:43]
	v_mfma_f32_16x16x32_bf16 v[28:31], v[80:83], v[192:195], v[28:31]
	v_mfma_f32_16x16x32_bf16 v[24:27], v[88:91], v[192:195], v[24:27]
	v_mfma_f32_16x16x32_bf16 v[20:23], v[80:83], v[200:203], v[20:23]
	v_mfma_f32_16x16x32_bf16 v[16:19], v[88:91], v[200:203], v[16:19]
	v_mfma_f32_16x16x32_bf16 v[60:63], v[84:87], v[180:183], v[60:63]
	v_mfma_f32_16x16x32_bf16 v[56:59], v[92:95], v[180:183], v[56:59]
	v_mfma_f32_16x16x32_bf16 v[44:47], v[84:87], v[188:191], v[44:47]
	v_mfma_f32_16x16x32_bf16 v[40:43], v[92:95], v[188:191], v[40:43]
	v_mfma_f32_16x16x32_bf16 v[28:31], v[84:87], v[196:199], v[28:31]
	v_mfma_f32_16x16x32_bf16 v[24:27], v[92:95], v[196:199], v[24:27]
	v_mfma_f32_16x16x32_bf16 v[20:23], v[84:87], v[204:207], v[20:23]
	v_mfma_f32_16x16x32_bf16 v[16:19], v[92:95], v[204:207], v[16:19]
	s_setprio 0
	s_barrier
	s_add_u32 s24, s24, 0x40080
	s_addc_u32 s25, s25, 0
	s_add_i32 s28, s28, s35
	v_lshl_add_u64 v[80:81], s[24:25], 0, v[144:145]
	s_mov_b32 m0, s28
	s_nop 0
	global_load_lds_dwordx4 v[80:81], off
	v_lshl_add_u64 v[80:81], s[24:25], 0, v[146:147]
	s_add_i32 m0, s28, 0x2000
	s_nop 0
	global_load_lds_dwordx4 v[80:81], off
	s_waitcnt vmcnt(6)
	s_barrier
	s_setprio 1
	v_mfma_f32_16x16x32_bf16 v[52:55], v[208:211], v[164:167], v[52:55]
	v_mfma_f32_16x16x32_bf16 v[48:51], v[216:219], v[164:167], v[48:51]
	v_mfma_f32_16x16x32_bf16 v[36:39], v[208:211], v[184:187], v[36:39]
	v_mfma_f32_16x16x32_bf16 v[32:35], v[216:219], v[184:187], v[32:35]
	v_mfma_f32_16x16x32_bf16 v[12:15], v[208:211], v[192:195], v[12:15]
	v_mfma_f32_16x16x32_bf16 v[8:11], v[216:219], v[192:195], v[8:11]
	v_mfma_f32_16x16x32_bf16 v[4:7], v[208:211], v[200:203], v[4:7]
	v_mfma_f32_16x16x32_bf16 v[0:3], v[216:219], v[200:203], v[0:3]
	v_mfma_f32_16x16x32_bf16 v[52:55], v[212:215], v[180:183], v[52:55]
	v_mfma_f32_16x16x32_bf16 v[48:51], v[220:223], v[180:183], v[48:51]
	v_mfma_f32_16x16x32_bf16 v[36:39], v[212:215], v[188:191], v[36:39]
	v_mfma_f32_16x16x32_bf16 v[32:35], v[220:223], v[188:191], v[32:35]
	v_mfma_f32_16x16x32_bf16 v[12:15], v[212:215], v[196:199], v[12:15]
	v_mfma_f32_16x16x32_bf16 v[8:11], v[220:223], v[196:199], v[8:11]
	v_mfma_f32_16x16x32_bf16 v[4:7], v[212:215], v[204:207], v[4:7]
	v_mfma_f32_16x16x32_bf16 v[0:3], v[220:223], v[204:207], v[0:3]
	s_setprio 0
	s_add_i32 s57, s57, 2
	s_add_u32 s18, s18, 0x100
	s_addc_u32 s19, s19, 0
	s_add_u32 s55, s55, 0x100
	s_addc_u32 s56, s56, 0
	s_cmp_gt_u32 s57, 13
	s_barrier
	s_cbranch_scc0 .LBB0_1253
	s_lshl_b32 s3, s12, 8
	s_add_i32 s5, s3, 0xffffe000
	s_lshr_b32 s5, s5, 12
	s_add_i32 s5, s5, 1
	s_cmp_gt_i32 s12, 31
	s_cselect_b32 s5, s5, 0
	v_lshl_or_b32 v80, s52, 8, v170
	s_mul_hi_u32 s12, s5, 0x6000
	s_mulk_i32 s5, 0x6000
	s_add_u32 s18, s44, s5
	v_ashrrev_i32_e32 v81, 31, v80
	v_readlane_b32 s52, v252, 2
	s_addc_u32 s19, s45, s12
	v_lshlrev_b64 v[158:159], 2, v[80:81]
	v_add_u32_e32 v164, s3, v168
	v_readlane_b32 s53, v252, 3
	v_lshl_add_u64 v[80:81], s[18:19], 0, v[158:159]
	v_ashrrev_i32_e32 v165, 31, v164
	v_readlane_b32 s54, v252, 4
	v_readlane_b32 s55, v252, 5
	s_mov_b64 s[16:17], s[52:53]
	v_add_u32_e32 v148, 0xffffe000, v164
	v_lshlrev_b64 v[166:167], 12, v[164:165]
	s_mov_b64 s[18:19], s[54:55]
	v_lshlrev_b64 v[180:181], 12, v[148:149]
	v_lshl_add_u64 v[174:175], s[16:17], 0, v[166:167]
	v_cmp_lt_i32_e32 vcc, s51, v164
	v_lshl_add_u64 v[180:181], s[18:19], 0, v[180:181]
	global_load_dwordx4 v[92:95], v[80:81], off
	global_load_dwordx4 v[88:91], v[80:81], off offset:64
	global_load_dwordx4 v[84:87], v[80:81], off offset:512
	s_nop 0
	global_load_dwordx4 v[80:83], v[80:81], off offset:576
	v_cndmask_b32_e32 v175, v175, v181, vcc
	v_cndmask_b32_e32 v174, v174, v180, vcc
	v_lshl_add_u64 v[174:175], v[174:175], 0, v[158:159]
	global_load_dwordx4 v[180:183], v[174:175], off
	global_load_dwordx4 v[184:187], v[174:175], off offset:64
	global_load_dwordx4 v[188:191], v[174:175], off offset:512
	global_load_dwordx4 v[192:195], v[174:175], off offset:576
	v_or_b32_e32 v174, 16, v164
	v_ashrrev_i32_e32 v175, 31, v174
	v_add_u32_e32 v148, 0xffffe010, v164
	v_lshlrev_b64 v[212:213], 12, v[174:175]
	v_cmp_lt_i32_e32 vcc, s51, v174
	v_lshlrev_b64 v[174:175], 12, v[148:149]
	v_lshl_add_u64 v[196:197], s[16:17], 0, v[212:213]
	v_lshl_add_u64 v[174:175], s[18:19], 0, v[174:175]
	v_cndmask_b32_e32 v175, v197, v175, vcc
	v_cndmask_b32_e32 v174, v196, v174, vcc
	v_lshl_add_u64 v[174:175], v[174:175], 0, v[158:159]
	global_load_dwordx4 v[196:199], v[174:175], off
	global_load_dwordx4 v[200:203], v[174:175], off offset:64
	global_load_dwordx4 v[204:207], v[174:175], off offset:512
	global_load_dwordx4 v[208:211], v[174:175], off offset:576
	v_readlane_b32 s56, v252, 6
	v_readlane_b32 s57, v252, 7
	v_readlane_b32 s58, v252, 8
	v_readlane_b32 s59, v252, 9
	v_readlane_b32 s60, v252, 10
	v_readlane_b32 s61, v252, 11
	v_readlane_b32 s62, v252, 12
	v_readlane_b32 s63, v252, 13
	v_readlane_b32 s64, v252, 14
	v_readlane_b32 s65, v252, 15
	v_readlane_b32 s66, v252, 16
	v_readlane_b32 s67, v252, 17
	v_readlane_b32 s52, v252, 51
	v_readlane_b32 s66, v253, 1
	v_readlane_b32 s67, v253, 2
	v_add_u32_e32 v148, 0xffffe020, v164
	s_mov_b32 s52, s2
	v_lshl_add_u64 v[166:167], s[66:67], 0, v[166:167]
	v_lshl_add_u64 v[166:167], v[166:167], 0, v[158:159]
	v_lshl_add_u64 v[174:175], s[66:67], 0, v[212:213]
	v_lshl_add_u64 v[174:175], v[174:175], 0, v[158:159]
	s_mov_b32 s12, s4
	s_mov_b64 s[24:25], s[10:11]
	v_readlane_b32 s53, v252, 52
	v_readlane_b32 s54, v252, 53
	v_readlane_b32 s55, v252, 54
	v_readlane_b32 s56, v252, 55
	v_readlane_b32 s57, v252, 56
	v_readlane_b32 s58, v252, 57
	v_readlane_b32 s59, v252, 58
	v_readlane_b32 s60, v252, 59
	v_readlane_b32 s61, v252, 60
	v_readlane_b32 s62, v252, 61
	v_readlane_b32 s63, v252, 62
	v_readlane_b32 s64, v252, 63
	v_readlane_b32 s65, v253, 0
	s_waitcnt vmcnt(0)
	v_pk_fma_f32 v[142:143], v[142:143], v[94:95], v[182:183]
	v_pk_fma_f32 v[140:141], v[140:141], v[92:93], v[180:181]
	v_pk_fma_f32 v[138:139], v[138:139], v[90:91], v[186:187]
	v_pk_fma_f32 v[130:131], v[130:131], v[82:83], v[194:195]
	v_pk_fma_f32 v[128:129], v[128:129], v[80:81], v[192:193]
	global_store_dwordx4 v[166:167], v[128:131], off offset:576 sc1
	v_pk_fma_f32 v[136:137], v[136:137], v[88:89], v[184:185]
	v_pk_fma_f32 v[134:135], v[134:135], v[86:87], v[190:191]
	v_or_b32_e32 v128, 32, v164
	v_pk_fma_f32 v[132:133], v[132:133], v[84:85], v[188:189]
	v_ashrrev_i32_e32 v129, 31, v128
	global_store_dwordx4 v[166:167], v[140:143], off sc1
	global_store_dwordx4 v[166:167], v[136:139], off offset:64 sc1
	global_store_dwordx4 v[166:167], v[132:135], off offset:512 sc1
	v_lshlrev_b64 v[166:167], 12, v[128:129]
	v_cmp_lt_i32_e32 vcc, s51, v128
	v_lshlrev_b64 v[128:129], 12, v[148:149]
	v_lshl_add_u64 v[130:131], s[16:17], 0, v[166:167]
	v_lshl_add_u64 v[128:129], s[18:19], 0, v[128:129]
	v_cndmask_b32_e32 v129, v131, v129, vcc
	v_cndmask_b32_e32 v128, v130, v128, vcc
	v_lshl_add_u64 v[128:129], v[128:129], 0, v[158:159]
	v_pk_fma_f32 v[114:115], v[114:115], v[82:83], v[210:211]
	v_pk_fma_f32 v[112:113], v[112:113], v[80:81], v[208:209]
	global_load_dwordx4 v[140:143], v[128:129], off
	global_load_dwordx4 v[136:139], v[128:129], off offset:64
	global_load_dwordx4 v[132:135], v[128:129], off offset:512
	s_nop 0
	global_load_dwordx4 v[128:131], v[128:129], off offset:576
	v_pk_fma_f32 v[126:127], v[126:127], v[94:95], v[198:199]
	global_store_dwordx4 v[174:175], v[112:115], off offset:576 sc1
	v_pk_fma_f32 v[124:125], v[124:125], v[92:93], v[196:197]
	v_add_u32_e32 v148, 0xffffe030, v164
	v_or_b32_e32 v112, 48, v164
	v_ashrrev_i32_e32 v113, 31, v112
	global_store_dwordx4 v[174:175], v[124:127], off sc1
	v_cmp_lt_i32_e32 vcc, s51, v112
	v_pk_fma_f32 v[122:123], v[122:123], v[90:91], v[202:203]
	v_lshlrev_b64 v[126:127], 12, v[112:113]
	v_lshlrev_b64 v[112:113], 12, v[148:149]
	v_lshl_add_u64 v[114:115], s[16:17], 0, v[126:127]
	v_lshl_add_u64 v[112:113], s[18:19], 0, v[112:113]
	v_pk_fma_f32 v[120:121], v[120:121], v[88:89], v[200:201]
	v_pk_fma_f32 v[118:119], v[118:119], v[86:87], v[206:207]
	v_pk_fma_f32 v[116:117], v[116:117], v[84:85], v[204:205]
	v_cndmask_b32_e32 v113, v115, v113, vcc
	v_cndmask_b32_e32 v112, v114, v112, vcc
	global_store_dwordx4 v[174:175], v[120:123], off offset:64 sc1
	global_store_dwordx4 v[174:175], v[116:119], off offset:512 sc1
	v_lshl_add_u64 v[112:113], v[112:113], 0, v[158:159]
	global_load_dwordx4 v[114:117], v[112:113], off
	global_load_dwordx4 v[118:121], v[112:113], off offset:64
	global_load_dwordx4 v[122:125], v[112:113], off offset:512
	global_load_dwordx4 v[180:183], v[112:113], off offset:576
	v_lshl_add_u64 v[112:113], s[66:67], 0, v[166:167]
	v_lshl_add_u64 v[112:113], v[112:113], 0, v[158:159]
	v_add_u32_e32 v148, 0xffffe080, v164
	v_lshl_add_u64 v[126:127], s[66:67], 0, v[126:127]
	v_lshl_add_u64 v[126:127], v[126:127], 0, v[158:159]
	s_waitcnt vmcnt(0)
	v_pk_fma_f32 v[110:111], v[110:111], v[94:95], v[142:143]
	v_pk_fma_f32 v[108:109], v[108:109], v[92:93], v[140:141]
	v_pk_fma_f32 v[106:107], v[106:107], v[90:91], v[138:139]
	v_pk_fma_f32 v[98:99], v[98:99], v[82:83], v[130:131]
	v_pk_fma_f32 v[96:97], v[96:97], v[80:81], v[128:129]
	global_store_dwordx4 v[112:113], v[96:99], off offset:576 sc1
	v_pk_fma_f32 v[104:105], v[104:105], v[88:89], v[136:137]
	v_pk_fma_f32 v[102:103], v[102:103], v[86:87], v[134:135]
	v_add_u32_e32 v96, 0x80, v164
	v_pk_fma_f32 v[100:101], v[100:101], v[84:85], v[132:133]
	v_ashrrev_i32_e32 v97, 31, v96
	global_store_dwordx4 v[112:113], v[108:111], off sc1
	global_store_dwordx4 v[112:113], v[104:107], off offset:64 sc1
	global_store_dwordx4 v[112:113], v[100:103], off offset:512 sc1
	v_lshlrev_b64 v[112:113], 12, v[96:97]
	v_cmp_lt_i32_e32 vcc, s51, v96
	v_lshlrev_b64 v[96:97], 12, v[148:149]
	v_lshl_add_u64 v[98:99], s[16:17], 0, v[112:113]
	v_lshl_add_u64 v[96:97], s[18:19], 0, v[96:97]
	v_cndmask_b32_e32 v97, v99, v97, vcc
	v_cndmask_b32_e32 v96, v98, v96, vcc
	v_lshl_add_u64 v[96:97], v[96:97], 0, v[158:159]
	global_load_dwordx4 v[108:111], v[96:97], off
	global_load_dwordx4 v[104:107], v[96:97], off offset:64
	global_load_dwordx4 v[100:103], v[96:97], off offset:512
	s_nop 0
	global_load_dwordx4 v[96:99], v[96:97], off offset:576
	v_pk_fma_f32 v[78:79], v[78:79], v[94:95], v[116:117]
	v_pk_fma_f32 v[76:77], v[76:77], v[92:93], v[114:115]
	v_pk_fma_f32 v[66:67], v[66:67], v[82:83], v[182:183]
	v_pk_fma_f32 v[64:65], v[64:65], v[80:81], v[180:181]
	global_store_dwordx4 v[126:127], v[64:67], off offset:576 sc1
	v_add_u32_e32 v148, 0xffffe090, v164
	global_store_dwordx4 v[126:127], v[76:79], off sc1
	v_add_u32_e32 v64, 0x90, v164
	v_ashrrev_i32_e32 v65, 31, v64
	v_lshlrev_b64 v[78:79], 12, v[64:65]
	v_cmp_lt_i32_e32 vcc, s51, v64
	v_lshlrev_b64 v[64:65], 12, v[148:149]
	v_lshl_add_u64 v[66:67], s[16:17], 0, v[78:79]
	v_lshl_add_u64 v[64:65], s[18:19], 0, v[64:65]
	v_pk_fma_f32 v[74:75], v[74:75], v[90:91], v[120:121]
	v_pk_fma_f32 v[72:73], v[72:73], v[88:89], v[118:119]
	v_pk_fma_f32 v[70:71], v[70:71], v[86:87], v[124:125]
	v_pk_fma_f32 v[68:69], v[68:69], v[84:85], v[122:123]
	v_cndmask_b32_e32 v65, v67, v65, vcc
	v_cndmask_b32_e32 v64, v66, v64, vcc
	global_store_dwordx4 v[126:127], v[72:75], off offset:64 sc1
	global_store_dwordx4 v[126:127], v[68:71], off offset:512 sc1
	v_lshl_add_u64 v[64:65], v[64:65], 0, v[158:159]
	global_load_dwordx4 v[66:69], v[64:65], off
	global_load_dwordx4 v[70:73], v[64:65], off offset:64
	global_load_dwordx4 v[74:77], v[64:65], off offset:512
	global_load_dwordx4 v[114:117], v[64:65], off offset:576
	v_lshl_add_u64 v[64:65], s[66:67], 0, v[112:113]
	v_lshl_add_u64 v[64:65], v[64:65], 0, v[158:159]
	v_add_u32_e32 v148, 0xffffe0a0, v164
	v_lshl_add_u64 v[78:79], s[66:67], 0, v[78:79]
	v_lshl_add_u64 v[78:79], v[78:79], 0, v[158:159]
	s_waitcnt vmcnt(0)
	v_pk_fma_f32 v[62:63], v[62:63], v[94:95], v[110:111]
	v_pk_fma_f32 v[60:61], v[60:61], v[92:93], v[108:109]
	v_pk_fma_f32 v[58:59], v[58:59], v[90:91], v[106:107]
	v_pk_fma_f32 v[50:51], v[50:51], v[82:83], v[98:99]
	v_pk_fma_f32 v[48:49], v[48:49], v[80:81], v[96:97]
	global_store_dwordx4 v[64:65], v[48:51], off offset:576 sc1
	v_pk_fma_f32 v[56:57], v[56:57], v[88:89], v[104:105]
	v_pk_fma_f32 v[54:55], v[54:55], v[86:87], v[102:103]
	v_add_u32_e32 v48, 0xa0, v164
	v_pk_fma_f32 v[52:53], v[52:53], v[84:85], v[100:101]
	v_ashrrev_i32_e32 v49, 31, v48
	global_store_dwordx4 v[64:65], v[60:63], off sc1
	global_store_dwordx4 v[64:65], v[56:59], off offset:64 sc1
	global_store_dwordx4 v[64:65], v[52:55], off offset:512 sc1
	v_lshlrev_b64 v[64:65], 12, v[48:49]
	v_cmp_lt_i32_e32 vcc, s51, v48
	v_lshlrev_b64 v[48:49], 12, v[148:149]
	v_lshl_add_u64 v[50:51], s[16:17], 0, v[64:65]
	v_lshl_add_u64 v[48:49], s[18:19], 0, v[48:49]
	v_cndmask_b32_e32 v49, v51, v49, vcc
	v_cndmask_b32_e32 v48, v50, v48, vcc
	v_lshl_add_u64 v[48:49], v[48:49], 0, v[158:159]
	global_load_dwordx4 v[60:63], v[48:49], off
	global_load_dwordx4 v[56:59], v[48:49], off offset:64
	global_load_dwordx4 v[52:55], v[48:49], off offset:512
	s_nop 0
	global_load_dwordx4 v[48:51], v[48:49], off offset:576
	v_add_u32_e32 v148, 0xffffe0b0, v164
	v_pk_fma_f32 v[44:45], v[44:45], v[92:93], v[66:67]
	v_pk_fma_f32 v[46:47], v[46:47], v[94:95], v[68:69]
	v_pk_fma_f32 v[42:43], v[42:43], v[90:91], v[72:73]
	v_pk_fma_f32 v[34:35], v[34:35], v[82:83], v[116:117]
	v_pk_fma_f32 v[32:33], v[32:33], v[80:81], v[114:115]
	global_store_dwordx4 v[78:79], v[32:35], off offset:576 sc1
	v_pk_fma_f32 v[40:41], v[40:41], v[88:89], v[70:71]
	v_pk_fma_f32 v[38:39], v[38:39], v[86:87], v[76:77]
	v_add_u32_e32 v32, 0xb0, v164
	v_ashrrev_i32_e32 v33, 31, v32
	v_lshlrev_b64 v[66:67], 12, v[32:33]
	v_cmp_lt_i32_e32 vcc, s51, v32
	v_lshlrev_b64 v[32:33], 12, v[148:149]
	v_lshl_add_u64 v[34:35], s[16:17], 0, v[66:67]
	v_lshl_add_u64 v[32:33], s[18:19], 0, v[32:33]
	v_pk_fma_f32 v[36:37], v[36:37], v[84:85], v[74:75]
	v_cndmask_b32_e32 v33, v35, v33, vcc
	v_cndmask_b32_e32 v32, v34, v32, vcc
	global_store_dwordx4 v[78:79], v[44:47], off sc1
	global_store_dwordx4 v[78:79], v[40:43], off offset:64 sc1
	global_store_dwordx4 v[78:79], v[36:39], off offset:512 sc1
	v_lshl_add_u64 v[44:45], v[32:33], 0, v[158:159]
	global_load_dwordx4 v[32:35], v[44:45], off
	global_load_dwordx4 v[36:39], v[44:45], off offset:64
	global_load_dwordx4 v[40:43], v[44:45], off offset:512
	s_nop 0
	global_load_dwordx4 v[44:47], v[44:45], off offset:576
	v_lshl_add_u64 v[64:65], s[66:67], 0, v[64:65]
	v_lshl_add_u64 v[64:65], v[64:65], 0, v[158:159]
	v_readlane_b32 s16, v253, 9
	s_and_b64 vcc, exec, s[38:39]
	s_mov_b64 s[18:19], s[6:7]
	v_readlane_b32 s17, v253, 10
	s_waitcnt vmcnt(0)
	v_pk_fma_f32 v[30:31], v[30:31], v[94:95], v[62:63]
	v_pk_fma_f32 v[28:29], v[28:29], v[92:93], v[60:61]
	v_pk_fma_f32 v[14:15], v[14:15], v[86:87], v[54:55]
	v_pk_fma_f32 v[10:11], v[10:11], v[82:83], v[50:51]
	v_pk_fma_f32 v[8:9], v[8:9], v[80:81], v[48:49]
	v_pk_fma_f32 v[12:13], v[12:13], v[84:85], v[52:53]
	global_store_dwordx4 v[64:65], v[8:11], off offset:576 sc1
	global_store_dwordx4 v[64:65], v[12:15], off offset:512 sc1
	v_pk_fma_f32 v[26:27], v[26:27], v[90:91], v[58:59]
	v_lshl_add_u64 v[8:9], s[66:67], 0, v[66:67]
	v_lshl_add_u64 v[12:13], v[8:9], 0, v[158:159]
	v_pk_fma_f32 v[24:25], v[24:25], v[88:89], v[56:57]
	global_store_dwordx4 v[64:65], v[28:31], off sc1
	global_store_dwordx4 v[64:65], v[24:27], off offset:64 sc1
	v_pk_fma_f32 v[10:11], v[22:23], v[94:95], v[34:35]
	v_pk_fma_f32 v[8:9], v[20:21], v[92:93], v[32:33]
	global_store_dwordx4 v[12:13], v[8:11], off sc1
	v_pk_fma_f32 v[6:7], v[6:7], v[86:87], v[42:43]
	v_pk_fma_f32 v[4:5], v[4:5], v[84:85], v[40:41]
	v_pk_fma_f32 v[10:11], v[18:19], v[90:91], v[38:39]
	v_pk_fma_f32 v[8:9], v[16:17], v[88:89], v[36:37]
	v_pk_fma_f32 v[2:3], v[2:3], v[82:83], v[46:47]
	v_pk_fma_f32 v[0:1], v[0:1], v[80:81], v[44:45]
	global_store_dwordx4 v[12:13], v[8:11], off offset:64 sc1
	global_store_dwordx4 v[12:13], v[4:7], off offset:512 sc1
	global_store_dwordx4 v[12:13], v[0:3], off offset:576 sc1
	s_cbranch_vccz .LBB0_1246
	s_waitcnt vmcnt(0)
	s_cmpk_gt_u32 s30, 0xff
	s_cbranch_scc1 .LBB0_1257
	s_barrier

.LBB0_1323:
	s_or_b64 exec, exec, s[0:1]
	s_waitcnt vmcnt(0)
	s_barrier
	s_and_saveexec_b64 s[0:1], s[34:35]
	s_cbranch_execz .LBB0_1371
	s_add_u32 s98, s98, 1
	v_mov_b32_e32 v7, 0x26c00
	ds_read2_b32 v[8:9], v7 offset1:1
	v_mov_b32_e32 v2, s99
	v_mov_b32_e32 v3, 1
	global_atomic_add v4, v2, v3, s[100:101] sc0
	v_add_u32_e32 v2, 0x1000, v2
	v_mov_b32_e32 v10, 0x2480
	s_waitcnt vmcnt(0) lgkmcnt(0)
	v_add_u32_e32 v4, 1, v4
	v_mul_lo_u32 v5, v8, s98
	v_mul_lo_u32 v9, v9, s98
	v_cmp_eq_u32_e32 vcc, v4, v5
	s_and_saveexec_b64 s[4:5], vcc
	s_cbranch_execz .Lh2_skip_7
	buffer_wbl2 sc1
	s_waitcnt vmcnt(0)
	global_atomic_add v10, v3, s[100:101]
	global_atomic_add v10, v3, s[100:101] offset:256
	global_atomic_add v10, v3, s[100:101] offset:512
	global_atomic_add v10, v3, s[100:101] offset:768
	global_atomic_add v10, v3, s[100:101] offset:1024
	global_atomic_add v10, v3, s[100:101] offset:1280
	global_atomic_add v10, v3, s[100:101] offset:1536
	global_atomic_add v10, v3, s[100:101] offset:1792
	global_atomic_add v10, v3, s[100:101] offset:2048
	global_atomic_add v10, v3, s[100:101] offset:2304
	global_atomic_add v10, v3, s[100:101] offset:2560
	global_atomic_add v10, v3, s[100:101] offset:2816
	global_atomic_add v10, v3, s[100:101] offset:3072
	global_atomic_add v10, v3, s[100:101] offset:3328
	global_atomic_add v10, v3, s[100:101] offset:3584
	global_atomic_add v10, v3, s[100:101] offset:3840

.LBB0_1378:
	ds_read_b128 v[152:155], v149
	ds_read_b128 v[156:159], v149 offset:1024
	ds_read_b128 v[164:167], v149 offset:2048
	ds_read_b128 v[168:171], v149 offset:3072
	s_add_u32 s24, s18, 0xfffc0080
	s_addc_u32 s25, s19, -1
	s_cmp_eq_u32 s56, 12
	s_cselect_b32 s29, s7, s25
	s_cselect_b32 s28, s52, s24
	s_cselect_b32 s25, s5, s55
	s_cselect_b32 s24, s53, s54
	v_lshl_add_u64 v[144:145], s[18:19], 0, v[136:137]
	s_add_i32 m0, s9, 0xc000
	ds_read_b128 v[172:175], v150
	ds_read_b128 v[180:183], v150 offset:1024
	ds_read_b128 v[184:187], v150 offset:2048
	ds_read_b128 v[188:191], v150 offset:3072
	ds_read_b128 v[192:195], v150 offset:4096
	ds_read_b128 v[196:199], v150 offset:5120
	ds_read_b128 v[200:203], v150 offset:6144
	ds_read_b128 v[204:207], v150 offset:7168
	global_load_lds_dwordx4 v[144:145], off
	v_lshl_add_u64 v[144:145], s[18:19], 0, v[138:139]
	s_add_i32 m0, s9, 0xe000
	s_nop 0
	global_load_lds_dwordx4 v[144:145], off
	s_waitcnt lgkmcnt(8)
	s_barrier
	s_waitcnt lgkmcnt(0)
	s_setprio 1
	s_waitcnt lgkmcnt(0)
	v_mfma_f32_16x16x32_bf16 v[124:127], v[152:155], v[172:175], v[124:127]
	v_mfma_f32_16x16x32_bf16 v[120:123], v[164:167], v[172:175], v[120:123]
	v_mfma_f32_16x16x32_bf16 v[116:119], v[152:155], v[184:187], v[116:119]
	v_mfma_f32_16x16x32_bf16 v[108:111], v[164:167], v[184:187], v[108:111]
	v_mfma_f32_16x16x32_bf16 v[100:103], v[152:155], v[192:195], v[100:103]
	v_mfma_f32_16x16x32_bf16 v[92:95], v[164:167], v[192:195], v[92:95]
	v_mfma_f32_16x16x32_bf16 v[84:87], v[152:155], v[200:203], v[84:87]
	v_mfma_f32_16x16x32_bf16 v[76:79], v[164:167], v[200:203], v[76:79]
	v_mfma_f32_16x16x32_bf16 v[124:127], v[156:159], v[180:183], v[124:127]
	v_mfma_f32_16x16x32_bf16 v[120:123], v[168:171], v[180:183], v[120:123]
	v_mfma_f32_16x16x32_bf16 v[116:119], v[156:159], v[188:191], v[116:119]
	v_mfma_f32_16x16x32_bf16 v[108:111], v[168:171], v[188:191], v[108:111]
	v_mfma_f32_16x16x32_bf16 v[100:103], v[156:159], v[196:199], v[100:103]
	v_mfma_f32_16x16x32_bf16 v[92:95], v[168:171], v[196:199], v[92:95]
	v_mfma_f32_16x16x32_bf16 v[84:87], v[156:159], v[204:207], v[84:87]
	v_mfma_f32_16x16x32_bf16 v[76:79], v[168:171], v[204:207], v[76:79]
	s_setprio 0
	s_barrier
	s_add_i32 s57, s48, s34
	v_lshl_add_u64 v[144:145], s[24:25], 0, v[132:133]
	s_mov_b32 m0, s57
	ds_read_b128 v[208:211], v151
	ds_read_b128 v[212:215], v151 offset:1024
	ds_read_b128 v[216:219], v151 offset:2048
	ds_read_b128 v[220:223], v151 offset:3072
	global_load_lds_dwordx4 v[144:145], off
	v_lshl_add_u64 v[224:225], s[24:25], 0, v[128:129]
	s_add_i32 m0, s57, 0x2000
	s_nop 0
	global_load_lds_dwordx4 v[224:225], off
	s_barrier
	s_waitcnt lgkmcnt(0)
	s_setprio 1
	s_waitcnt lgkmcnt(0)
	v_mfma_f32_16x16x32_bf16 v[112:115], v[208:211], v[172:175], v[112:115]
	v_mfma_f32_16x16x32_bf16 v[104:107], v[216:219], v[172:175], v[104:107]
	v_mfma_f32_16x16x32_bf16 v[96:99], v[208:211], v[184:187], v[96:99]
	v_mfma_f32_16x16x32_bf16 v[88:91], v[216:219], v[184:187], v[88:91]
	v_mfma_f32_16x16x32_bf16 v[80:83], v[208:211], v[192:195], v[80:83]
	v_mfma_f32_16x16x32_bf16 v[72:75], v[216:219], v[192:195], v[72:75]
	v_mfma_f32_16x16x32_bf16 v[68:71], v[208:211], v[200:203], v[68:71]
	v_mfma_f32_16x16x32_bf16 v[64:67], v[216:219], v[200:203], v[64:67]
	v_mfma_f32_16x16x32_bf16 v[112:115], v[212:215], v[180:183], v[112:115]
	v_mfma_f32_16x16x32_bf16 v[104:107], v[220:223], v[180:183], v[104:107]
	v_mfma_f32_16x16x32_bf16 v[96:99], v[212:215], v[188:191], v[96:99]
	v_mfma_f32_16x16x32_bf16 v[88:91], v[220:223], v[188:191], v[88:91]
	v_mfma_f32_16x16x32_bf16 v[80:83], v[212:215], v[196:199], v[80:83]
	v_mfma_f32_16x16x32_bf16 v[72:75], v[220:223], v[196:199], v[72:75]
	v_mfma_f32_16x16x32_bf16 v[68:71], v[212:215], v[204:207], v[68:71]
	v_mfma_f32_16x16x32_bf16 v[64:67], v[220:223], v[204:207], v[64:67]
	s_setprio 0
	s_mov_b32 m0, s9
	v_lshl_add_u64 v[226:227], s[28:29], 0, v[134:135]
	s_barrier
	ds_read_b128 v[172:175], v150 offset:16384
	ds_read_b128 v[180:183], v150 offset:17408
	ds_read_b128 v[184:187], v150 offset:18432
	ds_read_b128 v[188:191], v150 offset:19456
	ds_read_b128 v[192:195], v150 offset:20480
	ds_read_b128 v[196:199], v150 offset:21504
	ds_read_b128 v[200:203], v150 offset:22528
	ds_read_b128 v[204:207], v150 offset:23552
	global_load_lds_dwordx4 v[226:227], off
	v_lshl_add_u64 v[228:229], s[28:29], 0, v[130:131]
	s_mov_b32 m0, s41
	s_nop 0
	global_load_lds_dwordx4 v[228:229], off
	s_barrier
	s_waitcnt lgkmcnt(0)
	s_setprio 1
	s_waitcnt lgkmcnt(0)
	v_mfma_f32_16x16x32_bf16 v[60:63], v[152:155], v[172:175], v[60:63]
	v_mfma_f32_16x16x32_bf16 v[56:59], v[164:167], v[172:175], v[56:59]
	v_mfma_f32_16x16x32_bf16 v[52:55], v[152:155], v[184:187], v[52:55]
	v_mfma_f32_16x16x32_bf16 v[44:47], v[164:167], v[184:187], v[44:47]
	v_mfma_f32_16x16x32_bf16 v[36:39], v[152:155], v[192:195], v[36:39]
	v_mfma_f32_16x16x32_bf16 v[28:31], v[164:167], v[192:195], v[28:31]
	v_mfma_f32_16x16x32_bf16 v[20:23], v[152:155], v[200:203], v[20:23]
	v_mfma_f32_16x16x32_bf16 v[12:15], v[164:167], v[200:203], v[12:15]
	v_mfma_f32_16x16x32_bf16 v[60:63], v[156:159], v[180:183], v[60:63]
	v_mfma_f32_16x16x32_bf16 v[56:59], v[168:171], v[180:183], v[56:59]
	v_mfma_f32_16x16x32_bf16 v[52:55], v[156:159], v[188:191], v[52:55]
	v_mfma_f32_16x16x32_bf16 v[44:47], v[168:171], v[188:191], v[44:47]
	v_mfma_f32_16x16x32_bf16 v[36:39], v[156:159], v[196:199], v[36:39]
	v_mfma_f32_16x16x32_bf16 v[28:31], v[168:171], v[196:199], v[28:31]
	v_mfma_f32_16x16x32_bf16 v[20:23], v[156:159], v[204:207], v[20:23]
	v_mfma_f32_16x16x32_bf16 v[12:15], v[168:171], v[204:207], v[12:15]
	s_setprio 0
	s_barrier
	s_add_u32 s58, s24, 0x40000
	s_addc_u32 s59, s25, 0
	s_add_i32 s57, s49, s34
	v_lshl_add_u64 v[152:153], s[58:59], 0, v[132:133]
	s_mov_b32 m0, s57
	s_nop 0
	global_load_lds_dwordx4 v[152:153], off
	v_lshl_add_u64 v[152:153], s[58:59], 0, v[128:129]
	s_add_i32 m0, s57, 0x2000
	s_nop 0
	global_load_lds_dwordx4 v[152:153], off
	s_waitcnt vmcnt(6)
	s_barrier
	s_setprio 1
	v_mfma_f32_16x16x32_bf16 v[48:51], v[208:211], v[172:175], v[48:51]
	v_mfma_f32_16x16x32_bf16 v[40:43], v[216:219], v[172:175], v[40:43]
	v_mfma_f32_16x16x32_bf16 v[32:35], v[208:211], v[184:187], v[32:35]
	v_mfma_f32_16x16x32_bf16 v[24:27], v[216:219], v[184:187], v[24:27]
	v_mfma_f32_16x16x32_bf16 v[16:19], v[208:211], v[192:195], v[16:19]
	v_mfma_f32_16x16x32_bf16 v[8:11], v[216:219], v[192:195], v[8:11]
	v_mfma_f32_16x16x32_bf16 v[4:7], v[208:211], v[200:203], v[4:7]
	v_mfma_f32_16x16x32_bf16 v[0:3], v[216:219], v[200:203], v[0:3]
	v_mfma_f32_16x16x32_bf16 v[48:51], v[212:215], v[180:183], v[48:51]
	v_mfma_f32_16x16x32_bf16 v[40:43], v[220:223], v[180:183], v[40:43]
	v_mfma_f32_16x16x32_bf16 v[32:35], v[212:215], v[188:191], v[32:35]
	v_mfma_f32_16x16x32_bf16 v[24:27], v[220:223], v[188:191], v[24:27]
	v_mfma_f32_16x16x32_bf16 v[16:19], v[212:215], v[196:199], v[16:19]
	v_mfma_f32_16x16x32_bf16 v[8:11], v[220:223], v[196:199], v[8:11]
	v_mfma_f32_16x16x32_bf16 v[4:7], v[212:215], v[204:207], v[4:7]
	v_mfma_f32_16x16x32_bf16 v[0:3], v[220:223], v[204:207], v[0:3]
	s_setprio 0
	s_add_i32 s57, 0, 0x18000
	v_add_u32_e32 v168, s57, v147
	s_barrier
	ds_read_b128 v[152:155], v168
	ds_read_b128 v[156:159], v168 offset:1024
	ds_read_b128 v[164:167], v168 offset:2048
	ds_read_b128 v[168:171], v168 offset:3072
	s_add_u32 s28, s28, 0x40000
	s_addc_u32 s29, s29, 0
	s_mov_b32 m0, s42
	v_lshl_add_u64 v[208:209], s[28:29], 0, v[134:135]
	ds_read_b128 v[172:175], v150 offset:32768
	ds_read_b128 v[180:183], v150 offset:33792
	ds_read_b128 v[184:187], v150 offset:34816
	ds_read_b128 v[188:191], v150 offset:35840
	ds_read_b128 v[192:195], v150 offset:36864
	ds_read_b128 v[196:199], v150 offset:37888
	ds_read_b128 v[200:203], v150 offset:38912
	ds_read_b128 v[204:207], v150 offset:39936
	global_load_lds_dwordx4 v[208:209], off
	v_lshl_add_u64 v[208:209], s[28:29], 0, v[130:131]
	s_mov_b32 m0, s43
	s_nop 0
	global_load_lds_dwordx4 v[208:209], off
	s_waitcnt lgkmcnt(8)
	s_barrier
	s_waitcnt lgkmcnt(0)
	s_setprio 1
	s_waitcnt lgkmcnt(0)
	v_mfma_f32_16x16x32_bf16 v[124:127], v[152:155], v[172:175], v[124:127]
	v_mfma_f32_16x16x32_bf16 v[120:123], v[164:167], v[172:175], v[120:123]
	v_mfma_f32_16x16x32_bf16 v[116:119], v[152:155], v[184:187], v[116:119]
	v_mfma_f32_16x16x32_bf16 v[108:111], v[164:167], v[184:187], v[108:111]
	v_mfma_f32_16x16x32_bf16 v[100:103], v[152:155], v[192:195], v[100:103]
	v_mfma_f32_16x16x32_bf16 v[92:95], v[164:167], v[192:195], v[92:95]
	v_mfma_f32_16x16x32_bf16 v[84:87], v[152:155], v[200:203], v[84:87]
	v_mfma_f32_16x16x32_bf16 v[76:79], v[164:167], v[200:203], v[76:79]
	v_mfma_f32_16x16x32_bf16 v[124:127], v[156:159], v[180:183], v[124:127]
	v_mfma_f32_16x16x32_bf16 v[120:123], v[168:171], v[180:183], v[120:123]
	v_mfma_f32_16x16x32_bf16 v[116:119], v[156:159], v[188:191], v[116:119]
	v_mfma_f32_16x16x32_bf16 v[108:111], v[168:171], v[188:191], v[108:111]
	v_mfma_f32_16x16x32_bf16 v[100:103], v[156:159], v[196:199], v[100:103]
	v_mfma_f32_16x16x32_bf16 v[92:95], v[168:171], v[196:199], v[92:95]
	v_mfma_f32_16x16x32_bf16 v[84:87], v[156:159], v[204:207], v[84:87]
	v_mfma_f32_16x16x32_bf16 v[76:79], v[168:171], v[204:207], v[76:79]
	s_setprio 0
	s_barrier
	s_add_i32 s28, 0, 0x1c000
	s_add_i32 s29, s57, s34
	v_add_u32_e32 v176, s28, v147
	v_lshl_add_u64 v[144:145], v[144:145], 0, s[0:1]
	s_mov_b32 m0, s29
	ds_read_b128 v[208:211], v176
	ds_read_b128 v[212:215], v176 offset:1024
	ds_read_b128 v[216:219], v176 offset:2048
	ds_read_b128 v[220:223], v176 offset:3072
	global_load_lds_dwordx4 v[144:145], off
	v_lshl_add_u64 v[144:145], v[224:225], 0, s[0:1]
	s_add_i32 m0, s29, 0x2000
	s_nop 0
	global_load_lds_dwordx4 v[144:145], off
	s_barrier
	s_waitcnt lgkmcnt(0)
	s_setprio 1
	s_waitcnt lgkmcnt(0)
	v_mfma_f32_16x16x32_bf16 v[112:115], v[208:211], v[172:175], v[112:115]
	v_mfma_f32_16x16x32_bf16 v[104:107], v[216:219], v[172:175], v[104:107]
	v_mfma_f32_16x16x32_bf16 v[96:99], v[208:211], v[184:187], v[96:99]
	v_mfma_f32_16x16x32_bf16 v[88:91], v[216:219], v[184:187], v[88:91]
	v_mfma_f32_16x16x32_bf16 v[80:83], v[208:211], v[192:195], v[80:83]
	v_mfma_f32_16x16x32_bf16 v[72:75], v[216:219], v[192:195], v[72:75]
	v_mfma_f32_16x16x32_bf16 v[68:71], v[208:211], v[200:203], v[68:71]
	v_mfma_f32_16x16x32_bf16 v[64:67], v[216:219], v[200:203], v[64:67]
	v_mfma_f32_16x16x32_bf16 v[112:115], v[212:215], v[180:183], v[112:115]
	v_mfma_f32_16x16x32_bf16 v[104:107], v[220:223], v[180:183], v[104:107]
	v_mfma_f32_16x16x32_bf16 v[96:99], v[212:215], v[188:191], v[96:99]
	v_mfma_f32_16x16x32_bf16 v[88:91], v[220:223], v[188:191], v[88:91]
	v_mfma_f32_16x16x32_bf16 v[80:83], v[212:215], v[196:199], v[80:83]
	v_mfma_f32_16x16x32_bf16 v[72:75], v[220:223], v[196:199], v[72:75]
	v_mfma_f32_16x16x32_bf16 v[68:71], v[212:215], v[204:207], v[68:71]
	v_mfma_f32_16x16x32_bf16 v[64:67], v[220:223], v[204:207], v[64:67]
	s_setprio 0
	s_mov_b32 m0, s45
	v_lshl_add_u64 v[144:145], v[226:227], 0, s[0:1]
	s_barrier
	ds_read_b128 v[172:175], v150 offset:49152
	ds_read_b128 v[180:183], v150 offset:50176
	ds_read_b128 v[184:187], v150 offset:51200
	ds_read_b128 v[188:191], v150 offset:52224
	ds_read_b128 v[192:195], v150 offset:53248
	ds_read_b128 v[196:199], v150 offset:54272
	ds_read_b128 v[200:203], v150 offset:55296
	ds_read_b128 v[204:207], v150 offset:56320
	global_load_lds_dwordx4 v[144:145], off
	v_lshl_add_u64 v[144:145], v[228:229], 0, s[0:1]
	s_mov_b32 m0, s46
	s_nop 0
	global_load_lds_dwordx4 v[144:145], off
	s_barrier
	s_waitcnt lgkmcnt(0)
	s_setprio 1
	s_waitcnt lgkmcnt(0)
	v_mfma_f32_16x16x32_bf16 v[60:63], v[152:155], v[172:175], v[60:63]
	v_mfma_f32_16x16x32_bf16 v[56:59], v[164:167], v[172:175], v[56:59]
	v_mfma_f32_16x16x32_bf16 v[52:55], v[152:155], v[184:187], v[52:55]
	v_mfma_f32_16x16x32_bf16 v[44:47], v[164:167], v[184:187], v[44:47]
	v_mfma_f32_16x16x32_bf16 v[36:39], v[152:155], v[192:195], v[36:39]
	v_mfma_f32_16x16x32_bf16 v[28:31], v[164:167], v[192:195], v[28:31]
	v_mfma_f32_16x16x32_bf16 v[20:23], v[152:155], v[200:203], v[20:23]
	v_mfma_f32_16x16x32_bf16 v[12:15], v[164:167], v[200:203], v[12:15]
	v_mfma_f32_16x16x32_bf16 v[60:63], v[156:159], v[180:183], v[60:63]
	v_mfma_f32_16x16x32_bf16 v[56:59], v[168:171], v[180:183], v[56:59]
	v_mfma_f32_16x16x32_bf16 v[52:55], v[156:159], v[188:191], v[52:55]
	v_mfma_f32_16x16x32_bf16 v[44:47], v[168:171], v[188:191], v[44:47]
	v_mfma_f32_16x16x32_bf16 v[36:39], v[156:159], v[196:199], v[36:39]
	v_mfma_f32_16x16x32_bf16 v[28:31], v[168:171], v[196:199], v[28:31]
	v_mfma_f32_16x16x32_bf16 v[20:23], v[156:159], v[204:207], v[20:23]
	v_mfma_f32_16x16x32_bf16 v[12:15], v[168:171], v[204:207], v[12:15]
	s_setprio 0
	s_barrier
	s_add_u32 s24, s24, 0x40080
	s_addc_u32 s25, s25, 0
	s_add_i32 s28, s28, s34
	v_lshl_add_u64 v[144:145], s[24:25], 0, v[132:133]
	s_mov_b32 m0, s28
	s_nop 0
	global_load_lds_dwordx4 v[144:145], off
	v_lshl_add_u64 v[144:145], s[24:25], 0, v[128:129]
	s_add_i32 m0, s28, 0x2000
	s_nop 0
	global_load_lds_dwordx4 v[144:145], off
	s_waitcnt vmcnt(6)
	s_barrier
	s_setprio 1
	v_mfma_f32_16x16x32_bf16 v[48:51], v[208:211], v[172:175], v[48:51]
	v_mfma_f32_16x16x32_bf16 v[40:43], v[216:219], v[172:175], v[40:43]
	v_mfma_f32_16x16x32_bf16 v[32:35], v[208:211], v[184:187], v[32:35]
	v_mfma_f32_16x16x32_bf16 v[24:27], v[216:219], v[184:187], v[24:27]
	v_mfma_f32_16x16x32_bf16 v[16:19], v[208:211], v[192:195], v[16:19]
	v_mfma_f32_16x16x32_bf16 v[8:11], v[216:219], v[192:195], v[8:11]
	v_mfma_f32_16x16x32_bf16 v[4:7], v[208:211], v[200:203], v[4:7]
	v_mfma_f32_16x16x32_bf16 v[0:3], v[216:219], v[200:203], v[0:3]
	v_mfma_f32_16x16x32_bf16 v[48:51], v[212:215], v[180:183], v[48:51]
	v_mfma_f32_16x16x32_bf16 v[40:43], v[220:223], v[180:183], v[40:43]
	v_mfma_f32_16x16x32_bf16 v[32:35], v[212:215], v[188:191], v[32:35]
	v_mfma_f32_16x16x32_bf16 v[24:27], v[220:223], v[188:191], v[24:27]
	v_mfma_f32_16x16x32_bf16 v[16:19], v[212:215], v[196:199], v[16:19]
	v_mfma_f32_16x16x32_bf16 v[8:11], v[220:223], v[196:199], v[8:11]
	v_mfma_f32_16x16x32_bf16 v[4:7], v[212:215], v[204:207], v[4:7]
	v_mfma_f32_16x16x32_bf16 v[0:3], v[220:223], v[204:207], v[0:3]
	s_setprio 0
	s_add_i32 s56, s56, 2
	s_add_u32 s18, s18, 0x100
	s_addc_u32 s19, s19, 0
	s_add_u32 s54, s54, 0x100
	s_addc_u32 s55, s55, 0
	s_cmp_gt_u32 s56, 13
	s_barrier
	s_cbranch_scc0 .LBB0_1378
	s_lshl_b32 s5, s51, 8
	s_add_i32 s7, s5, 0xfffff500
	s_cmp_gt_i32 s51, 10
	s_cselect_b32 s5, s7, s5
	s_cselect_b32 s7, s3, s17
	s_cselect_b32 s18, s2, s16
	v_or_b32_e32 v152, s5, v148
	v_mov_b32_e32 v144, s18
	v_mov_b32_e32 v145, s7
	v_lshl_add_u32 v154, s8, 8, v146
	v_ashrrev_i32_e32 v153, 31, v152
	v_lshl_add_u64 v[144:145], v[152:153], 1, v[144:145]
	v_cvt_pk_bf16_f32 v68, v68, v69
	v_cvt_pk_bf16_f32 v69, v70, v71
	v_cvt_pk_bf16_f32 v70, v64, v65
	v_add_u32_e32 v64, 0x80, v154
	v_mad_i64_i32 v[152:153], s[18:19], v154, s50, v[144:145]
	v_cvt_pk_bf16_f32 v112, v112, v113
	v_cvt_pk_bf16_f32 v113, v114, v115
	v_cvt_pk_bf16_f32 v114, v104, v105
	v_or_b32_e32 v104, 16, v154
	v_mad_i64_i32 v[64:65], s[18:19], v64, s50, v[144:145]
	v_cvt_pk_bf16_f32 v48, v48, v49
	v_cvt_pk_bf16_f32 v49, v50, v51
	v_cvt_pk_bf16_f32 v50, v40, v41
	v_add_u32_e32 v40, 0x90, v154
	v_cvt_pk_bf16_f32 v115, v106, v107
	global_store_dwordx4 v[152:153], v[112:115], off offset:256 sc1
	v_cvt_pk_bf16_f32 v96, v96, v97
	v_cvt_pk_bf16_f32 v97, v98, v99
	v_cvt_pk_bf16_f32 v98, v88, v89
	v_or_b32_e32 v88, 32, v154
	v_cvt_pk_bf16_f32 v51, v42, v43
	s_nop 0
	v_mad_i64_i32 v[112:113], s[18:19], v104, s50, v[144:145]
	global_store_dwordx4 v[64:65], v[48:51], off offset:256 sc1
	v_cvt_pk_bf16_f32 v32, v32, v33
	v_cvt_pk_bf16_f32 v33, v34, v35
	v_cvt_pk_bf16_f32 v34, v24, v25
	v_add_u32_e32 v24, 0xa0, v154
	v_cvt_pk_bf16_f32 v99, v90, v91
	s_nop 0
	v_mad_i64_i32 v[48:49], s[18:19], v40, s50, v[144:145]
	global_store_dwordx4 v[112:113], v[96:99], off offset:256 sc1
	v_cvt_pk_bf16_f32 v80, v80, v81
	v_cvt_pk_bf16_f32 v81, v82, v83
	v_cvt_pk_bf16_f32 v82, v72, v73
	v_or_b32_e32 v72, 48, v154
	v_cvt_pk_bf16_f32 v35, v26, v27
	s_nop 0
	v_mad_i64_i32 v[96:97], s[18:19], v88, s50, v[144:145]
	global_store_dwordx4 v[48:49], v[32:35], off offset:256 sc1
	v_cvt_pk_bf16_f32 v16, v16, v17
	v_cvt_pk_bf16_f32 v17, v18, v19
	v_cvt_pk_bf16_f32 v18, v8, v9
	v_add_u32_e32 v8, 0xb0, v154
	v_cvt_pk_bf16_f32 v83, v74, v75
	s_nop 0
	v_mad_i64_i32 v[32:33], s[18:19], v24, s50, v[144:145]
	global_store_dwordx4 v[96:97], v[80:83], off offset:256 sc1
	v_cvt_pk_bf16_f32 v19, v10, v11
	global_store_dwordx4 v[32:33], v[16:19], off offset:256 sc1
	s_and_b64 vcc, exec, s[38:39]
	v_mad_i64_i32 v[80:81], s[18:19], v72, s50, v[144:145]
	v_mad_i64_i32 v[16:17], s[18:19], v8, s50, v[144:145]
	s_mov_b32 s51, s4
	s_mov_b32 s8, s6
	s_mov_b64 s[24:25], s[12:13]
	s_mov_b64 s[18:19], s[10:11]
	v_cvt_pk_bf16_f32 v124, v124, v125
	v_cvt_pk_bf16_f32 v125, v126, v127
	v_cvt_pk_bf16_f32 v126, v120, v121
	v_cvt_pk_bf16_f32 v127, v122, v123
	global_store_dwordx4 v[152:153], v[124:127], off sc1
	v_cvt_pk_bf16_f32 v104, v116, v117
	v_cvt_pk_bf16_f32 v105, v118, v119
	v_cvt_pk_bf16_f32 v106, v108, v109
	v_cvt_pk_bf16_f32 v107, v110, v111
	global_store_dwordx4 v[112:113], v[104:107], off sc1
	v_cvt_pk_bf16_f32 v88, v100, v101
	v_cvt_pk_bf16_f32 v89, v102, v103
	v_cvt_pk_bf16_f32 v90, v92, v93
	v_cvt_pk_bf16_f32 v91, v94, v95
	global_store_dwordx4 v[96:97], v[88:91], off sc1
	v_cvt_pk_bf16_f32 v72, v84, v85
	v_cvt_pk_bf16_f32 v73, v86, v87
	v_cvt_pk_bf16_f32 v74, v76, v77
	v_cvt_pk_bf16_f32 v75, v78, v79
	global_store_dwordx4 v[80:81], v[72:75], off sc1
	v_cvt_pk_bf16_f32 v71, v66, v67
	global_store_dwordx4 v[80:81], v[68:71], off offset:256 sc1
	v_cvt_pk_bf16_f32 v60, v60, v61
	v_cvt_pk_bf16_f32 v61, v62, v63
	v_cvt_pk_bf16_f32 v62, v56, v57
	v_cvt_pk_bf16_f32 v63, v58, v59
	global_store_dwordx4 v[64:65], v[60:63], off sc1
	v_cvt_pk_bf16_f32 v40, v52, v53
	v_cvt_pk_bf16_f32 v41, v54, v55
	v_cvt_pk_bf16_f32 v42, v44, v45
	v_cvt_pk_bf16_f32 v43, v46, v47
	global_store_dwordx4 v[48:49], v[40:43], off sc1
	v_cvt_pk_bf16_f32 v24, v36, v37
	v_cvt_pk_bf16_f32 v25, v38, v39
	v_cvt_pk_bf16_f32 v26, v28, v29
	v_cvt_pk_bf16_f32 v27, v30, v31
	global_store_dwordx4 v[32:33], v[24:27], off sc1
	v_cvt_pk_bf16_f32 v8, v20, v21
	v_cvt_pk_bf16_f32 v9, v22, v23
	v_cvt_pk_bf16_f32 v10, v12, v13
	v_cvt_pk_bf16_f32 v11, v14, v15
	global_store_dwordx4 v[16:17], v[8:11], off sc1
	v_cvt_pk_bf16_f32 v4, v4, v5
	v_cvt_pk_bf16_f32 v5, v6, v7
	v_cvt_pk_bf16_f32 v6, v0, v1
	v_cvt_pk_bf16_f32 v7, v2, v3
	global_store_dwordx4 v[16:17], v[4:7], off offset:256 sc1
	s_cbranch_vccz .LBB0_1375
	s_waitcnt vmcnt(0)
	s_cmpk_gt_u32 s30, 0xff
	s_cbranch_scc1 .LBB0_1382
	s_barrier

.LBB0_1443:
	s_or_b64 exec, exec, s[0:1]
	s_waitcnt vmcnt(23)
	v_mul_f32_e32 v168, v0, v190
	s_waitcnt vmcnt(9)
	v_lshlrev_b32_e32 v191, 16, v136
	s_waitcnt vmcnt(5)
	v_fma_f32 v168, v168, v191, v72
	v_mul_f32_e32 v191, v1, v190
	v_and_b32_e32 v136, 0xffff0000, v136
	v_fma_f32 v136, v191, v136, v73
	v_mul_f32_e32 v191, v2, v190
	v_lshlrev_b32_e32 v192, 16, v137
	v_fma_f32 v191, v191, v192, v74
	v_mul_f32_e32 v192, v3, v190
	v_and_b32_e32 v137, 0xffff0000, v137
	v_fma_f32 v137, v192, v137, v75
	v_mul_f32_e32 v192, v4, v190
	v_lshlrev_b32_e32 v193, 16, v138
	s_waitcnt vmcnt(4)
	v_fma_f32 v192, v192, v193, v76
	v_mul_f32_e32 v193, v5, v190
	v_and_b32_e32 v138, 0xffff0000, v138
	v_fma_f32 v138, v193, v138, v77
	v_mul_f32_e32 v193, v6, v190
	v_lshlrev_b32_e32 v194, 16, v139
	v_mul_f32_e32 v190, v7, v190
	v_and_b32_e32 v139, 0xffff0000, v139
	v_fma_f32 v193, v193, v194, v78
	v_fma_f32 v139, v190, v139, v79
	v_mul_f32_e32 v190, v8, v188
	v_lshlrev_b32_e32 v194, 16, v124
	v_fmac_f32_e32 v168, v190, v194
	v_mul_f32_e32 v190, v9, v188
	v_and_b32_e32 v124, 0xffff0000, v124
	v_fmac_f32_e32 v136, v190, v124
	v_mul_f32_e32 v124, v10, v188
	v_lshlrev_b32_e32 v190, 16, v125
	v_fmac_f32_e32 v191, v124, v190
	v_mul_f32_e32 v124, v11, v188
	v_and_b32_e32 v125, 0xffff0000, v125
	v_fmac_f32_e32 v137, v124, v125
	v_mul_f32_e32 v124, v12, v188
	v_lshlrev_b32_e32 v125, 16, v126
	v_fmac_f32_e32 v192, v124, v125
	v_mul_f32_e32 v124, v13, v188
	v_and_b32_e32 v125, 0xffff0000, v126
	v_fmac_f32_e32 v138, v124, v125
	v_mul_f32_e32 v124, v14, v188
	v_lshlrev_b32_e32 v125, 16, v127
	v_fmac_f32_e32 v193, v124, v125
	v_mul_f32_e32 v124, v15, v188
	v_and_b32_e32 v125, 0xffff0000, v127
	v_fmac_f32_e32 v139, v124, v125
	v_mul_f32_e32 v124, v16, v189
	v_lshlrev_b32_e32 v125, 16, v128
	v_fmac_f32_e32 v168, v124, v125
	v_mul_f32_e32 v124, v17, v189
	v_and_b32_e32 v125, 0xffff0000, v128
	v_fmac_f32_e32 v136, v124, v125
	v_mul_f32_e32 v124, v18, v189
	v_lshlrev_b32_e32 v125, 16, v129
	v_fmac_f32_e32 v191, v124, v125
	v_mul_f32_e32 v124, v19, v189
	v_and_b32_e32 v125, 0xffff0000, v129
	v_fmac_f32_e32 v137, v124, v125
	v_mul_f32_e32 v124, v20, v189
	v_lshlrev_b32_e32 v125, 16, v130
	v_fmac_f32_e32 v192, v124, v125
	v_mul_f32_e32 v124, v21, v189
	v_and_b32_e32 v125, 0xffff0000, v130
	v_fmac_f32_e32 v138, v124, v125
	v_mul_f32_e32 v124, v22, v189
	v_lshlrev_b32_e32 v125, 16, v131
	v_fmac_f32_e32 v193, v124, v125
	v_mul_f32_e32 v124, v23, v189
	v_and_b32_e32 v125, 0xffff0000, v131
	v_fmac_f32_e32 v139, v124, v125
	v_mul_f32_e32 v124, v24, v187
	s_waitcnt vmcnt(3)
	v_lshlrev_b32_e32 v125, 16, v156
	v_fmac_f32_e32 v168, v124, v125
	v_mul_f32_e32 v124, v25, v187
	v_and_b32_e32 v125, 0xffff0000, v156
	v_fmac_f32_e32 v136, v124, v125
	v_mul_f32_e32 v124, v26, v187
	v_lshlrev_b32_e32 v125, 16, v157
	v_fmac_f32_e32 v191, v124, v125
	v_mul_f32_e32 v124, v27, v187
	v_and_b32_e32 v125, 0xffff0000, v157
	v_fmac_f32_e32 v137, v124, v125
	v_mul_f32_e32 v124, v28, v187
	v_lshlrev_b32_e32 v125, 16, v158
	v_fmac_f32_e32 v192, v124, v125
	v_mul_f32_e32 v124, v29, v187
	v_and_b32_e32 v125, 0xffff0000, v158
	v_fmac_f32_e32 v138, v124, v125
	v_mul_f32_e32 v124, v30, v187
	v_lshlrev_b32_e32 v125, 16, v159
	v_fmac_f32_e32 v193, v124, v125
	v_mul_f32_e32 v124, v31, v187
	v_and_b32_e32 v125, 0xffff0000, v159
	v_fmac_f32_e32 v139, v124, v125
	s_waitcnt vmcnt(2)
	v_lshlrev_b32_e32 v124, 16, v152
	v_fmac_f32_e32 v168, v32, v124
	v_and_b32_e32 v124, 0xffff0000, v152
	v_fmac_f32_e32 v136, v33, v124
	v_lshlrev_b32_e32 v124, 16, v153
	v_fmac_f32_e32 v191, v34, v124
	v_and_b32_e32 v124, 0xffff0000, v153
	v_fmac_f32_e32 v137, v35, v124
	v_lshlrev_b32_e32 v124, 16, v154
	v_fmac_f32_e32 v192, v36, v124
	v_and_b32_e32 v124, 0xffff0000, v154
	v_fmac_f32_e32 v138, v37, v124
	v_lshlrev_b32_e32 v124, 16, v155
	v_fmac_f32_e32 v193, v38, v124
	v_and_b32_e32 v124, 0xffff0000, v155
	v_fmac_f32_e32 v139, v39, v124
	v_mul_f32_e32 v124, v40, v184
	s_waitcnt vmcnt(1)
	v_lshlrev_b32_e32 v125, 16, v148
	v_fmac_f32_e32 v168, v124, v125
	v_mul_f32_e32 v124, v41, v184
	v_and_b32_e32 v125, 0xffff0000, v148
	v_fmac_f32_e32 v136, v124, v125
	v_mul_f32_e32 v124, v42, v184
	v_lshlrev_b32_e32 v125, 16, v149
	v_fmac_f32_e32 v191, v124, v125
	v_mul_f32_e32 v124, v43, v184
	v_and_b32_e32 v125, 0xffff0000, v149
	v_fmac_f32_e32 v137, v124, v125
	v_mul_f32_e32 v124, v44, v184
	v_lshlrev_b32_e32 v125, 16, v150
	v_fmac_f32_e32 v192, v124, v125
	v_mul_f32_e32 v124, v45, v184
	v_and_b32_e32 v125, 0xffff0000, v150
	v_fmac_f32_e32 v138, v124, v125
	v_mul_f32_e32 v124, v46, v184
	v_lshlrev_b32_e32 v125, 16, v151
	v_fmac_f32_e32 v193, v124, v125
	v_mul_f32_e32 v124, v47, v184
	v_and_b32_e32 v125, 0xffff0000, v151
	v_fmac_f32_e32 v139, v124, v125
	v_mul_f32_e32 v124, v48, v186
	v_lshlrev_b32_e32 v125, 16, v120
	v_fmac_f32_e32 v168, v124, v125
	v_mul_f32_e32 v124, v49, v186
	v_and_b32_e32 v120, 0xffff0000, v120
	v_fmac_f32_e32 v136, v124, v120
	v_mul_f32_e32 v120, v50, v186
	v_lshlrev_b32_e32 v124, 16, v121
	v_fmac_f32_e32 v191, v120, v124
	v_mul_f32_e32 v120, v51, v186
	v_and_b32_e32 v121, 0xffff0000, v121
	v_fmac_f32_e32 v137, v120, v121
	v_mul_f32_e32 v120, v52, v186
	v_lshlrev_b32_e32 v121, 16, v122
	v_fmac_f32_e32 v192, v120, v121
	v_mul_f32_e32 v120, v53, v186
	v_and_b32_e32 v121, 0xffff0000, v122
	v_fmac_f32_e32 v138, v120, v121
	v_mul_f32_e32 v120, v54, v186
	v_lshlrev_b32_e32 v121, 16, v123
	v_fmac_f32_e32 v193, v120, v121
	v_mul_f32_e32 v120, v55, v186
	v_and_b32_e32 v121, 0xffff0000, v123
	v_fmac_f32_e32 v139, v120, v121
	v_mul_f32_e32 v120, v56, v183
	v_lshlrev_b32_e32 v121, 16, v112
	v_fmac_f32_e32 v168, v120, v121
	v_mul_f32_e32 v120, v57, v183
	v_and_b32_e32 v112, 0xffff0000, v112
	v_fmac_f32_e32 v136, v120, v112
	v_mul_f32_e32 v112, v58, v183
	v_lshlrev_b32_e32 v120, 16, v113
	v_fmac_f32_e32 v191, v112, v120
	v_mul_f32_e32 v112, v59, v183
	v_and_b32_e32 v113, 0xffff0000, v113
	v_fmac_f32_e32 v137, v112, v113
	v_mul_f32_e32 v112, v60, v183
	v_lshlrev_b32_e32 v113, 16, v114
	v_fmac_f32_e32 v192, v112, v113
	v_mul_f32_e32 v112, v61, v183
	v_and_b32_e32 v113, 0xffff0000, v114
	v_fmac_f32_e32 v138, v112, v113
	v_mul_f32_e32 v112, v62, v183
	v_lshlrev_b32_e32 v113, 16, v115
	v_fmac_f32_e32 v193, v112, v113
	v_mul_f32_e32 v112, v63, v183
	v_and_b32_e32 v113, 0xffff0000, v115
	v_fmac_f32_e32 v139, v112, v113
	v_mul_f32_e32 v112, v64, v180
	v_lshlrev_b32_e32 v113, 16, v96
	v_fmac_f32_e32 v168, v112, v113
	v_mul_f32_e32 v112, v65, v180
	v_and_b32_e32 v96, 0xffff0000, v96
	v_fmac_f32_e32 v136, v112, v96
	v_mul_f32_e32 v96, v66, v180
	v_lshlrev_b32_e32 v112, 16, v97
	v_fmac_f32_e32 v191, v96, v112
	v_mul_f32_e32 v96, v67, v180
	v_and_b32_e32 v97, 0xffff0000, v97
	v_fmac_f32_e32 v137, v96, v97
	v_mul_f32_e32 v96, v68, v180
	v_lshlrev_b32_e32 v97, 16, v98
	v_fmac_f32_e32 v192, v96, v97
	v_mul_f32_e32 v96, v69, v180
	v_and_b32_e32 v97, 0xffff0000, v98
	v_fmac_f32_e32 v138, v96, v97
	v_mul_f32_e32 v96, 0x3d372713, v168
	v_mul_f32_e32 v96, v168, v96
	v_fma_f32 v96, v168, v96, v168
	v_mul_f32_e32 v96, 0x3f4c422a, v96
	v_add_f32_e32 v96, v96, v96
	v_mul_f32_e32 v96, 0x3fb8aa3b, v96
	v_exp_f32_e32 v96, v96
	v_mul_f32_e32 v97, v70, v180
	v_lshlrev_b32_e32 v98, 16, v99
	v_fmac_f32_e32 v193, v97, v98
	v_add_f32_e32 v96, 1.0, v96
	v_div_scale_f32 v97, s[0:1], v96, v96, v168
	v_rcp_f32_e32 v98, v97
	v_mul_f32_e32 v112, v71, v180
	v_and_b32_e32 v99, 0xffff0000, v99
	v_fmac_f32_e32 v139, v112, v99
	v_fma_f32 v99, -v97, v98, 1.0
	v_fmac_f32_e32 v98, v99, v98
	v_div_scale_f32 v99, vcc, v168, v96, v168
	v_mul_f32_e32 v112, v99, v98
	v_fma_f32 v113, -v97, v112, v99
	v_fmac_f32_e32 v112, v113, v98
	v_fma_f32 v97, -v97, v112, v99
	v_mul_f32_e32 v99, 0x3d372713, v136
	v_mul_f32_e32 v99, v136, v99
	v_fma_f32 v99, v136, v99, v136
	v_mul_f32_e32 v99, 0x3f4c422a, v99
	v_add_f32_e32 v99, v99, v99
	v_mul_f32_e32 v99, 0x3fb8aa3b, v99
	v_exp_f32_e32 v99, v99
	v_div_fmas_f32 v97, v97, v98, v112
	v_div_fixup_f32 v96, v97, v96, v168
	v_sub_f32_e32 v96, v168, v96
	v_add_f32_e32 v97, 1.0, v99
	v_div_scale_f32 v98, s[0:1], v97, v97, v136
	v_rcp_f32_e32 v99, v98
	s_waitcnt vmcnt(0)
	v_lshlrev_b32_e32 v112, 16, v100
	v_mul_f32_e32 v96, v96, v112
	v_and_b32_e32 v100, 0xffff0000, v100
	v_fma_f32 v112, -v98, v99, 1.0
	v_fmac_f32_e32 v99, v112, v99
	v_div_scale_f32 v112, vcc, v136, v97, v136
	v_mul_f32_e32 v113, v112, v99
	v_fma_f32 v114, -v98, v113, v112
	v_fmac_f32_e32 v113, v114, v99
	v_fma_f32 v98, -v98, v113, v112
	v_mul_f32_e32 v112, 0x3d372713, v191
	v_mul_f32_e32 v112, v191, v112
	v_fma_f32 v112, v191, v112, v191
	v_mul_f32_e32 v112, 0x3f4c422a, v112
	v_add_f32_e32 v112, v112, v112
	v_mul_f32_e32 v112, 0x3fb8aa3b, v112
	v_exp_f32_e32 v112, v112
	v_div_fmas_f32 v98, v98, v99, v113
	v_div_fixup_f32 v97, v98, v97, v136
	v_sub_f32_e32 v97, v136, v97
	v_add_f32_e32 v98, 1.0, v112
	v_div_scale_f32 v99, s[0:1], v98, v98, v191
	v_rcp_f32_e32 v112, v99
	v_mul_f32_e32 v97, v97, v100
	v_cvt_pk_bf16_f32 v96, v96, v97
	v_mad_u64_u32 v[132:133], s[0:1], v86, s15, v[166:167]
	v_fma_f32 v97, -v99, v112, 1.0
	v_fmac_f32_e32 v112, v97, v112
	v_div_scale_f32 v97, vcc, v191, v98, v191
	v_mul_f32_e32 v100, v97, v112
	v_fma_f32 v113, -v99, v100, v97
	v_fmac_f32_e32 v100, v113, v112
	v_fma_f32 v97, -v99, v100, v97
	v_mul_f32_e32 v99, 0x3d372713, v137
	v_mul_f32_e32 v99, v137, v99
	v_fma_f32 v99, v137, v99, v137
	v_mul_f32_e32 v99, 0x3f4c422a, v99
	v_add_f32_e32 v99, v99, v99
	v_mul_f32_e32 v99, 0x3fb8aa3b, v99
	v_exp_f32_e32 v99, v99
	v_div_fmas_f32 v97, v97, v112, v100
	v_div_fixup_f32 v97, v97, v98, v191
	v_sub_f32_e32 v97, v191, v97
	v_add_f32_e32 v98, 1.0, v99
	v_div_scale_f32 v99, s[0:1], v98, v98, v137
	v_rcp_f32_e32 v100, v99
	v_lshlrev_b32_e32 v112, 16, v101
	v_mul_f32_e32 v97, v97, v112
	v_mov_b32_e32 v86, v133
	v_fma_f32 v112, -v99, v100, 1.0
	v_fmac_f32_e32 v100, v112, v100
	v_div_scale_f32 v112, vcc, v137, v98, v137
	v_mul_f32_e32 v113, v112, v100
	v_fma_f32 v114, -v99, v113, v112
	v_fmac_f32_e32 v113, v114, v100
	v_fma_f32 v99, -v99, v113, v112
	v_mul_f32_e32 v112, 0x3d372713, v192
	v_mul_f32_e32 v112, v192, v112
	v_fma_f32 v112, v192, v112, v192
	v_mad_u64_u32 v[86:87], s[0:1], v87, s15, v[86:87]
	v_mul_f32_e32 v112, 0x3f4c422a, v112
	v_mov_b32_e32 v133, v86
	v_mad_u64_u32 v[86:87], s[0:1], v84, s15, v[166:167]
	v_mul_lo_u32 v134, v85, s15
	v_cndmask_b32_e64 v85, 0, 1, s[8:9]
	v_add_f32_e32 v112, v112, v112
	v_add_u32_e32 v87, v134, v87
	v_add_u32_e32 v85, v84, v85
	v_mul_f32_e32 v112, 0x3fb8aa3b, v112
	global_load_dwordx4 v[144:147], v[132:133], off
	global_load_dwordx4 v[140:143], v[86:87], off
	v_mad_i64_i32 v[86:87], s[0:1], v85, s15, v[166:167]
	v_mad_u64_u32 v[84:85], s[0:1], v84, s15, v[164:165]
	v_exp_f32_e32 v112, v112
	v_add_u32_e32 v85, v134, v85
	global_load_dwordx4 v[132:135], v[86:87], off
	s_nop 0
	global_load_dwordx4 v[84:87], v[84:85], off
	v_div_fmas_f32 v99, v99, v100, v113
	v_div_fixup_f32 v98, v99, v98, v137
	v_add_f32_e32 v99, 1.0, v112
	v_div_scale_f32 v100, s[0:1], v99, v99, v192
	v_rcp_f32_e32 v112, v100
	v_sub_f32_e32 v98, v137, v98
	v_and_b32_e32 v101, 0xffff0000, v101
	v_mul_f32_e32 v98, v98, v101
	v_cvt_pk_bf16_f32 v97, v97, v98
	v_fma_f32 v98, -v100, v112, 1.0
	v_fmac_f32_e32 v112, v98, v112
	v_div_scale_f32 v98, vcc, v192, v99, v192
	v_mul_f32_e32 v101, v98, v112
	v_fma_f32 v113, -v100, v101, v98
	v_fmac_f32_e32 v101, v113, v112
	v_fma_f32 v98, -v100, v101, v98
	v_mul_f32_e32 v100, 0x3d372713, v138
	v_mul_f32_e32 v100, v138, v100
	v_fma_f32 v100, v138, v100, v138
	v_mul_f32_e32 v100, 0x3f4c422a, v100
	v_add_f32_e32 v100, v100, v100
	v_mul_f32_e32 v100, 0x3fb8aa3b, v100
	v_exp_f32_e32 v100, v100
	v_div_fmas_f32 v98, v98, v112, v101
	v_div_fixup_f32 v98, v98, v99, v192
	v_sub_f32_e32 v98, v192, v98
	v_add_f32_e32 v99, 1.0, v100
	v_div_scale_f32 v100, s[0:1], v99, v99, v138
	v_rcp_f32_e32 v101, v100
	v_lshlrev_b32_e32 v112, 16, v102
	v_mul_f32_e32 v98, v98, v112
	v_and_b32_e32 v102, 0xffff0000, v102
	v_fma_f32 v112, -v100, v101, 1.0
	v_fmac_f32_e32 v101, v112, v101
	v_div_scale_f32 v112, vcc, v138, v99, v138
	v_mul_f32_e32 v113, v112, v101
	v_fma_f32 v114, -v100, v113, v112
	v_fmac_f32_e32 v113, v114, v101
	v_fma_f32 v100, -v100, v113, v112
	v_mul_f32_e32 v112, 0x3d372713, v193
	v_mul_f32_e32 v112, v193, v112
	v_fma_f32 v112, v193, v112, v193
	v_mul_f32_e32 v112, 0x3f4c422a, v112
	v_add_f32_e32 v112, v112, v112
	v_mul_f32_e32 v112, 0x3fb8aa3b, v112
	v_exp_f32_e32 v112, v112
	v_div_fmas_f32 v100, v100, v101, v113
	v_div_fixup_f32 v99, v100, v99, v138
	v_sub_f32_e32 v99, v138, v99
	v_add_f32_e32 v100, 1.0, v112
	v_div_scale_f32 v101, s[0:1], v100, v100, v193
	v_rcp_f32_e32 v112, v101
	v_mul_f32_e32 v99, v99, v102
	v_cvt_pk_bf16_f32 v98, v98, v99
	v_fma_f32 v99, -v101, v112, 1.0
	v_fmac_f32_e32 v112, v99, v112
	v_div_scale_f32 v99, vcc, v193, v100, v193
	v_mul_f32_e32 v102, v99, v112
	v_fma_f32 v113, -v101, v102, v99
	v_fmac_f32_e32 v102, v113, v112
	v_fma_f32 v99, -v101, v102, v99
	v_mul_f32_e32 v101, 0x3d372713, v139
	v_mul_f32_e32 v101, v139, v101
	v_fma_f32 v101, v139, v101, v139
	v_mul_f32_e32 v101, 0x3f4c422a, v101
	v_add_f32_e32 v101, v101, v101
	v_mul_f32_e32 v101, 0x3fb8aa3b, v101
	v_exp_f32_e32 v101, v101
	v_div_fmas_f32 v99, v99, v112, v102
	v_div_fixup_f32 v99, v99, v100, v193
	v_sub_f32_e32 v99, v193, v99
	v_add_f32_e32 v100, 1.0, v101
	v_div_scale_f32 v101, s[0:1], v100, v100, v139
	v_rcp_f32_e32 v102, v101
	v_lshlrev_b32_e32 v112, 16, v103
	v_mul_f32_e32 v99, v99, v112
	v_fma_f32 v112, -v101, v102, 1.0
	v_fmac_f32_e32 v102, v112, v102
	v_div_scale_f32 v112, vcc, v139, v100, v139
	v_mul_f32_e32 v113, v112, v102
	v_fma_f32 v114, -v101, v113, v112
	v_fmac_f32_e32 v113, v114, v102
	v_fma_f32 v101, -v101, v113, v112
	v_div_fmas_f32 v101, v101, v102, v113
	v_div_fixup_f32 v100, v101, v100, v139
	v_sub_f32_e32 v100, v139, v100
	v_and_b32_e32 v101, 0xffff0000, v103
	v_mul_f32_e32 v100, v100, v101
	v_cvt_pk_bf16_f32 v99, v99, v100
	s_and_saveexec_b64 s[0:1], s[40:41]
	s_cbranch_execz .LBB0_1445
	v_mad_i64_i32 v[100:101], s[8:9], v172, s15, v[164:165]
	global_store_dwordx4 v[100:101], v[96:99], off sc1
.LBB0_1445:
	s_or_b64 exec, exec, s[0:1]
	s_nop 0
	v_mul_f32_e32 v96, v0, v185
	v_lshlrev_b32_e32 v97, 16, v116
	v_fma_f32 v96, v96, v97, v72
	v_mul_f32_e32 v97, v1, v185
	v_and_b32_e32 v98, 0xffff0000, v116
	v_fma_f32 v97, v97, v98, v73
	v_mul_f32_e32 v98, v2, v185
	v_lshlrev_b32_e32 v99, 16, v117
	v_fma_f32 v98, v98, v99, v74
	v_mul_f32_e32 v99, v3, v185
	v_and_b32_e32 v100, 0xffff0000, v117
	v_fma_f32 v99, v99, v100, v75
	v_mul_f32_e32 v100, v4, v185
	v_lshlrev_b32_e32 v101, 16, v118
	v_fma_f32 v100, v100, v101, v76
	v_mul_f32_e32 v101, v5, v185
	v_and_b32_e32 v102, 0xffff0000, v118
	v_fma_f32 v101, v101, v102, v77
	v_mul_f32_e32 v102, v6, v185
	v_lshlrev_b32_e32 v103, 16, v119
	v_fma_f32 v102, v102, v103, v78
	v_mul_f32_e32 v103, v7, v185
	v_and_b32_e32 v112, 0xffff0000, v119
	v_fma_f32 v103, v103, v112, v79
	v_mul_f32_e32 v112, v8, v181
	v_lshlrev_b32_e32 v113, 16, v104
	v_fmac_f32_e32 v96, v112, v113
	v_mul_f32_e32 v112, v9, v181
	v_and_b32_e32 v104, 0xffff0000, v104
	v_fmac_f32_e32 v97, v112, v104
	v_mul_f32_e32 v104, v10, v181
	v_lshlrev_b32_e32 v112, 16, v105
	v_fmac_f32_e32 v98, v104, v112
	v_mul_f32_e32 v104, v11, v181
	v_and_b32_e32 v105, 0xffff0000, v105
	v_fmac_f32_e32 v99, v104, v105
	v_mul_f32_e32 v104, v12, v181
	v_lshlrev_b32_e32 v105, 16, v106
	v_fmac_f32_e32 v100, v104, v105
	v_mul_f32_e32 v104, v13, v181
	v_and_b32_e32 v105, 0xffff0000, v106
	v_fmac_f32_e32 v101, v104, v105
	v_mul_f32_e32 v104, v14, v181
	v_lshlrev_b32_e32 v105, 16, v107
	v_fmac_f32_e32 v102, v104, v105
	v_mul_f32_e32 v104, v15, v181
	v_and_b32_e32 v105, 0xffff0000, v107
	v_fmac_f32_e32 v103, v104, v105
	v_mul_f32_e32 v104, v16, v182
	v_lshlrev_b32_e32 v105, 16, v108
	v_fmac_f32_e32 v96, v104, v105
	v_mul_f32_e32 v104, v17, v182
	v_and_b32_e32 v105, 0xffff0000, v108
	v_fmac_f32_e32 v97, v104, v105
	v_mul_f32_e32 v104, v18, v182
	v_lshlrev_b32_e32 v105, 16, v109
	v_fmac_f32_e32 v98, v104, v105
	v_mul_f32_e32 v104, v19, v182
	v_and_b32_e32 v105, 0xffff0000, v109
	v_fmac_f32_e32 v99, v104, v105
	v_mul_f32_e32 v104, v20, v182
	v_lshlrev_b32_e32 v105, 16, v110
	v_fmac_f32_e32 v100, v104, v105
	v_mul_f32_e32 v104, v21, v182
	v_and_b32_e32 v105, 0xffff0000, v110
	v_fmac_f32_e32 v101, v104, v105
	v_mul_f32_e32 v104, v22, v182
	v_lshlrev_b32_e32 v105, 16, v111
	v_fmac_f32_e32 v102, v104, v105
	v_mul_f32_e32 v104, v23, v182
	v_and_b32_e32 v105, 0xffff0000, v111
	v_fmac_f32_e32 v103, v104, v105
	v_mul_f32_e32 v104, v24, v178
	s_waitcnt vmcnt(3)
	v_lshlrev_b32_e32 v105, 16, v144
	v_fmac_f32_e32 v96, v104, v105
	v_mul_f32_e32 v104, v25, v178
	v_and_b32_e32 v105, 0xffff0000, v144
	v_fmac_f32_e32 v97, v104, v105
	v_mul_f32_e32 v104, v26, v178
	v_lshlrev_b32_e32 v105, 16, v145
	v_fmac_f32_e32 v98, v104, v105
	v_mul_f32_e32 v104, v27, v178
	v_and_b32_e32 v105, 0xffff0000, v145
	v_fmac_f32_e32 v99, v104, v105
	v_mul_f32_e32 v104, v28, v178
	v_lshlrev_b32_e32 v105, 16, v146
	v_fmac_f32_e32 v100, v104, v105
	v_mul_f32_e32 v104, v29, v178
	v_and_b32_e32 v105, 0xffff0000, v146
	v_fmac_f32_e32 v101, v104, v105
	v_mul_f32_e32 v104, v30, v178
	v_lshlrev_b32_e32 v105, 16, v147
	v_fmac_f32_e32 v102, v104, v105
	v_mul_f32_e32 v104, v31, v178
	v_and_b32_e32 v105, 0xffff0000, v147
	v_fmac_f32_e32 v103, v104, v105
	s_waitcnt vmcnt(2)
	v_lshlrev_b32_e32 v104, 16, v140
	v_fmac_f32_e32 v96, v32, v104
	v_and_b32_e32 v104, 0xffff0000, v140
	v_fmac_f32_e32 v97, v33, v104
	v_lshlrev_b32_e32 v104, 16, v141
	v_fmac_f32_e32 v98, v34, v104
	v_and_b32_e32 v104, 0xffff0000, v141
	v_fmac_f32_e32 v99, v35, v104
	v_lshlrev_b32_e32 v104, 16, v142
	v_fmac_f32_e32 v100, v36, v104
	v_and_b32_e32 v104, 0xffff0000, v142
	v_fmac_f32_e32 v101, v37, v104
	v_lshlrev_b32_e32 v104, 16, v143
	v_fmac_f32_e32 v102, v38, v104
	v_and_b32_e32 v104, 0xffff0000, v143
	v_fmac_f32_e32 v103, v39, v104
	v_mul_f32_e32 v104, v40, v175
	s_waitcnt vmcnt(1)
	v_lshlrev_b32_e32 v105, 16, v132
	v_fmac_f32_e32 v96, v104, v105
	v_mul_f32_e32 v104, v41, v175
	v_and_b32_e32 v105, 0xffff0000, v132
	v_fmac_f32_e32 v97, v104, v105
	v_mul_f32_e32 v104, v42, v175
	v_lshlrev_b32_e32 v105, 16, v133
	v_fmac_f32_e32 v98, v104, v105
	v_mul_f32_e32 v104, v43, v175
	v_and_b32_e32 v105, 0xffff0000, v133
	v_fmac_f32_e32 v99, v104, v105
	v_mul_f32_e32 v104, v44, v175
	v_lshlrev_b32_e32 v105, 16, v134
	v_fmac_f32_e32 v100, v104, v105
	v_mul_f32_e32 v104, v45, v175
	v_and_b32_e32 v105, 0xffff0000, v134
	v_fmac_f32_e32 v101, v104, v105
	v_mul_f32_e32 v104, v46, v175
	v_lshlrev_b32_e32 v105, 16, v135
	v_fmac_f32_e32 v102, v104, v105
	v_mul_f32_e32 v104, v47, v175
	v_and_b32_e32 v105, 0xffff0000, v135
	v_fmac_f32_e32 v103, v104, v105
	v_mul_f32_e32 v104, v48, v176
	v_lshlrev_b32_e32 v105, 16, v92
	v_fmac_f32_e32 v96, v104, v105
	v_mul_f32_e32 v104, v49, v176
	v_and_b32_e32 v92, 0xffff0000, v92
	v_fmac_f32_e32 v97, v104, v92
	v_mul_f32_e32 v92, v50, v176
	v_lshlrev_b32_e32 v104, 16, v93
	v_fmac_f32_e32 v98, v92, v104
	v_mul_f32_e32 v92, v51, v176
	v_and_b32_e32 v93, 0xffff0000, v93
	v_fmac_f32_e32 v99, v92, v93
	v_mul_f32_e32 v92, v52, v176
	v_lshlrev_b32_e32 v93, 16, v94
	v_fmac_f32_e32 v100, v92, v93
	v_mul_f32_e32 v92, v53, v176
	v_and_b32_e32 v93, 0xffff0000, v94
	v_fmac_f32_e32 v101, v92, v93
	v_mul_f32_e32 v92, v54, v176
	v_lshlrev_b32_e32 v93, 16, v95
	v_fmac_f32_e32 v102, v92, v93
	v_mul_f32_e32 v92, v55, v176
	v_and_b32_e32 v93, 0xffff0000, v95
	v_fmac_f32_e32 v103, v92, v93
	v_mul_f32_e32 v92, v56, v174
	v_lshlrev_b32_e32 v93, 16, v88
	v_fmac_f32_e32 v96, v92, v93
	v_mul_f32_e32 v92, v57, v174
	v_and_b32_e32 v88, 0xffff0000, v88
	v_fmac_f32_e32 v97, v92, v88
	v_mul_f32_e32 v88, v58, v174
	v_lshlrev_b32_e32 v92, 16, v89
	v_fmac_f32_e32 v98, v88, v92
	v_mul_f32_e32 v88, v59, v174
	v_and_b32_e32 v89, 0xffff0000, v89
	v_fmac_f32_e32 v99, v88, v89
	v_mul_f32_e32 v88, v60, v174
	v_lshlrev_b32_e32 v89, 16, v90
	v_fmac_f32_e32 v100, v88, v89
	v_mul_f32_e32 v88, v61, v174
	v_and_b32_e32 v89, 0xffff0000, v90
	v_fmac_f32_e32 v101, v88, v89
	v_mul_f32_e32 v88, v62, v174
	v_lshlrev_b32_e32 v89, 16, v91
	v_fmac_f32_e32 v102, v88, v89
	v_mul_f32_e32 v88, v63, v174
	v_and_b32_e32 v89, 0xffff0000, v91
	v_fmac_f32_e32 v103, v88, v89
	v_mul_f32_e32 v88, v64, v173
	v_lshlrev_b32_e32 v89, 16, v80
	v_fmac_f32_e32 v96, v88, v89
	v_mul_f32_e32 v88, v65, v173
	v_and_b32_e32 v80, 0xffff0000, v80
	v_fmac_f32_e32 v97, v88, v80
	v_mul_f32_e32 v80, v66, v173
	v_lshlrev_b32_e32 v88, 16, v81
	v_fmac_f32_e32 v98, v80, v88
	v_mul_f32_e32 v80, v67, v173
	v_and_b32_e32 v81, 0xffff0000, v81
	v_fmac_f32_e32 v99, v80, v81
	v_mul_f32_e32 v80, v68, v173
	v_lshlrev_b32_e32 v81, 16, v82
	v_fmac_f32_e32 v100, v80, v81
	v_mul_f32_e32 v80, v69, v173
	v_and_b32_e32 v81, 0xffff0000, v82
	v_fmac_f32_e32 v101, v80, v81
	v_mul_f32_e32 v80, 0x3d372713, v96
	v_mul_f32_e32 v80, v96, v80
	v_fma_f32 v80, v96, v80, v96
	v_mul_f32_e32 v80, 0x3f4c422a, v80
	v_add_f32_e32 v80, v80, v80
	v_mul_f32_e32 v80, 0x3fb8aa3b, v80
	v_exp_f32_e32 v80, v80
	v_mul_f32_e32 v81, v70, v173
	v_lshlrev_b32_e32 v82, 16, v83
	v_fmac_f32_e32 v102, v81, v82
	v_add_f32_e32 v80, 1.0, v80
	v_div_scale_f32 v81, s[0:1], v80, v80, v96
	v_rcp_f32_e32 v82, v81
	v_mul_f32_e32 v88, v71, v173
	v_and_b32_e32 v83, 0xffff0000, v83
	v_fmac_f32_e32 v103, v88, v83
	v_fma_f32 v83, -v81, v82, 1.0
	v_fmac_f32_e32 v82, v83, v82
	v_div_scale_f32 v83, vcc, v96, v80, v96
	v_mul_f32_e32 v88, v83, v82
	v_fma_f32 v89, -v81, v88, v83
	v_fmac_f32_e32 v88, v89, v82
	v_fma_f32 v81, -v81, v88, v83
	v_mul_f32_e32 v83, 0x3d372713, v97
	v_mul_f32_e32 v83, v97, v83
	v_fma_f32 v83, v97, v83, v97
	v_mul_f32_e32 v83, 0x3f4c422a, v83
	v_add_f32_e32 v83, v83, v83
	v_mul_f32_e32 v83, 0x3fb8aa3b, v83
	v_exp_f32_e32 v83, v83
	v_div_fmas_f32 v81, v81, v82, v88
	v_div_fixup_f32 v80, v81, v80, v96
	v_sub_f32_e32 v80, v96, v80
	v_add_f32_e32 v81, 1.0, v83
	v_div_scale_f32 v82, s[0:1], v81, v81, v97
	v_rcp_f32_e32 v83, v82
	s_waitcnt vmcnt(0)
	v_lshlrev_b32_e32 v88, 16, v84
	v_mul_f32_e32 v80, v80, v88
	v_and_b32_e32 v84, 0xffff0000, v84
	v_fma_f32 v88, -v82, v83, 1.0
	v_fmac_f32_e32 v83, v88, v83
	v_div_scale_f32 v88, vcc, v97, v81, v97
	v_mul_f32_e32 v89, v88, v83
	v_fma_f32 v90, -v82, v89, v88
	v_fmac_f32_e32 v89, v90, v83
	v_fma_f32 v82, -v82, v89, v88
	v_mul_f32_e32 v88, 0x3d372713, v98
	v_mul_f32_e32 v88, v98, v88
	v_fma_f32 v88, v98, v88, v98
	v_mul_f32_e32 v88, 0x3f4c422a, v88
	v_add_f32_e32 v88, v88, v88
	v_mul_f32_e32 v88, 0x3fb8aa3b, v88
	v_exp_f32_e32 v88, v88
	v_div_fmas_f32 v82, v82, v83, v89
	v_div_fixup_f32 v81, v82, v81, v97
	v_sub_f32_e32 v81, v97, v81
	v_add_f32_e32 v82, 1.0, v88
	v_div_scale_f32 v83, s[0:1], v82, v82, v98
	v_rcp_f32_e32 v88, v83
	v_mul_f32_e32 v81, v81, v84
	v_cvt_pk_bf16_f32 v80, v80, v81
	v_fma_f32 v81, -v83, v88, 1.0
	v_fmac_f32_e32 v88, v81, v88
	v_div_scale_f32 v81, vcc, v98, v82, v98
	v_mul_f32_e32 v84, v81, v88
	v_fma_f32 v89, -v83, v84, v81
	v_fmac_f32_e32 v84, v89, v88
	v_fma_f32 v81, -v83, v84, v81
	v_mul_f32_e32 v83, 0x3d372713, v99
	v_mul_f32_e32 v83, v99, v83
	v_fma_f32 v83, v99, v83, v99
	v_mul_f32_e32 v83, 0x3f4c422a, v83
	v_add_f32_e32 v83, v83, v83
	v_mul_f32_e32 v83, 0x3fb8aa3b, v83
	v_exp_f32_e32 v83, v83
	v_div_fmas_f32 v81, v81, v88, v84
	v_div_fixup_f32 v81, v81, v82, v98
	v_sub_f32_e32 v81, v98, v81
	v_add_f32_e32 v82, 1.0, v83
	v_div_scale_f32 v83, s[0:1], v82, v82, v99
	v_rcp_f32_e32 v84, v83
	v_lshlrev_b32_e32 v88, 16, v85
	v_mul_f32_e32 v81, v81, v88
	v_and_b32_e32 v85, 0xffff0000, v85
	v_fma_f32 v88, -v83, v84, 1.0
	v_fmac_f32_e32 v84, v88, v84
	v_div_scale_f32 v88, vcc, v99, v82, v99
	v_mul_f32_e32 v89, v88, v84
	v_fma_f32 v90, -v83, v89, v88
	v_fmac_f32_e32 v89, v90, v84
	v_fma_f32 v83, -v83, v89, v88
	v_mul_f32_e32 v88, 0x3d372713, v100
	v_mul_f32_e32 v88, v100, v88
	v_fma_f32 v88, v100, v88, v100
	v_mul_f32_e32 v88, 0x3f4c422a, v88
	v_add_f32_e32 v88, v88, v88
	v_mul_f32_e32 v88, 0x3fb8aa3b, v88
	v_exp_f32_e32 v88, v88
	v_div_fmas_f32 v83, v83, v84, v89
	v_div_fixup_f32 v82, v83, v82, v99
	v_sub_f32_e32 v82, v99, v82
	v_add_f32_e32 v83, 1.0, v88
	v_div_scale_f32 v84, s[0:1], v83, v83, v100
	v_rcp_f32_e32 v88, v84
	v_mul_f32_e32 v82, v82, v85
	v_cvt_pk_bf16_f32 v81, v81, v82
	v_fma_f32 v82, -v84, v88, 1.0
	v_fmac_f32_e32 v88, v82, v88
	v_div_scale_f32 v82, vcc, v100, v83, v100
	v_mul_f32_e32 v85, v82, v88
	v_fma_f32 v89, -v84, v85, v82
	v_fmac_f32_e32 v85, v89, v88
	v_fma_f32 v82, -v84, v85, v82
	v_mul_f32_e32 v84, 0x3d372713, v101
	v_mul_f32_e32 v84, v101, v84
	v_fma_f32 v84, v101, v84, v101
	v_mul_f32_e32 v84, 0x3f4c422a, v84
	v_add_f32_e32 v84, v84, v84
	v_mul_f32_e32 v84, 0x3fb8aa3b, v84
	v_exp_f32_e32 v84, v84
	v_div_fmas_f32 v82, v82, v88, v85
	v_div_fixup_f32 v82, v82, v83, v100
	v_sub_f32_e32 v82, v100, v82
	v_add_f32_e32 v83, 1.0, v84
	v_div_scale_f32 v84, s[0:1], v83, v83, v101
	v_rcp_f32_e32 v85, v84
	v_lshlrev_b32_e32 v88, 16, v86
	v_mul_f32_e32 v82, v82, v88
	v_and_b32_e32 v86, 0xffff0000, v86
	v_fma_f32 v88, -v84, v85, 1.0
	v_fmac_f32_e32 v85, v88, v85
	v_div_scale_f32 v88, vcc, v101, v83, v101
	v_mul_f32_e32 v89, v88, v85
	v_fma_f32 v90, -v84, v89, v88
	v_fmac_f32_e32 v89, v90, v85
	v_fma_f32 v84, -v84, v89, v88
	v_mul_f32_e32 v88, 0x3d372713, v102
	v_mul_f32_e32 v88, v102, v88
	v_fma_f32 v88, v102, v88, v102
	v_mul_f32_e32 v88, 0x3f4c422a, v88
	v_add_f32_e32 v88, v88, v88
	v_mul_f32_e32 v88, 0x3fb8aa3b, v88
	v_exp_f32_e32 v88, v88
	v_div_fmas_f32 v84, v84, v85, v89
	v_div_fixup_f32 v83, v84, v83, v101
	v_sub_f32_e32 v83, v101, v83
	v_add_f32_e32 v84, 1.0, v88
	v_div_scale_f32 v85, s[0:1], v84, v84, v102
	v_rcp_f32_e32 v88, v85
	v_mul_f32_e32 v83, v83, v86
	v_cvt_pk_bf16_f32 v82, v82, v83
	v_fma_f32 v83, -v85, v88, 1.0
	v_fmac_f32_e32 v88, v83, v88
	v_div_scale_f32 v83, vcc, v102, v84, v102
	v_mul_f32_e32 v86, v83, v88
	v_fma_f32 v89, -v85, v86, v83
	v_fmac_f32_e32 v86, v89, v88
	v_fma_f32 v83, -v85, v86, v83
	v_mul_f32_e32 v85, 0x3d372713, v103
	v_mul_f32_e32 v85, v103, v85
	v_fma_f32 v85, v103, v85, v103
	v_mul_f32_e32 v85, 0x3f4c422a, v85
	v_add_f32_e32 v85, v85, v85
	v_mul_f32_e32 v85, 0x3fb8aa3b, v85
	v_exp_f32_e32 v85, v85
	v_div_fmas_f32 v83, v83, v88, v86
	v_div_fixup_f32 v83, v83, v84, v102
	v_sub_f32_e32 v83, v102, v83
	v_add_f32_e32 v84, 1.0, v85
	v_div_scale_f32 v85, s[0:1], v84, v84, v103
	v_rcp_f32_e32 v86, v85
	v_lshlrev_b32_e32 v88, 16, v87
	v_mul_f32_e32 v83, v83, v88
	v_fma_f32 v88, -v85, v86, 1.0
	v_fmac_f32_e32 v86, v88, v86
	v_div_scale_f32 v88, vcc, v103, v84, v103
	v_mul_f32_e32 v89, v88, v86
	v_fma_f32 v90, -v85, v89, v88
	v_fmac_f32_e32 v89, v90, v86
	v_fma_f32 v85, -v85, v89, v88
	v_div_fmas_f32 v85, v85, v86, v89
	v_div_fixup_f32 v84, v85, v84, v103
	v_sub_f32_e32 v84, v103, v84
	v_and_b32_e32 v85, 0xffff0000, v87
	v_mul_f32_e32 v84, v84, v85
	v_cvt_pk_bf16_f32 v83, v83, v84
	s_and_saveexec_b64 s[0:1], s[38:39]
	s_cbranch_execz .LBB0_1434
	v_mad_i64_i32 v[84:85], s[8:9], v171, s15, v[164:165]
	global_store_dwordx4 v[84:85], v[80:83], off sc1
	s_branch .LBB0_1434
.LBB0_1447:
	s_or_b64 exec, exec, s[4:5]
	s_waitcnt vmcnt(0)
	s_barrier
	s_and_saveexec_b64 s[0:1], s[34:35]
	s_cbranch_execz .LBB0_1495
	s_add_u32 s98, s98, 1
	v_mov_b32_e32 v7, 0x26c00
	ds_read2_b32 v[8:9], v7 offset1:1
	v_mov_b32_e32 v2, s99
	v_mov_b32_e32 v3, 1
	global_atomic_add v4, v2, v3, s[100:101] sc0
	v_add_u32_e32 v2, 0x1000, v2
	v_mov_b32_e32 v10, 0x2480
	s_waitcnt vmcnt(0) lgkmcnt(0)
	v_add_u32_e32 v4, 1, v4
	v_mul_lo_u32 v5, v8, s98
	v_mul_lo_u32 v9, v9, s98
	v_cmp_eq_u32_e32 vcc, v4, v5
	s_and_saveexec_b64 s[4:5], vcc
	s_cbranch_execz .Lh2_skip_9
	buffer_wbl2 sc1
	s_waitcnt vmcnt(0)
	global_atomic_add v10, v3, s[100:101]
	global_atomic_add v10, v3, s[100:101] offset:256
	global_atomic_add v10, v3, s[100:101] offset:512
	global_atomic_add v10, v3, s[100:101] offset:768
	global_atomic_add v10, v3, s[100:101] offset:1024
	global_atomic_add v10, v3, s[100:101] offset:1280
	global_atomic_add v10, v3, s[100:101] offset:1536
	global_atomic_add v10, v3, s[100:101] offset:1792
	global_atomic_add v10, v3, s[100:101] offset:2048
	global_atomic_add v10, v3, s[100:101] offset:2304
	global_atomic_add v10, v3, s[100:101] offset:2560
	global_atomic_add v10, v3, s[100:101] offset:2816
	global_atomic_add v10, v3, s[100:101] offset:3072
	global_atomic_add v10, v3, s[100:101] offset:3328
	global_atomic_add v10, v3, s[100:101] offset:3584
	global_atomic_add v10, v3, s[100:101] offset:3840

.LBB0_1514:
	ds_read_b128 v[80:83], v167
	ds_read_b128 v[84:87], v167 offset:1024
	ds_read_b128 v[92:95], v167 offset:2048
	ds_read_b128 v[100:103], v167 offset:3072
	s_add_u32 s10, s8, 0x100
	s_addc_u32 s11, s9, 0
	s_cmp_eq_u32 s46, 40
	s_cselect_b32 s15, s1, s11
	s_cselect_b32 s14, s0, s10
	s_cselect_b32 s13, s7, s39
	s_cselect_b32 s12, s6, s38
	v_lshl_add_u64 v[174:175], s[8:9], 0, v[148:149]
	s_add_i32 m0, s25, 0xc000
	ds_read_b128 v[156:159], v168
	ds_read_b128 v[170:173], v168 offset:1024
	ds_read_b128 v[180:183], v168 offset:2048
	ds_read_b128 v[184:187], v168 offset:3072
	ds_read_b128 v[188:191], v168 offset:4096
	ds_read_b128 v[192:195], v168 offset:5120
	ds_read_b128 v[196:199], v168 offset:6144
	ds_read_b128 v[200:203], v168 offset:7168
	global_load_lds_dwordx4 v[174:175], off
	v_lshl_add_u64 v[174:175], s[8:9], 0, v[150:151]
	s_add_i32 m0, s25, 0xe000
	s_nop 0
	global_load_lds_dwordx4 v[174:175], off
	s_waitcnt lgkmcnt(8)
	s_barrier
	s_waitcnt lgkmcnt(0)
	s_setprio 1
	s_waitcnt lgkmcnt(0)
	v_mfma_f32_16x16x32_bf16 v[140:143], v[80:83], v[156:159], v[140:143]
	v_mfma_f32_16x16x32_bf16 v[136:139], v[92:95], v[156:159], v[136:139]
	v_mfma_f32_16x16x32_bf16 v[124:127], v[80:83], v[180:183], v[124:127]
	v_mfma_f32_16x16x32_bf16 v[120:123], v[92:95], v[180:183], v[120:123]
	v_mfma_f32_16x16x32_bf16 v[108:111], v[80:83], v[188:191], v[108:111]
	v_mfma_f32_16x16x32_bf16 v[104:107], v[92:95], v[188:191], v[104:107]
	v_mfma_f32_16x16x32_bf16 v[76:79], v[80:83], v[196:199], v[76:79]
	v_mfma_f32_16x16x32_bf16 v[72:75], v[92:95], v[196:199], v[72:75]
	v_mfma_f32_16x16x32_bf16 v[140:143], v[84:87], v[170:173], v[140:143]
	v_mfma_f32_16x16x32_bf16 v[136:139], v[100:103], v[170:173], v[136:139]
	v_mfma_f32_16x16x32_bf16 v[124:127], v[84:87], v[184:187], v[124:127]
	v_mfma_f32_16x16x32_bf16 v[120:123], v[100:103], v[184:187], v[120:123]
	v_mfma_f32_16x16x32_bf16 v[108:111], v[84:87], v[192:195], v[108:111]
	v_mfma_f32_16x16x32_bf16 v[104:107], v[100:103], v[192:195], v[104:107]
	v_mfma_f32_16x16x32_bf16 v[76:79], v[84:87], v[200:203], v[76:79]
	v_mfma_f32_16x16x32_bf16 v[72:75], v[100:103], v[200:203], v[72:75]
	s_setprio 0
	s_barrier
	s_add_i32 s8, s40, s24
	v_lshl_add_u64 v[174:175], s[12:13], 0, v[144:145]
	s_mov_b32 m0, s8
	ds_read_b128 v[204:207], v169
	ds_read_b128 v[208:211], v169 offset:1024
	ds_read_b128 v[212:215], v169 offset:2048
	ds_read_b128 v[216:219], v169 offset:3072
	global_load_lds_dwordx4 v[174:175], off
	v_lshl_add_u64 v[220:221], s[12:13], 0, v[146:147]
	s_add_i32 m0, s8, 0x2000
	s_nop 0
	global_load_lds_dwordx4 v[220:221], off
	s_barrier
	s_waitcnt lgkmcnt(0)
	s_setprio 1
	s_waitcnt lgkmcnt(0)
	v_mfma_f32_16x16x32_bf16 v[132:135], v[204:207], v[156:159], v[132:135]
	v_mfma_f32_16x16x32_bf16 v[128:131], v[212:215], v[156:159], v[128:131]
	v_mfma_f32_16x16x32_bf16 v[116:119], v[204:207], v[180:183], v[116:119]
	v_mfma_f32_16x16x32_bf16 v[112:115], v[212:215], v[180:183], v[112:115]
	v_mfma_f32_16x16x32_bf16 v[96:99], v[204:207], v[188:191], v[96:99]
	v_mfma_f32_16x16x32_bf16 v[88:91], v[212:215], v[188:191], v[88:91]
	v_mfma_f32_16x16x32_bf16 v[68:71], v[204:207], v[196:199], v[68:71]
	v_mfma_f32_16x16x32_bf16 v[64:67], v[212:215], v[196:199], v[64:67]
	v_mfma_f32_16x16x32_bf16 v[132:135], v[208:211], v[170:173], v[132:135]
	v_mfma_f32_16x16x32_bf16 v[128:131], v[216:219], v[170:173], v[128:131]
	v_mfma_f32_16x16x32_bf16 v[116:119], v[208:211], v[184:187], v[116:119]
	v_mfma_f32_16x16x32_bf16 v[112:115], v[216:219], v[184:187], v[112:115]
	v_mfma_f32_16x16x32_bf16 v[96:99], v[208:211], v[192:195], v[96:99]
	v_mfma_f32_16x16x32_bf16 v[88:91], v[216:219], v[192:195], v[88:91]
	v_mfma_f32_16x16x32_bf16 v[68:71], v[208:211], v[200:203], v[68:71]
	v_mfma_f32_16x16x32_bf16 v[64:67], v[216:219], v[200:203], v[64:67]
	s_setprio 0
	s_mov_b32 m0, s25
	v_lshl_add_u64 v[222:223], s[14:15], 0, v[144:145]
	s_barrier
	ds_read_b128 v[156:159], v168 offset:16384
	ds_read_b128 v[170:173], v168 offset:17408
	ds_read_b128 v[180:183], v168 offset:18432
	ds_read_b128 v[184:187], v168 offset:19456
	ds_read_b128 v[188:191], v168 offset:20480
	ds_read_b128 v[192:195], v168 offset:21504
	ds_read_b128 v[196:199], v168 offset:22528
	ds_read_b128 v[200:203], v168 offset:23552
	global_load_lds_dwordx4 v[222:223], off
	v_lshl_add_u64 v[224:225], s[14:15], 0, v[146:147]
	s_mov_b32 m0, s26
	s_nop 0
	global_load_lds_dwordx4 v[224:225], off
	s_barrier
	s_waitcnt lgkmcnt(0)
	s_setprio 1
	s_waitcnt lgkmcnt(0)
	v_mfma_f32_16x16x32_bf16 v[60:63], v[80:83], v[156:159], v[60:63]
	v_mfma_f32_16x16x32_bf16 v[56:59], v[92:95], v[156:159], v[56:59]
	v_mfma_f32_16x16x32_bf16 v[44:47], v[80:83], v[180:183], v[44:47]
	v_mfma_f32_16x16x32_bf16 v[40:43], v[92:95], v[180:183], v[40:43]
	v_mfma_f32_16x16x32_bf16 v[28:31], v[80:83], v[188:191], v[28:31]
	v_mfma_f32_16x16x32_bf16 v[24:27], v[92:95], v[188:191], v[24:27]
	v_mfma_f32_16x16x32_bf16 v[20:23], v[80:83], v[196:199], v[20:23]
	v_mfma_f32_16x16x32_bf16 v[12:15], v[92:95], v[196:199], v[12:15]
	v_mfma_f32_16x16x32_bf16 v[60:63], v[84:87], v[170:173], v[60:63]
	v_mfma_f32_16x16x32_bf16 v[56:59], v[100:103], v[170:173], v[56:59]
	v_mfma_f32_16x16x32_bf16 v[44:47], v[84:87], v[184:187], v[44:47]
	v_mfma_f32_16x16x32_bf16 v[40:43], v[100:103], v[184:187], v[40:43]
	v_mfma_f32_16x16x32_bf16 v[28:31], v[84:87], v[192:195], v[28:31]
	v_mfma_f32_16x16x32_bf16 v[24:27], v[100:103], v[192:195], v[24:27]
	v_mfma_f32_16x16x32_bf16 v[20:23], v[84:87], v[200:203], v[20:23]
	v_mfma_f32_16x16x32_bf16 v[12:15], v[100:103], v[200:203], v[12:15]
	s_setprio 0
	s_barrier
	s_add_u32 s8, s12, 0xb0000
	s_addc_u32 s9, s13, 0
	s_add_i32 s47, s41, s24
	v_lshl_add_u64 v[80:81], s[8:9], 0, v[144:145]
	s_mov_b32 m0, s47
	s_nop 0
	global_load_lds_dwordx4 v[80:81], off
	v_lshl_add_u64 v[80:81], s[8:9], 0, v[146:147]
	s_add_i32 m0, s47, 0x2000
	s_nop 0
	global_load_lds_dwordx4 v[80:81], off
	s_waitcnt vmcnt(6)
	s_barrier
	s_setprio 1
	v_mfma_f32_16x16x32_bf16 v[52:55], v[204:207], v[156:159], v[52:55]
	v_mfma_f32_16x16x32_bf16 v[48:51], v[212:215], v[156:159], v[48:51]
	v_mfma_f32_16x16x32_bf16 v[36:39], v[204:207], v[180:183], v[36:39]
	v_mfma_f32_16x16x32_bf16 v[32:35], v[212:215], v[180:183], v[32:35]
	v_mfma_f32_16x16x32_bf16 v[16:19], v[204:207], v[188:191], v[16:19]
	v_mfma_f32_16x16x32_bf16 v[8:11], v[212:215], v[188:191], v[8:11]
	v_mfma_f32_16x16x32_bf16 v[4:7], v[204:207], v[196:199], v[4:7]
	v_mfma_f32_16x16x32_bf16 v[0:3], v[212:215], v[196:199], v[0:3]
	v_mfma_f32_16x16x32_bf16 v[52:55], v[208:211], v[170:173], v[52:55]
	v_mfma_f32_16x16x32_bf16 v[48:51], v[216:219], v[170:173], v[48:51]
	v_mfma_f32_16x16x32_bf16 v[36:39], v[208:211], v[184:187], v[36:39]
	v_mfma_f32_16x16x32_bf16 v[32:35], v[216:219], v[184:187], v[32:35]
	v_mfma_f32_16x16x32_bf16 v[16:19], v[208:211], v[192:195], v[16:19]
	v_mfma_f32_16x16x32_bf16 v[8:11], v[216:219], v[192:195], v[8:11]
	v_mfma_f32_16x16x32_bf16 v[4:7], v[208:211], v[200:203], v[4:7]
	v_mfma_f32_16x16x32_bf16 v[0:3], v[216:219], v[200:203], v[0:3]
	s_setprio 0
	s_add_i32 s47, 0, 0x18000
	v_add_u32_e32 v100, s47, v165
	s_barrier
	ds_read_b128 v[80:83], v100
	ds_read_b128 v[84:87], v100 offset:1024
	ds_read_b128 v[92:95], v100 offset:2048
	ds_read_b128 v[100:103], v100 offset:3072
	s_add_u32 s8, s14, 0xb0000
	s_addc_u32 s9, s15, 0
	s_mov_b32 m0, s27
	v_lshl_add_u64 v[204:205], s[8:9], 0, v[144:145]
	ds_read_b128 v[156:159], v168 offset:32768
	ds_read_b128 v[170:173], v168 offset:33792
	ds_read_b128 v[180:183], v168 offset:34816
	ds_read_b128 v[184:187], v168 offset:35840
	ds_read_b128 v[188:191], v168 offset:36864
	ds_read_b128 v[192:195], v168 offset:37888
	ds_read_b128 v[196:199], v168 offset:38912
	ds_read_b128 v[200:203], v168 offset:39936
	global_load_lds_dwordx4 v[204:205], off
	v_lshl_add_u64 v[204:205], s[8:9], 0, v[146:147]
	s_mov_b32 m0, s28
	s_nop 0
	global_load_lds_dwordx4 v[204:205], off
	s_waitcnt lgkmcnt(8)
	s_barrier
	s_waitcnt lgkmcnt(0)
	s_setprio 1
	s_waitcnt lgkmcnt(0)
	v_mfma_f32_16x16x32_bf16 v[140:143], v[80:83], v[156:159], v[140:143]
	v_mfma_f32_16x16x32_bf16 v[136:139], v[92:95], v[156:159], v[136:139]
	v_mfma_f32_16x16x32_bf16 v[124:127], v[80:83], v[180:183], v[124:127]
	v_mfma_f32_16x16x32_bf16 v[120:123], v[92:95], v[180:183], v[120:123]
	v_mfma_f32_16x16x32_bf16 v[108:111], v[80:83], v[188:191], v[108:111]
	v_mfma_f32_16x16x32_bf16 v[104:107], v[92:95], v[188:191], v[104:107]
	v_mfma_f32_16x16x32_bf16 v[76:79], v[80:83], v[196:199], v[76:79]
	v_mfma_f32_16x16x32_bf16 v[72:75], v[92:95], v[196:199], v[72:75]
	v_mfma_f32_16x16x32_bf16 v[140:143], v[84:87], v[170:173], v[140:143]
	v_mfma_f32_16x16x32_bf16 v[136:139], v[100:103], v[170:173], v[136:139]
	v_mfma_f32_16x16x32_bf16 v[124:127], v[84:87], v[184:187], v[124:127]
	v_mfma_f32_16x16x32_bf16 v[120:123], v[100:103], v[184:187], v[120:123]
	v_mfma_f32_16x16x32_bf16 v[108:111], v[84:87], v[192:195], v[108:111]
	v_mfma_f32_16x16x32_bf16 v[104:107], v[100:103], v[192:195], v[104:107]
	v_mfma_f32_16x16x32_bf16 v[76:79], v[84:87], v[200:203], v[76:79]
	v_mfma_f32_16x16x32_bf16 v[72:75], v[100:103], v[200:203], v[72:75]
	s_setprio 0
	s_barrier
	s_add_i32 s14, 0, 0x1c000
	s_add_i32 s8, s47, s24
	v_add_u32_e32 v176, s14, v165
	v_lshl_add_u64 v[174:175], v[174:175], 0, s[4:5]
	s_mov_b32 m0, s8
	ds_read_b128 v[204:207], v176
	ds_read_b128 v[208:211], v176 offset:1024
	ds_read_b128 v[212:215], v176 offset:2048
	ds_read_b128 v[216:219], v176 offset:3072
	global_load_lds_dwordx4 v[174:175], off
	v_lshl_add_u64 v[174:175], v[220:221], 0, s[4:5]
	s_add_i32 m0, s8, 0x2000
	s_nop 0
	global_load_lds_dwordx4 v[174:175], off
	s_barrier
	s_waitcnt lgkmcnt(0)
	s_setprio 1
	s_waitcnt lgkmcnt(0)
	v_mfma_f32_16x16x32_bf16 v[132:135], v[204:207], v[156:159], v[132:135]
	v_mfma_f32_16x16x32_bf16 v[128:131], v[212:215], v[156:159], v[128:131]
	v_mfma_f32_16x16x32_bf16 v[116:119], v[204:207], v[180:183], v[116:119]
	v_mfma_f32_16x16x32_bf16 v[112:115], v[212:215], v[180:183], v[112:115]
	v_mfma_f32_16x16x32_bf16 v[96:99], v[204:207], v[188:191], v[96:99]
	v_mfma_f32_16x16x32_bf16 v[88:91], v[212:215], v[188:191], v[88:91]
	v_mfma_f32_16x16x32_bf16 v[68:71], v[204:207], v[196:199], v[68:71]
	v_mfma_f32_16x16x32_bf16 v[64:67], v[212:215], v[196:199], v[64:67]
	v_mfma_f32_16x16x32_bf16 v[132:135], v[208:211], v[170:173], v[132:135]
	v_mfma_f32_16x16x32_bf16 v[128:131], v[216:219], v[170:173], v[128:131]
	v_mfma_f32_16x16x32_bf16 v[116:119], v[208:211], v[184:187], v[116:119]
	v_mfma_f32_16x16x32_bf16 v[112:115], v[216:219], v[184:187], v[112:115]
	v_mfma_f32_16x16x32_bf16 v[96:99], v[208:211], v[192:195], v[96:99]
	v_mfma_f32_16x16x32_bf16 v[88:91], v[216:219], v[192:195], v[88:91]
	v_mfma_f32_16x16x32_bf16 v[68:71], v[208:211], v[200:203], v[68:71]
	v_mfma_f32_16x16x32_bf16 v[64:67], v[216:219], v[200:203], v[64:67]
	s_setprio 0
	s_mov_b32 m0, s33
	v_lshl_add_u64 v[174:175], v[222:223], 0, s[4:5]
	s_barrier
	ds_read_b128 v[156:159], v168 offset:49152
	ds_read_b128 v[170:173], v168 offset:50176
	ds_read_b128 v[180:183], v168 offset:51200
	ds_read_b128 v[184:187], v168 offset:52224
	ds_read_b128 v[188:191], v168 offset:53248
	ds_read_b128 v[192:195], v168 offset:54272
	ds_read_b128 v[196:199], v168 offset:55296
	ds_read_b128 v[200:203], v168 offset:56320
	global_load_lds_dwordx4 v[174:175], off
	v_lshl_add_u64 v[174:175], v[224:225], 0, s[4:5]
	s_mov_b32 m0, s34
	s_nop 0
	global_load_lds_dwordx4 v[174:175], off
	s_barrier
	s_waitcnt lgkmcnt(0)
	s_setprio 1
	s_waitcnt lgkmcnt(0)
	v_mfma_f32_16x16x32_bf16 v[60:63], v[80:83], v[156:159], v[60:63]
	v_mfma_f32_16x16x32_bf16 v[56:59], v[92:95], v[156:159], v[56:59]
	v_mfma_f32_16x16x32_bf16 v[44:47], v[80:83], v[180:183], v[44:47]
	v_mfma_f32_16x16x32_bf16 v[40:43], v[92:95], v[180:183], v[40:43]
	v_mfma_f32_16x16x32_bf16 v[28:31], v[80:83], v[188:191], v[28:31]
	v_mfma_f32_16x16x32_bf16 v[24:27], v[92:95], v[188:191], v[24:27]
	v_mfma_f32_16x16x32_bf16 v[20:23], v[80:83], v[196:199], v[20:23]
	v_mfma_f32_16x16x32_bf16 v[12:15], v[92:95], v[196:199], v[12:15]
	v_mfma_f32_16x16x32_bf16 v[60:63], v[84:87], v[170:173], v[60:63]
	v_mfma_f32_16x16x32_bf16 v[56:59], v[100:103], v[170:173], v[56:59]
	v_mfma_f32_16x16x32_bf16 v[44:47], v[84:87], v[184:187], v[44:47]
	v_mfma_f32_16x16x32_bf16 v[40:43], v[100:103], v[184:187], v[40:43]
	v_mfma_f32_16x16x32_bf16 v[28:31], v[84:87], v[192:195], v[28:31]
	v_mfma_f32_16x16x32_bf16 v[24:27], v[100:103], v[192:195], v[24:27]
	v_mfma_f32_16x16x32_bf16 v[20:23], v[84:87], v[200:203], v[20:23]
	v_mfma_f32_16x16x32_bf16 v[12:15], v[100:103], v[200:203], v[12:15]
	s_setprio 0
	s_barrier
	s_add_u32 s8, s12, 0xb0080
	s_addc_u32 s9, s13, 0
	s_add_i32 s12, s14, s24
	v_lshl_add_u64 v[80:81], s[8:9], 0, v[144:145]
	s_mov_b32 m0, s12
	s_nop 0
	global_load_lds_dwordx4 v[80:81], off
	v_lshl_add_u64 v[80:81], s[8:9], 0, v[146:147]
	s_add_i32 m0, s12, 0x2000
	s_nop 0
	global_load_lds_dwordx4 v[80:81], off
	s_waitcnt vmcnt(6)
	s_barrier
	s_setprio 1
	v_mfma_f32_16x16x32_bf16 v[52:55], v[204:207], v[156:159], v[52:55]
	v_mfma_f32_16x16x32_bf16 v[48:51], v[212:215], v[156:159], v[48:51]
	v_mfma_f32_16x16x32_bf16 v[36:39], v[204:207], v[180:183], v[36:39]
	v_mfma_f32_16x16x32_bf16 v[32:35], v[212:215], v[180:183], v[32:35]
	v_mfma_f32_16x16x32_bf16 v[16:19], v[204:207], v[188:191], v[16:19]
	v_mfma_f32_16x16x32_bf16 v[8:11], v[212:215], v[188:191], v[8:11]
	v_mfma_f32_16x16x32_bf16 v[4:7], v[204:207], v[196:199], v[4:7]
	v_mfma_f32_16x16x32_bf16 v[0:3], v[212:215], v[196:199], v[0:3]
	v_mfma_f32_16x16x32_bf16 v[52:55], v[208:211], v[170:173], v[52:55]
	v_mfma_f32_16x16x32_bf16 v[48:51], v[216:219], v[170:173], v[48:51]
	v_mfma_f32_16x16x32_bf16 v[36:39], v[208:211], v[184:187], v[36:39]
	v_mfma_f32_16x16x32_bf16 v[32:35], v[216:219], v[184:187], v[32:35]
	v_mfma_f32_16x16x32_bf16 v[16:19], v[208:211], v[192:195], v[16:19]
	v_mfma_f32_16x16x32_bf16 v[8:11], v[216:219], v[192:195], v[8:11]
	v_mfma_f32_16x16x32_bf16 v[4:7], v[208:211], v[200:203], v[4:7]
	v_mfma_f32_16x16x32_bf16 v[0:3], v[216:219], v[200:203], v[0:3]
	s_setprio 0
	s_add_i32 s46, s46, 2
	s_add_u32 s38, s38, 0x100
	s_addc_u32 s39, s39, 0
	s_cmp_gt_u32 s46, 41
	s_mov_b64 s[8:9], s[10:11]
	s_barrier
	s_cbranch_scc0 .LBB0_1514
	s_lshl_b32 s10, s44, 8
	s_add_i32 s8, s10, 0xffffe000
	s_lshr_b32 s8, s8, 12
	s_add_i32 s8, s8, 1
	v_lshl_or_b32 v80, s45, 8, v166
	s_cmp_gt_i32 s44, 31
	v_readlane_b32 s44, v252, 51
	s_cselect_b32 s8, s8, 0
	v_add_u32_e32 v158, s10, v164
	v_readlane_b32 s56, v252, 63
	v_readlane_b32 s57, v253, 0
	s_mul_hi_u32 s9, s8, 0x6000
	s_mulk_i32 s8, 0x6000
	v_ashrrev_i32_e32 v159, 31, v158
	v_readlane_b32 s58, v253, 1
	v_readlane_b32 s59, v253, 2
	s_mov_b64 s[12:13], s[56:57]
	s_add_u32 s8, s30, s8
	v_ashrrev_i32_e32 v81, 31, v80
	v_lshlrev_b64 v[170:171], 12, v[158:159]
	s_mov_b64 s[14:15], s[58:59]
	s_addc_u32 s9, s31, s9
	v_lshlrev_b64 v[156:157], 2, v[80:81]
	v_lshl_add_u64 v[170:171], s[14:15], 0, v[170:171]
	v_lshl_add_u64 v[80:81], s[8:9], 0, v[156:157]
	v_lshl_add_u64 v[174:175], v[170:171], 0, v[156:157]
	global_load_dwordx4 v[100:103], v[80:81], off
	global_load_dwordx4 v[92:95], v[80:81], off offset:64
	global_load_dwordx4 v[84:87], v[80:81], off offset:512
	s_nop 0
	global_load_dwordx4 v[80:83], v[80:81], off offset:576
	s_nop 0
	global_load_dwordx4 v[170:173], v[174:175], off
	global_load_dwordx4 v[180:183], v[174:175], off offset:64
	global_load_dwordx4 v[184:187], v[174:175], off offset:512
	global_load_dwordx4 v[188:191], v[174:175], off offset:576
	v_or_b32_e32 v192, 16, v158
	v_ashrrev_i32_e32 v193, 31, v192
	v_lshlrev_b64 v[192:193], 12, v[192:193]
	v_lshl_add_u64 v[192:193], s[14:15], 0, v[192:193]
	v_lshl_add_u64 v[208:209], v[192:193], 0, v[156:157]
	global_load_dwordx4 v[192:195], v[208:209], off
	global_load_dwordx4 v[196:199], v[208:209], off offset:64
	global_load_dwordx4 v[200:203], v[208:209], off offset:512
	global_load_dwordx4 v[204:207], v[208:209], off offset:576
	v_readlane_b32 s45, v252, 52
	s_and_b64 vcc, exec, s[36:37]
	s_mov_b32 s45, s42
	s_mov_b32 s44, s43
	s_mov_b64 s[10:11], s[6:7]
	s_mov_b64 s[8:9], s[0:1]
	v_readlane_b32 s46, v252, 53
	v_readlane_b32 s47, v252, 54
	v_readlane_b32 s48, v252, 55
	v_readlane_b32 s49, v252, 56
	v_readlane_b32 s50, v252, 57
	v_readlane_b32 s51, v252, 58
	v_readlane_b32 s52, v252, 59
	v_readlane_b32 s53, v252, 60
	v_readlane_b32 s54, v252, 61
	v_readlane_b32 s55, v252, 62
	s_waitcnt vmcnt(0)
	v_pk_fma_f32 v[142:143], v[142:143], v[102:103], v[172:173]
	v_pk_fma_f32 v[140:141], v[140:141], v[100:101], v[170:171]
	v_pk_fma_f32 v[138:139], v[138:139], v[94:95], v[182:183]
	v_pk_fma_f32 v[130:131], v[130:131], v[82:83], v[190:191]
	v_pk_fma_f32 v[128:129], v[128:129], v[80:81], v[188:189]
	global_store_dwordx4 v[174:175], v[128:131], off offset:576 sc1
	v_pk_fma_f32 v[136:137], v[136:137], v[92:93], v[180:181]
	v_pk_fma_f32 v[134:135], v[134:135], v[86:87], v[186:187]
	v_or_b32_e32 v128, 32, v158
	v_ashrrev_i32_e32 v129, 31, v128
	v_lshlrev_b64 v[128:129], 12, v[128:129]
	v_pk_fma_f32 v[132:133], v[132:133], v[84:85], v[184:185]
	v_lshl_add_u64 v[128:129], s[14:15], 0, v[128:129]
	global_store_dwordx4 v[174:175], v[140:143], off sc1
	global_store_dwordx4 v[174:175], v[136:139], off offset:64 sc1
	global_store_dwordx4 v[174:175], v[132:135], off offset:512 sc1
	v_lshl_add_u64 v[170:171], v[128:129], 0, v[156:157]
	v_pk_fma_f32 v[114:115], v[114:115], v[82:83], v[206:207]
	v_pk_fma_f32 v[112:113], v[112:113], v[80:81], v[204:205]
	global_load_dwordx4 v[128:131], v[170:171], off
	global_load_dwordx4 v[132:135], v[170:171], off offset:64
	global_load_dwordx4 v[136:139], v[170:171], off offset:512
	global_load_dwordx4 v[140:143], v[170:171], off offset:576
	v_pk_fma_f32 v[126:127], v[126:127], v[102:103], v[194:195]
	global_store_dwordx4 v[208:209], v[112:115], off offset:576 sc1
	v_pk_fma_f32 v[124:125], v[124:125], v[100:101], v[192:193]
	v_pk_fma_f32 v[122:123], v[122:123], v[94:95], v[198:199]
	v_or_b32_e32 v112, 48, v158
	v_ashrrev_i32_e32 v113, 31, v112
	v_lshlrev_b64 v[112:113], 12, v[112:113]
	v_pk_fma_f32 v[120:121], v[120:121], v[92:93], v[196:197]
	v_pk_fma_f32 v[118:119], v[118:119], v[86:87], v[202:203]
	v_pk_fma_f32 v[116:117], v[116:117], v[84:85], v[200:201]
	v_lshl_add_u64 v[112:113], s[14:15], 0, v[112:113]
	global_store_dwordx4 v[208:209], v[124:127], off sc1
	global_store_dwordx4 v[208:209], v[120:123], off offset:64 sc1
	global_store_dwordx4 v[208:209], v[116:119], off offset:512 sc1
	v_lshl_add_u64 v[172:173], v[112:113], 0, v[156:157]
	global_load_dwordx4 v[112:115], v[172:173], off
	global_load_dwordx4 v[116:119], v[172:173], off offset:64
	global_load_dwordx4 v[120:123], v[172:173], off offset:512
	global_load_dwordx4 v[124:127], v[172:173], off offset:576
	s_waitcnt vmcnt(0)
	v_pk_fma_f32 v[110:111], v[110:111], v[102:103], v[130:131]
	v_pk_fma_f32 v[108:109], v[108:109], v[100:101], v[128:129]
	v_pk_fma_f32 v[106:107], v[106:107], v[94:95], v[134:135]
	v_pk_fma_f32 v[90:91], v[90:91], v[82:83], v[142:143]
	v_pk_fma_f32 v[88:89], v[88:89], v[80:81], v[140:141]
	global_store_dwordx4 v[170:171], v[88:91], off offset:576 sc1
	v_pk_fma_f32 v[104:105], v[104:105], v[92:93], v[132:133]
	v_pk_fma_f32 v[98:99], v[98:99], v[86:87], v[138:139]
	v_add_u32_e32 v88, 0x80, v158
	v_ashrrev_i32_e32 v89, 31, v88
	v_lshlrev_b64 v[88:89], 12, v[88:89]
	v_pk_fma_f32 v[96:97], v[96:97], v[84:85], v[136:137]
	v_lshl_add_u64 v[88:89], s[14:15], 0, v[88:89]
	global_store_dwordx4 v[170:171], v[108:111], off sc1
	global_store_dwordx4 v[170:171], v[104:107], off offset:64 sc1
	global_store_dwordx4 v[170:171], v[96:99], off offset:512 sc1
	v_lshl_add_u64 v[128:129], v[88:89], 0, v[156:157]
	global_load_dwordx4 v[88:91], v[128:129], off
	global_load_dwordx4 v[96:99], v[128:129], off offset:64
	global_load_dwordx4 v[104:107], v[128:129], off offset:512
	global_load_dwordx4 v[108:111], v[128:129], off offset:576
	v_pk_fma_f32 v[78:79], v[78:79], v[102:103], v[114:115]
	v_pk_fma_f32 v[66:67], v[66:67], v[82:83], v[126:127]
	v_pk_fma_f32 v[64:65], v[64:65], v[80:81], v[124:125]
	global_store_dwordx4 v[172:173], v[64:67], off offset:576 sc1
	v_pk_fma_f32 v[76:77], v[76:77], v[100:101], v[112:113]
	v_pk_fma_f32 v[74:75], v[74:75], v[94:95], v[118:119]
	v_add_u32_e32 v64, 0x90, v158
	v_ashrrev_i32_e32 v65, 31, v64
	v_lshlrev_b64 v[64:65], 12, v[64:65]
	v_pk_fma_f32 v[72:73], v[72:73], v[92:93], v[116:117]
	v_pk_fma_f32 v[70:71], v[70:71], v[86:87], v[122:123]
	v_pk_fma_f32 v[68:69], v[68:69], v[84:85], v[120:121]
	v_lshl_add_u64 v[64:65], s[14:15], 0, v[64:65]
	global_store_dwordx4 v[172:173], v[76:79], off sc1
	global_store_dwordx4 v[172:173], v[72:75], off offset:64 sc1
	global_store_dwordx4 v[172:173], v[68:71], off offset:512 sc1
	v_lshl_add_u64 v[78:79], v[64:65], 0, v[156:157]
	global_load_dwordx4 v[66:69], v[78:79], off
	global_load_dwordx4 v[70:73], v[78:79], off offset:64
	global_load_dwordx4 v[74:77], v[78:79], off offset:512
	global_load_dwordx4 v[112:115], v[78:79], off offset:576
	s_waitcnt vmcnt(0)
	v_pk_fma_f32 v[62:63], v[62:63], v[102:103], v[90:91]
	v_pk_fma_f32 v[60:61], v[60:61], v[100:101], v[88:89]
	v_pk_fma_f32 v[58:59], v[58:59], v[94:95], v[98:99]
	v_pk_fma_f32 v[50:51], v[50:51], v[82:83], v[110:111]
	v_pk_fma_f32 v[48:49], v[48:49], v[80:81], v[108:109]
	global_store_dwordx4 v[128:129], v[48:51], off offset:576 sc1
	v_pk_fma_f32 v[56:57], v[56:57], v[92:93], v[96:97]
	v_pk_fma_f32 v[54:55], v[54:55], v[86:87], v[106:107]
	v_add_u32_e32 v48, 0xa0, v158
	v_ashrrev_i32_e32 v49, 31, v48
	v_lshlrev_b64 v[48:49], 12, v[48:49]
	v_pk_fma_f32 v[52:53], v[52:53], v[84:85], v[104:105]
	v_lshl_add_u64 v[48:49], s[14:15], 0, v[48:49]
	global_store_dwordx4 v[128:129], v[60:63], off sc1
	global_store_dwordx4 v[128:129], v[56:59], off offset:64 sc1
	global_store_dwordx4 v[128:129], v[52:55], off offset:512 sc1
	v_lshl_add_u64 v[64:65], v[48:49], 0, v[156:157]
	global_load_dwordx4 v[60:63], v[64:65], off
	global_load_dwordx4 v[56:59], v[64:65], off offset:64
	global_load_dwordx4 v[52:55], v[64:65], off offset:512
	global_load_dwordx4 v[48:51], v[64:65], off offset:576
	v_pk_fma_f32 v[46:47], v[46:47], v[102:103], v[68:69]
	v_pk_fma_f32 v[44:45], v[44:45], v[100:101], v[66:67]
	v_pk_fma_f32 v[42:43], v[42:43], v[94:95], v[72:73]
	v_pk_fma_f32 v[34:35], v[34:35], v[82:83], v[114:115]
	v_pk_fma_f32 v[32:33], v[32:33], v[80:81], v[112:113]
	global_store_dwordx4 v[78:79], v[32:35], off offset:576 sc1
	v_pk_fma_f32 v[40:41], v[40:41], v[92:93], v[70:71]
	v_pk_fma_f32 v[38:39], v[38:39], v[86:87], v[76:77]
	v_add_u32_e32 v32, 0xb0, v158
	v_ashrrev_i32_e32 v33, 31, v32
	v_lshlrev_b64 v[32:33], 12, v[32:33]
	v_pk_fma_f32 v[36:37], v[36:37], v[84:85], v[74:75]
	v_lshl_add_u64 v[32:33], s[14:15], 0, v[32:33]
	global_store_dwordx4 v[78:79], v[44:47], off sc1
	global_store_dwordx4 v[78:79], v[40:43], off offset:64 sc1
	global_store_dwordx4 v[78:79], v[36:39], off offset:512 sc1
	s_waitcnt vmcnt(0)
	v_pk_fma_f32 v[30:31], v[30:31], v[102:103], v[62:63]
	v_lshl_add_u64 v[36:37], v[32:33], 0, v[156:157]
	global_load_dwordx4 v[38:41], v[36:37], off
	global_load_dwordx4 v[42:45], v[36:37], off offset:64
	global_load_dwordx4 v[66:69], v[36:37], off offset:512
	global_load_dwordx4 v[32:35], v[36:37], off offset:576
	v_pk_fma_f32 v[10:11], v[10:11], v[82:83], v[50:51]
	v_pk_fma_f32 v[8:9], v[8:9], v[80:81], v[48:49]
	global_store_dwordx4 v[64:65], v[8:11], off offset:576 sc1
	v_pk_fma_f32 v[28:29], v[28:29], v[100:101], v[60:61]
	v_pk_fma_f32 v[26:27], v[26:27], v[94:95], v[58:59]
	v_pk_fma_f32 v[24:25], v[24:25], v[92:93], v[56:57]
	v_pk_fma_f32 v[18:19], v[18:19], v[86:87], v[54:55]
	v_pk_fma_f32 v[16:17], v[16:17], v[84:85], v[52:53]
	global_store_dwordx4 v[64:65], v[28:31], off sc1
	global_store_dwordx4 v[64:65], v[24:27], off offset:64 sc1
	global_store_dwordx4 v[64:65], v[16:19], off offset:512 sc1
	s_waitcnt vmcnt(0)
	v_pk_fma_f32 v[10:11], v[22:23], v[102:103], v[40:41]
	v_pk_fma_f32 v[8:9], v[20:21], v[100:101], v[38:39]
	global_store_dwordx4 v[36:37], v[8:11], off sc1
	v_pk_fma_f32 v[6:7], v[6:7], v[86:87], v[68:69]
	v_pk_fma_f32 v[4:5], v[4:5], v[84:85], v[66:67]
	v_pk_fma_f32 v[10:11], v[14:15], v[94:95], v[44:45]
	v_pk_fma_f32 v[8:9], v[12:13], v[92:93], v[42:43]
	v_pk_fma_f32 v[2:3], v[2:3], v[82:83], v[34:35]
	v_pk_fma_f32 v[0:1], v[0:1], v[80:81], v[32:33]
	global_store_dwordx4 v[36:37], v[8:11], off offset:64 sc1
	global_store_dwordx4 v[36:37], v[4:7], off offset:512 sc1
	global_store_dwordx4 v[36:37], v[0:3], off offset:576 sc1
	s_cbranch_vccz .LBB0_1503
	s_waitcnt vmcnt(0)
	s_cmpk_gt_u32 s16, 0xff
	s_cbranch_scc1 .LBB0_1518
	s_barrier

.LBB0_1569:
	v_ashrrev_i32_e32 v29, 31, v28
	v_lshlrev_b64 v[0:1], 12, v[28:29]
	v_lshl_add_u64 v[56:57], v[46:47], 0, v[0:1]
	v_add_u32_e32 v50, s20, v28
	global_load_dwordx4 v[32:35], v[56:57], off
	global_load_dwordx4 v[24:27], v[56:57], off offset:1024
	global_load_dwordx4 v[20:23], v[56:57], off offset:2048
	global_load_dwordx4 v[16:19], v[56:57], off offset:3072
	v_ashrrev_i32_e32 v51, 31, v50
	v_lshlrev_b64 v[0:1], 12, v[50:51]
	v_lshl_add_u64 v[52:53], v[46:47], 0, v[0:1]
	global_load_dwordx4 v[12:15], v[52:53], off
	global_load_dwordx4 v[8:11], v[52:53], off offset:1024
	global_load_dwordx4 v[4:7], v[52:53], off offset:2048
	global_load_dwordx4 v[0:3], v[52:53], off offset:3072
	global_load_dwordx4 v[66:69], v[44:45], off
	s_waitcnt vmcnt(8)
	v_mov_b32_e32 v36, v33
	s_waitcnt vmcnt(7)
	v_mov_b32_e32 v37, v25
	s_waitcnt vmcnt(6)
	v_mov_b32_e32 v54, v21
	s_waitcnt vmcnt(5)
	v_mov_b32_e32 v55, v17
	v_mov_b32_e32 v30, v32
	v_mov_b32_e32 v31, v24
	v_mov_b32_e32 v42, v20
	v_mov_b32_e32 v43, v16
	v_pk_mul_f32 v[36:37], v[36:37], v[36:37]
	v_pk_mul_f32 v[54:55], v[54:55], v[54:55]
	s_waitcnt vmcnt(4)
	v_mov_b32_e32 v74, v13
	s_waitcnt vmcnt(3)
	v_mov_b32_e32 v75, v9
	v_mov_b32_e32 v38, v34
	v_mov_b32_e32 v39, v26
	v_mov_b32_e32 v72, v12
	v_mov_b32_e32 v73, v8
	s_waitcnt vmcnt(2)
	v_mov_b32_e32 v82, v5
	s_waitcnt vmcnt(1)
	v_mov_b32_e32 v83, v1
	v_pk_fma_f32 v[30:31], v[30:31], v[30:31], v[36:37]
	v_pk_fma_f32 v[36:37], v[42:43], v[42:43], v[54:55]
	v_pk_mul_f32 v[42:43], v[74:75], v[74:75]
	v_mov_b32_e32 v76, v14
	v_mov_b32_e32 v77, v10
	v_mov_b32_e32 v80, v4
	v_mov_b32_e32 v81, v0
	v_pk_mul_f32 v[54:55], v[82:83], v[82:83]
	v_pk_fma_f32 v[30:31], v[38:39], v[38:39], v[30:31]
	v_pk_fma_f32 v[38:39], v[72:73], v[72:73], v[42:43]
	v_mov_b32_e32 v40, v35
	v_mov_b32_e32 v41, v27
	v_mov_b32_e32 v58, v22
	v_mov_b32_e32 v59, v18
	v_mov_b32_e32 v78, v15
	v_mov_b32_e32 v79, v11
	v_mov_b32_e32 v84, v6
	v_mov_b32_e32 v85, v2
	v_pk_fma_f32 v[42:43], v[80:81], v[80:81], v[54:55]
	v_pk_fma_f32 v[38:39], v[76:77], v[76:77], v[38:39]
	v_mov_b32_e32 v70, v23
	v_mov_b32_e32 v71, v19
	v_mov_b32_e32 v86, v7
	v_mov_b32_e32 v87, v3
	v_pk_fma_f32 v[36:37], v[58:59], v[58:59], v[36:37]
	v_pk_fma_f32 v[30:31], v[40:41], v[40:41], v[30:31]
	v_pk_fma_f32 v[40:41], v[84:85], v[84:85], v[42:43]
	v_pk_fma_f32 v[38:39], v[78:79], v[78:79], v[38:39]
	v_pk_fma_f32 v[36:37], v[70:71], v[70:71], v[36:37]
	v_pk_fma_f32 v[40:41], v[86:87], v[86:87], v[40:41]
	v_mov_b32_e32 v43, v30
	v_mov_b32_e32 v42, v38
	v_mov_b32_e32 v30, v39
	v_mov_b32_e32 v55, v36
	v_mov_b32_e32 v54, v40
	v_pk_add_f32 v[30:31], v[42:43], v[30:31]
	v_mov_b32_e32 v36, v41
	v_pk_add_f32 v[30:31], v[30:31], v[54:55]
	v_add_u32_e32 v38, s3, v28
	v_pk_add_f32 v[30:31], v[30:31], v[36:37]
	ds_bpermute_b32 v37, v60, v31
	ds_bpermute_b32 v36, v60, v30
	v_add_u32_e32 v28, s22, v28
	v_ashrrev_i32_e32 v29, 31, v28
	v_lshlrev_b64 v[28:29], 12, v[28:29]
	v_lshl_add_u64 v[54:55], v[46:47], 0, v[28:29]
	s_waitcnt lgkmcnt(0)
	v_pk_add_f32 v[30:31], v[30:31], v[36:37]
	ds_bpermute_b32 v37, v61, v31
	ds_bpermute_b32 v36, v61, v30
	v_ashrrev_i32_e32 v39, 31, v38
	v_lshlrev_b64 v[38:39], 12, v[38:39]
	v_lshl_add_u64 v[58:59], v[46:47], 0, v[38:39]
	s_waitcnt lgkmcnt(0)
	v_pk_add_f32 v[30:31], v[30:31], v[36:37]
	ds_bpermute_b32 v37, v62, v31
	ds_bpermute_b32 v36, v62, v30
	s_waitcnt lgkmcnt(0)
	v_pk_add_f32 v[30:31], v[30:31], v[36:37]
	ds_bpermute_b32 v37, v63, v31
	ds_bpermute_b32 v36, v63, v30
	s_waitcnt lgkmcnt(0)
	v_pk_add_f32 v[30:31], v[30:31], v[36:37]
	ds_bpermute_b32 v37, v64, v31
	ds_bpermute_b32 v36, v64, v30
	s_waitcnt lgkmcnt(0)
	v_pk_add_f32 v[30:31], v[30:31], v[36:37]
	ds_bpermute_b32 v37, v65, v31
	ds_bpermute_b32 v36, v65, v30
	s_waitcnt lgkmcnt(0)
	v_pk_add_f32 v[28:29], v[30:31], v[36:37]
	s_nop 0
	v_pk_fma_f32 v[82:83], v[28:29], s[2:3], v[48:49] op_sel_hi:[1,0,0]
	s_nop 0
	v_mul_f32_e32 v28, 0x4b800000, v83
	v_cmp_gt_f32_e32 vcc, s4, v83
	s_nop 1
	v_cndmask_b32_e32 v28, v83, v28, vcc
	v_rsq_f32_e32 v51, v28
	global_load_dwordx4 v[70:73], v[58:59], off
	global_load_dwordx4 v[40:43], v[58:59], off offset:1024
	global_load_dwordx4 v[36:39], v[54:55], off
	global_load_dwordx4 v[28:31], v[54:55], off offset:1024
	v_mul_f32_e32 v74, 0x45800000, v51
	v_cndmask_b32_e32 v84, v51, v74, vcc
	v_pk_mul_f32 v[32:33], v[32:33], v[84:85] op_sel_hi:[1,0]
	v_pk_mul_f32 v[34:35], v[34:35], v[84:85] op_sel_hi:[1,0]
	s_waitcnt vmcnt(4)
	v_pk_mul_f32 v[32:33], v[66:67], v[32:33]
	v_pk_mul_f32 v[34:35], v[68:69], v[34:35]
	global_store_dwordx4 v[56:57], v[32:35], off sc1
	global_load_dwordx4 v[32:35], v[44:45], off offset:1024
	v_pk_mul_f32 v[26:27], v[26:27], v[84:85] op_sel_hi:[1,0]
	v_pk_mul_f32 v[24:25], v[24:25], v[84:85] op_sel_hi:[1,0]
	v_pk_mul_f32 v[22:23], v[22:23], v[84:85] op_sel_hi:[1,0]
	v_pk_mul_f32 v[20:21], v[20:21], v[84:85] op_sel_hi:[1,0]
	v_pk_mul_f32 v[18:19], v[18:19], v[84:85] op_sel_hi:[1,0]
	v_pk_mul_f32 v[16:17], v[16:17], v[84:85] op_sel_hi:[1,0]
	v_cmp_gt_f32_e32 vcc, s4, v82
	s_waitcnt vmcnt(3)
	v_mov_b32_e32 v84, v39
	s_waitcnt vmcnt(2)
	v_mov_b32_e32 v83, v30
	v_mov_b32_e32 v85, v31
	s_waitcnt vmcnt(0)
	v_pk_mul_f32 v[24:25], v[32:33], v[24:25]
	v_pk_mul_f32 v[26:27], v[34:35], v[26:27]
	global_store_dwordx4 v[56:57], v[24:27], off offset:1024 sc1
	global_load_dwordx4 v[66:69], v[44:45], off offset:2048
	global_load_dwordx4 v[74:77], v[58:59], off offset:2048
	global_load_dwordx4 v[78:81], v[58:59], off offset:3072
	global_load_dwordx4 v[32:35], v[54:55], off offset:2048
	s_nop 0
	global_load_dwordx4 v[24:27], v[54:55], off offset:3072
	s_waitcnt vmcnt(4)
	v_pk_mul_f32 v[20:21], v[66:67], v[20:21]
	v_pk_mul_f32 v[22:23], v[68:69], v[22:23]
	global_store_dwordx4 v[56:57], v[20:23], off offset:2048 sc1
	global_load_dwordx4 v[20:23], v[44:45], off offset:3072
	v_mov_b32_e32 v68, v37
	v_mov_b32_e32 v69, v29
	v_mov_b32_e32 v66, v36
	v_mov_b32_e32 v67, v28
	s_waitcnt vmcnt(3)
	v_mov_b32_e32 v88, v33
	s_waitcnt vmcnt(2)
	v_mov_b32_e32 v89, v25
	v_mov_b32_e32 v86, v32
	v_mov_b32_e32 v87, v24
	v_mov_b32_e32 v90, v34
	v_mov_b32_e32 v91, v26
	v_mov_b32_e32 v92, v35
	v_mov_b32_e32 v93, v27
	s_waitcnt vmcnt(0)
	v_pk_mul_f32 v[16:17], v[20:21], v[16:17]
	v_pk_mul_f32 v[18:19], v[22:23], v[18:19]
	global_store_dwordx4 v[56:57], v[16:19], off offset:3072 sc1
	global_load_dwordx4 v[16:19], v[44:45], off
	v_mul_f32_e32 v20, 0x4b800000, v82
	v_cndmask_b32_e32 v20, v82, v20, vcc
	v_rsq_f32_e32 v20, v20
	v_mov_b32_e32 v82, v38
	v_mov_b32_e32 v22, v76
	v_mov_b32_e32 v23, v80
	v_mul_f32_e32 v21, 0x45800000, v20
	v_cndmask_b32_e32 v20, v20, v21, vcc
	v_pk_mul_f32 v[14:15], v[14:15], v[20:21] op_sel_hi:[1,0]
	v_pk_mul_f32 v[12:13], v[12:13], v[20:21] op_sel_hi:[1,0]
	v_pk_mul_f32 v[10:11], v[10:11], v[20:21] op_sel_hi:[1,0]
	v_pk_mul_f32 v[8:9], v[8:9], v[20:21] op_sel_hi:[1,0]
	v_pk_mul_f32 v[6:7], v[6:7], v[20:21] op_sel_hi:[1,0]
	v_pk_mul_f32 v[4:5], v[4:5], v[20:21] op_sel_hi:[1,0]
	v_pk_mul_f32 v[2:3], v[2:3], v[20:21] op_sel_hi:[1,0]
	v_pk_mul_f32 v[0:1], v[0:1], v[20:21] op_sel_hi:[1,0]
	v_mov_b32_e32 v56, v77
	v_mov_b32_e32 v57, v81
	s_waitcnt vmcnt(0)
	v_pk_mul_f32 v[12:13], v[16:17], v[12:13]
	v_pk_mul_f32 v[14:15], v[18:19], v[14:15]
	global_store_dwordx4 v[52:53], v[12:15], off sc1
	global_load_dwordx4 v[12:15], v[44:45], off offset:1024
	v_mov_b32_e32 v18, v75
	v_mov_b32_e32 v19, v79
	v_mov_b32_e32 v16, v74
	v_mov_b32_e32 v17, v78
	s_waitcnt vmcnt(0)
	v_pk_mul_f32 v[8:9], v[12:13], v[8:9]
	v_pk_mul_f32 v[10:11], v[14:15], v[10:11]
	global_store_dwordx4 v[52:53], v[8:11], off offset:1024 sc1
	global_load_dwordx4 v[8:11], v[44:45], off offset:2048
	v_mov_b32_e32 v12, v72
	v_mov_b32_e32 v13, v42
	v_mov_b32_e32 v14, v73
	v_mov_b32_e32 v15, v43
	s_waitcnt vmcnt(0)
	v_pk_mul_f32 v[4:5], v[8:9], v[4:5]
	v_pk_mul_f32 v[6:7], v[10:11], v[6:7]
	global_store_dwordx4 v[52:53], v[4:7], off offset:2048 sc1
	global_load_dwordx4 v[4:7], v[44:45], off offset:3072
	v_mov_b32_e32 v10, v71
	v_mov_b32_e32 v11, v41
	v_mov_b32_e32 v8, v70
	v_mov_b32_e32 v9, v40
	s_waitcnt vmcnt(0)
	v_pk_mul_f32 v[0:1], v[4:5], v[0:1]
	v_pk_mul_f32 v[2:3], v[6:7], v[2:3]
	global_store_dwordx4 v[52:53], v[0:3], off offset:3072 sc1
	global_load_dwordx4 v[0:3], v[44:45], off
	v_pk_mul_f32 v[4:5], v[10:11], v[10:11]
	v_pk_mul_f32 v[10:11], v[68:69], v[68:69]
	v_pk_mul_f32 v[6:7], v[18:19], v[18:19]
	v_pk_mul_f32 v[18:19], v[88:89], v[88:89]
	v_pk_fma_f32 v[4:5], v[8:9], v[8:9], v[4:5]
	v_pk_fma_f32 v[8:9], v[66:67], v[66:67], v[10:11]
	v_pk_fma_f32 v[6:7], v[16:17], v[16:17], v[6:7]
	v_pk_fma_f32 v[10:11], v[86:87], v[86:87], v[18:19]
	v_pk_fma_f32 v[4:5], v[12:13], v[12:13], v[4:5]
	v_pk_fma_f32 v[8:9], v[82:83], v[82:83], v[8:9]
	v_pk_fma_f32 v[6:7], v[22:23], v[22:23], v[6:7]
	v_pk_fma_f32 v[10:11], v[90:91], v[90:91], v[10:11]
	v_pk_fma_f32 v[4:5], v[14:15], v[14:15], v[4:5]
	v_pk_fma_f32 v[8:9], v[84:85], v[84:85], v[8:9]
	v_pk_fma_f32 v[6:7], v[56:57], v[56:57], v[6:7]
	v_pk_fma_f32 v[10:11], v[92:93], v[92:93], v[10:11]
	v_mov_b32_e32 v12, v8
	v_mov_b32_e32 v13, v4
	v_mov_b32_e32 v4, v9
	v_mov_b32_e32 v8, v10
	v_mov_b32_e32 v9, v6
	v_pk_add_f32 v[4:5], v[12:13], v[4:5]
	v_mov_b32_e32 v6, v11
	v_pk_add_f32 v[4:5], v[4:5], v[8:9]
	s_nop 0
	v_pk_add_f32 v[4:5], v[4:5], v[6:7]
	ds_bpermute_b32 v7, v60, v5
	ds_bpermute_b32 v6, v60, v4
	s_waitcnt lgkmcnt(0)
	v_pk_add_f32 v[4:5], v[4:5], v[6:7]
	ds_bpermute_b32 v7, v61, v5
	ds_bpermute_b32 v6, v61, v4
	s_waitcnt lgkmcnt(0)
	v_pk_add_f32 v[4:5], v[4:5], v[6:7]
	ds_bpermute_b32 v7, v62, v5
	ds_bpermute_b32 v6, v62, v4
	s_waitcnt lgkmcnt(0)
	v_pk_add_f32 v[4:5], v[4:5], v[6:7]
	ds_bpermute_b32 v7, v63, v5
	ds_bpermute_b32 v6, v63, v4
	s_waitcnt lgkmcnt(0)
	v_pk_add_f32 v[4:5], v[4:5], v[6:7]
	ds_bpermute_b32 v7, v64, v5
	ds_bpermute_b32 v6, v64, v4
	s_waitcnt lgkmcnt(0)
	v_pk_add_f32 v[4:5], v[4:5], v[6:7]
	ds_bpermute_b32 v7, v65, v5
	ds_bpermute_b32 v6, v65, v4
	s_waitcnt lgkmcnt(0)
	v_pk_add_f32 v[4:5], v[4:5], v[6:7]
	s_nop 0
	v_pk_fma_f32 v[4:5], v[4:5], s[2:3], v[48:49] op_sel_hi:[1,0,0]
	s_nop 0
	v_mul_f32_e32 v6, 0x4b800000, v5
	v_cmp_gt_f32_e32 vcc, s4, v5
	s_nop 1
	v_cndmask_b32_e32 v5, v5, v6, vcc
	v_rsq_f32_e32 v5, v5
	s_nop 0
	v_mul_f32_e32 v6, 0x45800000, v5
	v_cndmask_b32_e32 v6, v5, v6, vcc
	v_pk_mul_f32 v[8:9], v[72:73], v[6:7] op_sel_hi:[1,0]
	v_pk_mul_f32 v[10:11], v[70:71], v[6:7] op_sel_hi:[1,0]
	s_waitcnt vmcnt(0)
	v_pk_mul_f32 v[2:3], v[2:3], v[8:9]
	v_pk_mul_f32 v[0:1], v[0:1], v[10:11]
	global_store_dwordx4 v[58:59], v[0:3], off sc1
	global_load_dwordx4 v[0:3], v[44:45], off offset:1024
	v_pk_mul_f32 v[8:9], v[42:43], v[6:7] op_sel_hi:[1,0]
	v_pk_mul_f32 v[10:11], v[40:41], v[6:7] op_sel_hi:[1,0]
	v_mul_f32_e32 v5, 0x4b800000, v4
	v_cmp_gt_f32_e32 vcc, s4, v4
	s_waitcnt vmcnt(0)
	v_pk_mul_f32 v[0:1], v[0:1], v[10:11]
	v_pk_mul_f32 v[2:3], v[2:3], v[8:9]
	global_store_dwordx4 v[58:59], v[0:3], off offset:1024 sc1
	global_load_dwordx4 v[0:3], v[44:45], off offset:2048
	v_pk_mul_f32 v[8:9], v[76:77], v[6:7] op_sel_hi:[1,0]
	v_pk_mul_f32 v[10:11], v[74:75], v[6:7] op_sel_hi:[1,0]
	v_cndmask_b32_e32 v4, v4, v5, vcc
	v_rsq_f32_e32 v4, v4
	s_waitcnt vmcnt(0)
	v_pk_mul_f32 v[0:1], v[0:1], v[10:11]
	v_pk_mul_f32 v[2:3], v[2:3], v[8:9]
	global_store_dwordx4 v[58:59], v[0:3], off offset:2048 sc1
	global_load_dwordx4 v[0:3], v[44:45], off offset:3072
	v_pk_mul_f32 v[8:9], v[80:81], v[6:7] op_sel_hi:[1,0]
	v_pk_mul_f32 v[6:7], v[78:79], v[6:7] op_sel_hi:[1,0]
	v_mul_f32_e32 v5, 0x45800000, v4
	v_cndmask_b32_e32 v4, v4, v5, vcc
	s_waitcnt vmcnt(0)
	v_pk_mul_f32 v[0:1], v[0:1], v[6:7]
	v_pk_mul_f32 v[2:3], v[2:3], v[8:9]
	global_store_dwordx4 v[58:59], v[0:3], off offset:3072 sc1
	global_load_dwordx4 v[0:3], v[44:45], off
	v_pk_mul_f32 v[6:7], v[38:39], v[4:5] op_sel_hi:[1,0]
	v_pk_mul_f32 v[8:9], v[36:37], v[4:5] op_sel_hi:[1,0]
	s_waitcnt vmcnt(0)
	v_pk_mul_f32 v[2:3], v[2:3], v[6:7]
	v_pk_mul_f32 v[0:1], v[0:1], v[8:9]
	global_store_dwordx4 v[54:55], v[0:3], off sc1
	global_load_dwordx4 v[0:3], v[44:45], off offset:1024
	v_pk_mul_f32 v[6:7], v[30:31], v[4:5] op_sel_hi:[1,0]
	v_pk_mul_f32 v[8:9], v[28:29], v[4:5] op_sel_hi:[1,0]
	v_add_u32_e32 v28, s5, v50
	v_cmp_lt_i32_e32 vcc, s6, v28
	s_or_b64 s[0:1], vcc, s[0:1]
	s_waitcnt vmcnt(0)
	v_pk_mul_f32 v[0:1], v[0:1], v[8:9]
	v_pk_mul_f32 v[2:3], v[2:3], v[6:7]
	global_store_dwordx4 v[54:55], v[0:3], off offset:1024 sc1
	global_load_dwordx4 v[0:3], v[44:45], off offset:2048
	v_pk_mul_f32 v[6:7], v[34:35], v[4:5] op_sel_hi:[1,0]
	v_pk_mul_f32 v[8:9], v[32:33], v[4:5] op_sel_hi:[1,0]
	s_waitcnt vmcnt(0)
	v_pk_mul_f32 v[2:3], v[2:3], v[6:7]
	v_pk_mul_f32 v[0:1], v[0:1], v[8:9]
	global_store_dwordx4 v[54:55], v[0:3], off offset:2048 sc1
	global_load_dwordx4 v[0:3], v[44:45], off offset:3072
	v_pk_mul_f32 v[6:7], v[26:27], v[4:5] op_sel_hi:[1,0]
	v_pk_mul_f32 v[4:5], v[24:25], v[4:5] op_sel_hi:[1,0]
	s_waitcnt vmcnt(0)
	v_pk_mul_f32 v[2:3], v[2:3], v[6:7]
	v_pk_mul_f32 v[0:1], v[0:1], v[4:5]
	global_store_dwordx4 v[54:55], v[0:3], off offset:3072 sc1
	s_andn2_b64 exec, exec, s[0:1]
	s_cbranch_execnz .LBB0_1569

	.amdhsa_kernel _Z4mega6Params
		.amdhsa_group_segment_fixed_size 0
		.amdhsa_private_segment_fixed_size 0
		.amdhsa_kernarg_size 520
		.amdhsa_user_sgpr_count 2
		.amdhsa_user_sgpr_dispatch_ptr 0
		.amdhsa_user_sgpr_queue_ptr 0
		.amdhsa_user_sgpr_kernarg_segment_ptr 1
		.amdhsa_user_sgpr_dispatch_id 0
		.amdhsa_user_sgpr_kernarg_preload_length 0
		.amdhsa_user_sgpr_kernarg_preload_offset 0
		.amdhsa_user_sgpr_private_segment_size 0
		.amdhsa_uses_dynamic_stack 0
		.amdhsa_enable_private_segment 0
		.amdhsa_system_sgpr_workgroup_id_x 1
		.amdhsa_system_sgpr_workgroup_id_y 0
		.amdhsa_system_sgpr_workgroup_id_z 0
		.amdhsa_system_sgpr_workgroup_info 0
		.amdhsa_system_vgpr_workitem_id 2
		.amdhsa_next_free_vgpr 256
		.amdhsa_next_free_sgpr 102
		.amdhsa_accum_offset 256
		.amdhsa_reserve_vcc 1
		.amdhsa_float_round_mode_32 0
		.amdhsa_float_round_mode_16_64 0
		.amdhsa_float_denorm_mode_32 3
		.amdhsa_float_denorm_mode_16_64 3
		.amdhsa_dx10_clamp 1
		.amdhsa_ieee_mode 1
		.amdhsa_fp16_overflow 0
		.amdhsa_tg_split 0
		.amdhsa_exception_fp_ieee_invalid_op 0
		.amdhsa_exception_fp_denorm_src 0
		.amdhsa_exception_fp_ieee_div_zero 0
		.amdhsa_exception_fp_ieee_overflow 0
		.amdhsa_exception_fp_ieee_underflow 0
		.amdhsa_exception_fp_ieee_inexact 0
		.amdhsa_exception_int_div_zero 0
	.end_amdhsa_kernel

amdhsa.kernels:
  - .agpr_count:     0
    .args:
      - .offset:         0
        .size:           264
        .value_kind:     by_value
      - .offset:         264
        .size:           4
        .value_kind:     hidden_block_count_x
      - .offset:         268
        .size:           4
        .value_kind:     hidden_block_count_y
      - .offset:         272
        .size:           4
        .value_kind:     hidden_block_count_z
      - .offset:         276
        .size:           2
        .value_kind:     hidden_group_size_x
      - .offset:         278
        .size:           2
        .value_kind:     hidden_group_size_y
      - .offset:         280
        .size:           2
        .value_kind:     hidden_group_size_z
      - .offset:         282
        .size:           2
        .value_kind:     hidden_remainder_x
      - .offset:         284
        .size:           2
        .value_kind:     hidden_remainder_y
      - .offset:         286
        .size:           2
        .value_kind:     hidden_remainder_z
      - .offset:         304
        .size:           8
        .value_kind:     hidden_global_offset_x
      - .offset:         312
        .size:           8
        .value_kind:     hidden_global_offset_y
      - .offset:         320
        .size:           8
        .value_kind:     hidden_global_offset_z
      - .offset:         328
        .size:           2
        .value_kind:     hidden_grid_dims
      - .offset:         352
        .size:           8
        .value_kind:     hidden_multigrid_sync_arg
      - .offset:         384
        .size:           4
        .value_kind:     hidden_dynamic_lds_size
    .group_segment_fixed_size: 0
    .kernarg_segment_align: 8
    .kernarg_segment_size: 520
    .language:       OpenCL C
    .language_version:
      - 2
      - 0
    .max_flat_workgroup_size: 512
    .name:           _Z4mega6Params
    .private_segment_fixed_size: 0
    .sgpr_count:     108
    .sgpr_spill_count: 214
    .symbol:         _Z4mega6Params.kd
    .uniform_work_group_size: 1
    .uses_dynamic_stack: false
    .vgpr_count:     256
    .vgpr_spill_count: 0
    .wavefront_size: 64
